# v84 + HGRN pass-C: four one-dword-per-line L2 prefetch loads (next sub-chunk q/v/z rows at the forward hg_out start; backward-direction z rows and sub-chunk-0 q/v rows at the second forward hg_out sta
# baseline (speedup 1.0000x reference)
.LBB0_372:
	s_andn2_b64 vcc, exec, s[2:3]
	s_cbranch_vccnz .LBB0_339
	s_mul_i32 s3, s4, 9
	s_ashr_i32 s2, s3, 1
	s_add_i32 s3, s3, 9
	s_ashr_i32 s3, s3, 1
	v_ashrrev_i32_e32 v0, 6, v205
	s_sub_i32 s3, s3, s2
	v_cmp_gt_i32_e32 vcc, s3, v0
	s_and_saveexec_b64 s[38:39], vcc
	s_cbranch_execz .LBB0_338
	v_add_u32_e32 v0, s2, v0
	s_mov_b32 s2, 0x38e38e39
	v_mul_hi_i32 v2, v0, s2
	v_lshrrev_b32_e32 v3, 31, v2
	v_ashrrev_i32_e32 v2, 3, v2
	v_add_u32_e32 v2, v2, v3
	v_mul_lo_u32 v3, v2, 36
	v_sub_u32_e32 v96, v0, v3
	v_cmp_gt_i32_e64 s[40:41], 4, v96
	s_and_b64 s[2:3], s[18:19], s[40:41]
	v_mov_b32_e32 v1, v236
	s_xor_b64 s[2:3], s[2:3], -1
	s_and_b64 exec, exec, s[2:3]
	s_cbranch_execz .LBB0_338
	v_lshrrev_b32_e32 v0, 6, v1
	s_movk_i32 s2, 0x4d00
	v_mul_lo_u32 v0, v0, s2
	v_add_u32_e32 v92, 16, v0
	v_lshlrev_b32_e32 v0, 6, v2
	v_and_b32_e32 v94, 63, v1
	v_and_b32_e32 v0, 0xc0, v0
	v_or_b32_e32 v3, v94, v0
	v_readlane_b32 s0, v255, 20
	v_lshlrev_b32_e32 v160, 2, v3
	v_readlane_b32 s1, v255, 21
	s_nop 4
	global_load_dword v3, v160, s[0:1]
	global_load_dword v6, v160, s[0:1] offset:2048
	v_lshl_add_u64 v[4:5], s[0:1], 0, v[160:161]
	v_add_co_u32_e32 v4, vcc, 0x1000, v4
	s_mov_b32 s0, 0xf149f2ca
	s_nop 0
	v_addc_co_u32_e32 v5, vcc, 0, v5, vcc
	global_load_dword v8, v[4:5], off
	s_nop 0
	global_load_dword v4, v[4:5], off offset:2048
	v_lshlrev_b32_e32 v148, 1, v2
	v_ashrrev_i32_e32 v97, 31, v96
	v_mov_b32_e32 v99, v161
	v_mov_b32_e32 v101, v161
	v_readlane_b32 s44, v254, 28
	v_readlane_b32 s45, v254, 29
	v_mov_b32_e32 v16, v94
	s_waitcnt vmcnt(2)
	v_max3_f32 v7, v3, s0, v6
	v_readlane_b32 s0, v255, 1
	v_readlane_b32 s1, v255, 2
	s_waitcnt vmcnt(0)
	v_max3_f32 v5, v7, v8, v4
	v_sub_f32_e32 v6, v6, v5
	v_mul_f32_e32 v6, 0x3fb8aa3b, v6
	v_sub_f32_e32 v3, v3, v5
	v_exp_f32_e32 v6, v6
	v_sub_f32_e32 v7, v8, v5
	v_mul_f32_e32 v3, 0x3fb8aa3b, v3
	v_mul_f32_e32 v7, 0x3fb8aa3b, v7
	v_exp_f32_e32 v3, v3
	v_exp_f32_e32 v7, v7
	v_sub_f32_e32 v4, v4, v5
	v_mul_f32_e32 v4, 0x3fb8aa3b, v4
	v_exp_f32_e32 v4, v4
	v_add_f32_e32 v5, 0, v6
	v_cndmask_b32_e64 v5, v5, 0, s[0:1]
	v_readlane_b32 s0, v255, 3
	v_add_f32_e32 v8, v7, v5
	v_readlane_b32 s1, v255, 4
	v_add_f32_e32 v3, 0, v3
	v_add_f32_e32 v3, v6, v3
	v_cndmask_b32_e64 v5, v8, v5, s[0:1]
	v_readlane_b32 s0, v255, 5
	v_add_f32_e32 v8, v4, v5
	v_readlane_b32 s1, v255, 6
	v_add_f32_e32 v3, v7, v3
	v_add_f32_e32 v3, v4, v3
	v_cndmask_b32_e64 v5, v8, v5, s[0:1]
	v_div_scale_f32 v4, s[2:3], v3, v3, v5
	v_rcp_f32_e32 v6, v4
	v_readlane_b32 s0, v255, 22
	v_readlane_b32 s1, v255, 23
	v_fma_f32 v7, -v4, v6, 1.0
	v_fmac_f32_e32 v6, v7, v6
	v_div_scale_f32 v7, vcc, v5, v3, v5
	v_mul_f32_e32 v8, v7, v6
	v_fma_f32 v9, -v4, v8, v7
	v_fmac_f32_e32 v8, v9, v6
	v_fma_f32 v4, -v4, v8, v7
	v_div_fmas_f32 v4, v4, v6, v8
	v_div_fixup_f32 v149, v4, v3, v5
	v_ashrrev_i32_e32 v6, 2, v2
	v_mad_i64_i32 v[2:3], s[2:3], v148, 36, v[96:97]
	v_lshlrev_b64 v[2:3], 13, v[2:3]
	v_lshlrev_b32_e32 v4, 7, v1
	v_lshl_add_u64 v[2:3], s[0:1], 0, v[2:3]
	v_and_b32_e32 v98, 0xf80, v4
	v_lshrrev_b32_e32 v1, 2, v1
	v_lshl_add_u64 v[2:3], v[2:3], 0, v[98:99]
	v_and_b32_e32 v100, 8, v1
	v_lshl_add_u64 v[2:3], v[2:3], 0, v[100:101]
	global_load_dwordx2 v[42:43], v[2:3], off
	global_load_dwordx2 v[36:37], v[2:3], off offset:16
	global_load_dwordx2 v[34:35], v[2:3], off offset:32
	global_load_dwordx2 v[4:5], v[2:3], off offset:48
	s_movk_i32 s0, 0x1000
	v_mov_b32_e32 v1, 0xffffff00
	v_lshl_add_u32 v1, v6, 11, v1
	s_mov_b64 s[2:3], s[44:45]
	v_sub_f32_e32 v80, 1.0, v149
	s_waitcnt vmcnt(1)
	v_lshlrev_b32_e32 v40, 16, v35
	s_waitcnt vmcnt(0)
	v_lshlrev_b32_e32 v44, 16, v4
	v_and_b32_e32 v45, 0xffff0000, v4
	v_add_co_u32_e32 v4, vcc, s0, v2
	v_lshlrev_b32_e32 v46, 16, v5
	v_and_b32_e32 v47, 0xffff0000, v5
	v_addc_co_u32_e32 v5, vcc, 0, v3, vcc
	global_load_dwordx2 v[52:53], v[4:5], off
	global_load_dwordx2 v[50:51], v[4:5], off offset:16
	global_load_dwordx2 v[48:49], v[4:5], off offset:32
	global_load_dwordx2 v[38:39], v[4:5], off offset:48
	global_load_dwordx2 v[60:61], v[2:3], off offset:64
	global_load_dwordx2 v[58:59], v[2:3], off offset:80
	global_load_dwordx2 v[56:57], v[2:3], off offset:96
	global_load_dwordx2 v[54:55], v[2:3], off offset:112
	global_load_dwordx2 v[26:27], v[4:5], off offset:64
	global_load_dwordx2 v[28:29], v[4:5], off offset:80
	global_load_dwordx2 v[30:31], v[4:5], off offset:96
	global_load_dwordx2 v[32:33], v[4:5], off offset:112
	v_mov_b32_e32 v2, 0x4000
	v_lshl_add_u32 v2, v6, 8, v2
	v_cndmask_b32_e64 v1, v1, v2, s[40:41]
	v_lshl_add_u32 v93, v96, 6, v1
	v_and_b32_e32 v41, 0xffff0000, v35
	v_ashrrev_i32_e32 v89, 31, v93
	v_and_b32_e32 v35, 31, v16
	v_ashrrev_i32_e32 v81, 5, v16
	v_mov_b64_e32 v[2:3], s[2:3]
	s_movk_i32 s0, 0x1200
	v_mad_i64_i32 v[2:3], s[4:5], v93, s0, v[2:3]
	v_lshlrev_b32_e32 v90, 1, v0
	v_mov_b32_e32 v91, v161
	v_ashrrev_i32_e32 v17, 31, v16
	v_lshl_add_u64 v[0:1], v[2:3], 0, v[90:91]
	v_lshl_add_u64 v[18:19], v[16:17], 1, v[0:1]
	s_mov_b64 s[0:1], 0xb200000
	v_lshl_add_u64 v[0:1], v[18:19], 0, s[0:1]
	global_load_ushort v15, v[0:1], off offset:3072
	global_load_ushort v66, v[0:1], off offset:2048
	s_mov_b32 s7, 0xb202000
	v_add_co_u32_e32 v2, vcc, s7, v18
	s_mov_b32 s11, 0xb205000
	s_nop 0
	v_addc_co_u32_e32 v3, vcc, 0, v19, vcc
	v_add_co_u32_e32 v4, vcc, s11, v18
	s_mov_b32 s12, 0xb207000
	s_nop 0
	v_addc_co_u32_e32 v5, vcc, 0, v19, vcc
	v_add_co_u32_e32 v6, vcc, s12, v18
	s_mov_b32 s13, 0xb209000
	s_nop 0
	v_addc_co_u32_e32 v7, vcc, 0, v19, vcc
	v_add_co_u32_e32 v8, vcc, s13, v18
	s_mov_b32 s14, 0xb20b000
	s_nop 0
	v_addc_co_u32_e32 v9, vcc, 0, v19, vcc
	v_add_co_u32_e32 v10, vcc, s14, v18
	s_mov_b32 s15, 0xb20e000
	s_nop 0
	v_addc_co_u32_e32 v11, vcc, 0, v19, vcc
	v_add_co_u32_e32 v62, vcc, s15, v18
	s_mov_b32 s18, 0xb210000
	s_nop 0
	v_addc_co_u32_e32 v63, vcc, 0, v19, vcc
	v_add_co_u32_e32 v64, vcc, s18, v18
	s_mov_b32 s19, 0xb212000
	s_nop 0
	v_addc_co_u32_e32 v65, vcc, 0, v19, vcc
	v_add_co_u32_e32 v76, vcc, s19, v18
	s_mov_b32 s21, 0xb214000
	s_nop 0
	v_addc_co_u32_e32 v77, vcc, 0, v19, vcc
	v_add_co_u32_e32 v102, vcc, s21, v18
	s_mov_b32 s30, 0xb217000
	s_nop 0
	v_addc_co_u32_e32 v103, vcc, 0, v19, vcc
	global_load_ushort v88, v[4:5], off offset:1024
	global_load_ushort v95, v[4:5], off
	global_load_ushort v104, v[2:3], off offset:3072
	global_load_ushort v14, v[4:5], off offset:512
	global_load_ushort v13, v[2:3], off offset:3584
	global_load_ushort v12, v[0:1], off offset:2560
	v_add_co_u32_e32 v78, vcc, s30, v18
	s_mov_b32 s9, 0xc1f00000
	s_nop 0
	v_addc_co_u32_e32 v79, vcc, 0, v19, vcc
	s_mov_b32 s31, 0xb219000
	v_add_co_u32_e32 v82, vcc, s31, v18
	s_mov_b32 s34, 0xb21b000
	s_nop 0
	v_addc_co_u32_e32 v83, vcc, 0, v19, vcc
	v_add_co_u32_e32 v20, vcc, s34, v18
	s_mov_b32 s35, 0xb21d000
	s_nop 0
	v_addc_co_u32_e32 v21, vcc, 0, v19, vcc
	v_add_co_u32_e32 v68, vcc, s35, v18
	s_mov_b32 s36, 0xb220000
	s_nop 0
	v_addc_co_u32_e32 v69, vcc, 0, v19, vcc
	v_add_co_u32_e32 v22, vcc, s36, v18
	s_mov_b32 s37, 0xb222000
	s_nop 0
	v_addc_co_u32_e32 v23, vcc, 0, v19, vcc
	v_add_co_u32_e32 v24, vcc, s37, v18
	s_mov_b32 s40, 0xb201000
	s_nop 0
	v_addc_co_u32_e32 v25, vcc, 0, v19, vcc
	s_waitcnt vmcnt(7)
	v_lshlrev_b32_e32 v0, 16, v15
	v_max_f32_e32 v0, v0, v0
	v_med3_f32 v0, v0, s9, v244
	v_mul_f32_e32 v0, 0xbfb8aa3b, v0
	v_exp_f32_e32 v86, v0
	v_add_co_u32_e32 v0, vcc, s40, v18
	s_mov_b32 s41, 0xb203000
	v_add_f32_e32 v2, 1.0, v86
	v_rcp_f32_e32 v118, v2
	v_addc_co_u32_e32 v1, vcc, 0, v19, vcc
	s_waitcnt vmcnt(6)
	v_lshlrev_b32_e32 v4, 16, v66
	v_fma_f32 v5, v80, v118, v149
	v_max_f32_e32 v15, 0xda24260, v5
	v_add_co_u32_e32 v2, vcc, s41, v18
	v_mul_f32_e32 v4, v15, v4
	s_nop 0
	v_addc_co_u32_e32 v3, vcc, 0, v19, vcc
	v_bfe_u32 v5, v4, 16, 1
	s_movk_i32 s10, 0x7fff
	s_mov_b32 s46, 0xb204000
	v_add3_u32 v105, v4, v5, s10
	v_add_co_u32_e32 v4, vcc, s46, v18
	s_mov_b32 s28, 0xb206000
	s_nop 0
	v_addc_co_u32_e32 v5, vcc, 0, v19, vcc
	global_load_ushort v106, v[4:5], off offset:-4096
	global_load_ushort v107, v[4:5], off offset:512
	global_load_ushort v87, v[0:1], off offset:3584
	global_load_ushort v110, v[0:1], off offset:2560
	global_load_ushort v111, v[2:3], off offset:3584
	v_add_co_u32_e32 v2, vcc, s28, v18
	s_mov_b32 s29, 0xb208000
	s_nop 0
	v_addc_co_u32_e32 v3, vcc, 0, v19, vcc
	global_load_ushort v156, v[6:7], off offset:1536
	global_load_ushort v157, v[8:9], off offset:2560
	global_load_ushort v158, v[10:11], off offset:3584
	global_load_ushort v116, v[6:7], off offset:2048
	global_load_ushort v117, v[8:9], off offset:3072
	global_load_ushort v121, v[10:11], off offset:3072
	global_load_ushort v120, v[8:9], off offset:2048
	global_load_ushort v126, v[6:7], off offset:1024
	v_add_co_u32_e32 v6, vcc, s29, v18
	s_mov_b32 s42, 0xb20a000
	s_nop 0
	v_addc_co_u32_e32 v7, vcc, 0, v19, vcc
	v_add_co_u32_e32 v8, vcc, s42, v18
	s_mov_b32 s6, 0xb20c000
	s_nop 0
	v_addc_co_u32_e32 v9, vcc, 0, v19, vcc
	v_add_co_u32_e32 v10, vcc, s6, v18
	s_mov_b32 s49, 0xb20d000
	s_nop 0
	v_addc_co_u32_e32 v11, vcc, 0, v19, vcc
	v_add_co_u32_e32 v66, vcc, s49, v18
	s_mov_b32 s4, 0xb20f000
	s_nop 0
	v_addc_co_u32_e32 v67, vcc, 0, v19, vcc
	v_add_co_u32_e32 v74, vcc, s4, v18
	s_mov_b32 s4, 0xb211000
	s_nop 0
	v_addc_co_u32_e32 v75, vcc, 0, v19, vcc
	v_add_co_u32_e32 v84, vcc, s4, v18
	s_mov_b32 s4, 0xb223000
	s_nop 0
	v_addc_co_u32_e32 v85, vcc, 0, v19, vcc
	global_load_ushort v159, v[62:63], off offset:512
	global_load_ushort v162, v[64:65], off offset:1536
	global_load_ushort v163, v[76:77], off offset:2560
	global_load_ushort v164, v[102:103], off offset:3584
	global_load_ushort v127, v[62:63], off offset:1024
	global_load_ushort v137, v[64:65], off offset:2048
	global_load_ushort v141, v[64:65], off offset:1024
	global_load_ushort v131, v[62:63], off
	v_add_co_u32_e32 v62, vcc, s4, v18
	s_mov_b32 s4, 0xb221000
	s_nop 0
	v_addc_co_u32_e32 v63, vcc, 0, v19, vcc
	v_add_co_u32_e32 v64, vcc, s4, v18
	s_mov_b32 s4, 0xb21f000
	s_nop 0
	v_addc_co_u32_e32 v65, vcc, 0, v19, vcc
	v_add_co_u32_e32 v70, vcc, s4, v18
	s_mov_b32 s97, 0xb21c000
	s_nop 0
	v_addc_co_u32_e32 v71, vcc, 0, v19, vcc
	v_add_co_u32_e32 v72, vcc, s97, v18
	s_mov_b32 s4, 0xb21a000
	s_nop 0
	v_addc_co_u32_e32 v73, vcc, 0, v19, vcc
	v_add_co_u32_e32 v108, vcc, s4, v18
	s_mov_b32 s48, 0xb218000
	s_nop 0
	v_addc_co_u32_e32 v109, vcc, 0, v19, vcc
	v_add_co_u32_e32 v112, vcc, s48, v18
	s_mov_b32 s47, 0xb216000
	s_nop 0
	v_addc_co_u32_e32 v113, vcc, 0, v19, vcc
	v_add_co_u32_e32 v114, vcc, s47, v18
	s_mov_b32 s43, 0xb213000
	s_nop 0
	v_addc_co_u32_e32 v115, vcc, 0, v19, vcc
	v_add_co_u32_e32 v124, vcc, s43, v18
	global_load_ushort v165, v[78:79], off offset:512
	global_load_ushort v166, v[82:83], off offset:1536
	global_load_ushort v167, v[20:21], off offset:2560
	global_load_ushort v168, v[68:69], off offset:3584
	global_load_ushort v169, v[22:23], off offset:512
	global_load_ushort v170, v[24:25], off offset:1536
	global_load_ushort v171, v[22:23], off offset:-4096
	global_load_ushort v172, v[78:79], off offset:-4096
	v_addc_co_u32_e32 v125, vcc, 0, v19, vcc
	global_load_ushort v128, v[66:67], off offset:-4096
	global_load_ushort v129, v[66:67], off offset:512
	global_load_ushort v173, v[112:113], off offset:1024
	s_nop 0
	global_load_ushort v66, v[66:67], off
	s_nop 0
	global_load_ushort v67, v[4:5], off
	s_nop 0
	global_load_ushort v4, v[124:125], off offset:3072
	global_load_ushort v5, v[2:3], off offset:1536
	global_load_ushort v130, v[2:3], off offset:512
	global_load_ushort v136, v[6:7], off offset:1536
	global_load_ushort v174, v[2:3], off offset:1024
	global_load_ushort v175, v[0:1], off offset:3072
	s_waitcnt vmcnt(37)
	v_lshlrev_b32_e32 v0, 16, v87
	v_max_f32_e32 v0, v0, v0
	v_med3_f32 v0, v0, s9, v244
	v_mul_f32_e32 v0, 0xbfb8aa3b, v0
	v_exp_f32_e32 v87, v0
	global_load_ushort v0, v[74:75], off offset:1536
	global_load_ushort v1, v[84:85], off offset:2560
	global_load_ushort v2, v[84:85], off offset:1536
	global_load_ushort v3, v[62:63], off offset:2048
	global_load_ushort v176, v[64:65], off offset:1024
	global_load_ushort v177, v[72:73], off offset:3072
	global_load_ushort v178, v[108:109], off offset:2048
	global_load_ushort v179, v[84:85], off offset:2048
	global_load_ushort v138, v[6:7], off offset:2560
	global_load_ushort v139, v[8:9], off offset:3584
	global_load_ushort v140, v[8:9], off offset:2560
	s_nop 0
	global_load_ushort v10, v[10:11], off offset:3584
	s_nop 0
	global_load_ushort v11, v[74:75], off offset:512
	global_load_ushort v180, v[74:75], off offset:1024
	s_nop 0
	global_load_ushort v8, v[8:9], off offset:3072
	s_nop 0
	global_load_ushort v181, v[6:7], off offset:2048
	v_lshlrev_b32_e32 v7, 16, v106
	v_max_f32_e32 v7, v7, v7
	v_add_f32_e32 v84, 1.0, v87
	v_med3_f32 v7, v7, s9, v244
	v_rcp_f32_e32 v119, v84
	v_mul_f32_e32 v7, 0xbfb8aa3b, v7
	v_exp_f32_e32 v84, v7
	s_waitcnt vmcnt(52)
	v_lshlrev_b32_e32 v7, 16, v110
	v_fma_f32 v6, v80, v119, v149
	v_mul_f32_e32 v6, v15, v6
	v_add_f32_e32 v9, 1.0, v84
	v_max_f32_e32 v6, 0xda24260, v6
	v_rcp_f32_e32 v132, v9
	v_mul_f32_e32 v7, v6, v7
	v_bfe_u32 v9, v7, 16, 1
	v_lshl_add_u32 v17, v16, 1, v92
	v_add3_u32 v7, v7, v9, s10
	ds_write_b16_d16_hi v17, v7 offset:144
	v_fma_f32 v7, v80, v132, v149
	v_rcp_f32_e32 v123, v6
	v_mul_f32_e32 v6, v6, v7
	v_lshlrev_b32_e32 v7, 16, v107
	v_max_f32_e32 v7, v7, v7
	v_med3_f32 v7, v7, s9, v244
	v_mul_f32_e32 v7, 0xbfb8aa3b, v7
	v_exp_f32_e32 v85, v7
	v_max_f32_e32 v6, 0xda24260, v6
	v_lshlrev_b32_e32 v7, 16, v104
	v_mul_f32_e32 v7, v6, v7
	v_add_f32_e32 v9, 1.0, v85
	v_rcp_f32_e32 v133, v9
	v_bfe_u32 v9, v7, 16, 1
	v_add3_u32 v7, v7, v9, s10
	ds_write_b16_d16_hi v17, v7 offset:288
	v_fma_f32 v7, v80, v133, v149
	v_rcp_f32_e32 v134, v6
	v_mul_f32_e32 v6, v6, v7
	v_lshlrev_b32_e32 v7, 16, v88
	v_max_f32_e32 v7, v7, v7
	v_med3_f32 v7, v7, s9, v244
	v_mul_f32_e32 v7, 0xbfb8aa3b, v7
	v_exp_f32_e32 v74, v7
	v_max_f32_e32 v6, 0xda24260, v6
	s_waitcnt vmcnt(51)
	v_lshlrev_b32_e32 v7, 16, v111
	v_mul_f32_e32 v7, v6, v7
	v_add_f32_e32 v9, 1.0, v74
	v_rcp_f32_e32 v144, v9
	v_bfe_u32 v9, v7, 16, 1
	v_add3_u32 v7, v7, v9, s10
	ds_write_b16_d16_hi v17, v7 offset:432
	v_fma_f32 v7, v80, v144, v149
	v_rcp_f32_e32 v135, v6
	v_mul_f32_e32 v6, v6, v7
	v_max_f32_e32 v6, 0xda24260, v6
	v_rcp_f32_e32 v146, v6
	ds_write_b16_d16_hi v17, v105
	v_rcp_f32_e32 v122, v15
	v_pk_mul_f32 v[84:85], v[84:85], v[132:133]
	v_pk_mul_f32 v[86:87], v[86:87], v[118:119]
	v_pk_mul_f32 v[84:85], v[80:81], v[84:85] op_sel_hi:[0,1]
	v_pk_mul_f32 v[86:87], v[80:81], v[86:87] op_sel_hi:[0,1]
	s_movk_i32 s4, 0x50
	v_pk_mul_f32 v[84:85], v[84:85], v[134:135]
	v_pk_mul_f32 v[86:87], v[86:87], v[122:123]
	v_and_b32_sdwa v132, v85, v239 dst_sel:DWORD dst_unused:UNUSED_PAD src0_sel:WORD_1 src1_sel:DWORD
	s_waitcnt vmcnt(23)
	v_lshl_or_b32 v9, v66, 16, v158
	s_waitcnt vmcnt(22)
	v_lshl_or_b32 v13, v67, 16, v13
	v_mad_u64_u32 v[66:67], s[4:5], v16, s4, v[92:93]
	s_waitcnt vmcnt(20)
	v_lshlrev_b32_e32 v5, 16, v5
	v_max_f32_e32 v5, v5, v5
	v_med3_f32 v5, v5, s9, v244
	v_mul_f32_e32 v5, 0xbfb8aa3b, v5
	v_exp_f32_e32 v75, v5
	v_lshlrev_b32_e32 v5, 16, v95
	v_mul_f32_e32 v5, v6, v5
	s_waitcnt vmcnt(15)
	v_lshlrev_b32_e32 v0, 16, v0
	v_add_f32_e32 v7, 1.0, v75
	v_rcp_f32_e32 v145, v7
	v_bfe_u32 v7, v5, 16, 1
	v_add3_u32 v5, v5, v7, s10
	ds_write_b16_d16_hi v17, v5 offset:576
	v_fma_f32 v5, v80, v145, v149
	v_mul_f32_e32 v5, v6, v5
	v_lshlrev_b32_e32 v6, 16, v116
	v_max_f32_e32 v6, v6, v6
	v_med3_f32 v6, v6, s9, v244
	v_mul_f32_e32 v6, 0xbfb8aa3b, v6
	v_exp_f32_e32 v150, v6
	v_max_f32_e32 v5, 0xda24260, v5
	v_lshlrev_b32_e32 v6, 16, v130
	v_mul_f32_e32 v6, v5, v6
	v_add_f32_e32 v7, 1.0, v150
	v_rcp_f32_e32 v152, v7
	v_bfe_u32 v7, v6, 16, 1
	v_add3_u32 v6, v6, v7, s10
	ds_write_b16_d16_hi v17, v6 offset:720
	v_fma_f32 v6, v80, v152, v149
	v_rcp_f32_e32 v147, v5
	v_mul_f32_e32 v5, v5, v6
	s_waitcnt vmcnt(7)
	v_lshlrev_b32_e32 v6, 16, v138
	v_max_f32_e32 v6, v6, v6
	v_med3_f32 v6, v6, s9, v244
	v_mul_f32_e32 v6, 0xbfb8aa3b, v6
	v_exp_f32_e32 v151, v6
	v_max_f32_e32 v5, 0xda24260, v5
	v_lshlrev_b32_e32 v6, 16, v126
	v_mul_f32_e32 v6, v5, v6
	v_add_f32_e32 v7, 1.0, v151
	v_rcp_f32_e32 v153, v7
	v_bfe_u32 v7, v6, 16, 1
	v_add3_u32 v6, v6, v7, s10
	ds_write_b16_d16_hi v17, v6 offset:864
	v_fma_f32 v6, v80, v153, v149
	v_rcp_f32_e32 v154, v5
	v_mul_f32_e32 v5, v5, v6
	v_lshlrev_b32_e32 v6, 16, v117
	v_max_f32_e32 v6, v6, v6
	v_med3_f32 v6, v6, s9, v244
	v_mul_f32_e32 v6, 0xbfb8aa3b, v6
	v_exp_f32_e32 v104, v6
	v_max_f32_e32 v5, 0xda24260, v5
	v_lshlrev_b32_e32 v6, 16, v136
	v_mul_f32_e32 v6, v5, v6
	v_add_f32_e32 v7, 1.0, v104
	v_rcp_f32_e32 v106, v7
	v_bfe_u32 v7, v6, 16, 1
	v_add3_u32 v6, v6, v7, s10
	ds_write_b16_d16_hi v17, v6 offset:1008
	v_fma_f32 v6, v80, v106, v149
	v_rcp_f32_e32 v155, v5
	v_mul_f32_e32 v5, v5, v6
	s_waitcnt vmcnt(6)
	v_lshlrev_b32_e32 v6, 16, v139
	v_max_f32_e32 v6, v6, v6
	v_med3_f32 v6, v6, s9, v244
	v_mul_f32_e32 v6, 0xbfb8aa3b, v6
	v_exp_f32_e32 v105, v6
	v_max_f32_e32 v5, 0xda24260, v5
	v_lshlrev_b32_e32 v6, 16, v120
	v_mul_f32_e32 v6, v5, v6
	v_add_f32_e32 v7, 1.0, v105
	v_rcp_f32_e32 v107, v7
	v_bfe_u32 v7, v6, 16, 1
	v_add3_u32 v88, v6, v7, s10
	v_rcp_f32_e32 v110, v5
	v_fma_f32 v6, v80, v107, v149
	v_mul_f32_e32 v5, v5, v6
	v_lshlrev_b32_e32 v6, 16, v128
	v_max_f32_e32 v6, v6, v6
	v_med3_f32 v6, v6, s9, v244
	v_mul_f32_e32 v6, 0xbfb8aa3b, v6
	v_exp_f32_e32 v116, v6
	v_max_f32_e32 v5, 0xda24260, v5
	s_waitcnt vmcnt(5)
	v_lshlrev_b32_e32 v6, 16, v140
	v_mul_f32_e32 v6, v5, v6
	v_add_f32_e32 v7, 1.0, v116
	v_rcp_f32_e32 v120, v7
	v_bfe_u32 v7, v6, 16, 1
	v_add3_u32 v95, v6, v7, s10
	v_rcp_f32_e32 v111, v5
	v_fma_f32 v6, v80, v120, v149
	v_mul_f32_e32 v5, v5, v6
	v_lshlrev_b32_e32 v6, 16, v129
	v_max_f32_e32 v6, v6, v6
	v_med3_f32 v6, v6, s9, v244
	v_mul_f32_e32 v6, 0xbfb8aa3b, v6
	v_exp_f32_e32 v117, v6
	v_lshlrev_b32_e32 v6, 16, v121
	v_max_f32_e32 v5, 0xda24260, v5
	v_mul_f32_e32 v6, v5, v6
	v_add_f32_e32 v7, 1.0, v117
	v_rcp_f32_e32 v121, v7
	v_bfe_u32 v7, v6, 16, 1
	v_add3_u32 v182, v6, v7, s10
	v_rcp_f32_e32 v126, v5
	v_fma_f32 v6, v80, v121, v149
	v_mul_f32_e32 v5, v5, v6
	v_lshlrev_b32_e32 v6, 16, v127
	v_max_f32_e32 v6, v6, v6
	v_med3_f32 v6, v6, s9, v244
	v_mul_f32_e32 v6, 0xbfb8aa3b, v6
	v_exp_f32_e32 v128, v6
	v_max_f32_e32 v0, v0, v0
	v_med3_f32 v0, v0, s9, v244
	v_mul_f32_e32 v0, 0xbfb8aa3b, v0
	v_add_f32_e32 v7, 1.0, v128
	v_rcp_f32_e32 v130, v7
	v_max_f32_e32 v5, 0xda24260, v5
	s_waitcnt vmcnt(4)
	v_lshlrev_b32_e32 v6, 16, v10
	v_exp_f32_e32 v129, v0
	v_mul_f32_e32 v6, v5, v6
	v_bfe_u32 v7, v6, 16, 1
	v_add3_u32 v183, v6, v7, s10
	v_fma_f32 v6, v80, v130, v149
	v_rcp_f32_e32 v127, v5
	v_mul_f32_e32 v5, v5, v6
	v_add_f32_e32 v6, 1.0, v129
	v_max_f32_e32 v0, 0xda24260, v5
	v_lshlrev_b32_e32 v5, 16, v131
	v_rcp_f32_e32 v131, v6
	v_mul_f32_e32 v5, v0, v5
	v_bfe_u32 v6, v5, 16, 1
	v_add3_u32 v184, v5, v6, s10
	v_fma_f32 v5, v80, v131, v149
	v_rcp_f32_e32 v136, v0
	v_mul_f32_e32 v0, v0, v5
	v_lshlrev_b32_e32 v5, 16, v137
	v_max_f32_e32 v5, v5, v5
	v_med3_f32 v5, v5, s9, v244
	v_mul_f32_e32 v5, 0xbfb8aa3b, v5
	v_exp_f32_e32 v138, v5
	v_lshlrev_b32_e32 v1, 16, v1
	v_max_f32_e32 v1, v1, v1
	v_med3_f32 v1, v1, s9, v244
	v_add_f32_e32 v6, 1.0, v138
	v_rcp_f32_e32 v140, v6
	v_mul_f32_e32 v1, 0xbfb8aa3b, v1
	v_max_f32_e32 v0, 0xda24260, v0
	s_waitcnt vmcnt(3)
	v_lshlrev_b32_e32 v5, 16, v11
	v_exp_f32_e32 v139, v1
	v_mul_f32_e32 v5, v0, v5
	v_bfe_u32 v6, v5, 16, 1
	v_add3_u32 v185, v5, v6, s10
	v_fma_f32 v5, v80, v140, v149
	v_rcp_f32_e32 v137, v0
	v_mul_f32_e32 v0, v0, v5
	v_add_f32_e32 v5, 1.0, v139
	v_lshlrev_b32_e32 v1, 16, v141
	v_rcp_f32_e32 v141, v5
	v_max_f32_e32 v0, 0xda24260, v0
	v_mul_f32_e32 v1, v0, v1
	v_bfe_u32 v5, v1, 16, 1
	v_add3_u32 v186, v1, v5, s10
	v_fma_f32 v1, v80, v141, v149
	v_pk_mul_f32 v[150:151], v[150:151], v[152:153]
	v_pk_mul_f32 v[74:75], v[74:75], v[144:145]
	v_rcp_f32_e32 v142, v0
	v_mul_f32_e32 v0, v0, v1
	v_pk_mul_f32 v[150:151], v[80:81], v[150:151] op_sel_hi:[0,1]
	v_pk_mul_f32 v[74:75], v[80:81], v[74:75] op_sel_hi:[0,1]
	v_max_f32_e32 v187, 0xda24260, v0
	v_lshlrev_b32_e32 v0, 16, v2
	v_pk_mul_f32 v[150:151], v[150:151], v[154:155]
	v_pk_mul_f32 v[74:75], v[74:75], v[146:147]
	v_mul_f32_e32 v0, v187, v0
	v_and_b32_sdwa v152, v150, v239 dst_sel:DWORD dst_unused:UNUSED_PAD src0_sel:WORD_1 src1_sel:DWORD
	v_and_b32_sdwa v144, v75, v239 dst_sel:DWORD dst_unused:UNUSED_PAD src0_sel:WORD_1 src1_sel:DWORD
	v_and_b32_sdwa v145, v74, v239 dst_sel:DWORD dst_unused:UNUSED_PAD src0_sel:WORD_1 src1_sel:DWORD
	v_and_b32_sdwa v133, v84, v239 dst_sel:DWORD dst_unused:UNUSED_PAD src0_sel:WORD_1 src1_sel:DWORD
	v_and_b32_sdwa v118, v87, v239 dst_sel:DWORD dst_unused:UNUSED_PAD src0_sel:WORD_1 src1_sel:DWORD
	v_and_b32_sdwa v119, v86, v239 dst_sel:DWORD dst_unused:UNUSED_PAD src0_sel:WORD_1 src1_sel:DWORD
	v_bfe_u32 v1, v0, 16, 1
	v_and_b32_sdwa v67, v151, v239 dst_sel:DWORD dst_unused:UNUSED_PAD src0_sel:WORD_1 src1_sel:DWORD
	v_add3_u32 v150, v150, v152, s10
	v_add3_u32 v75, v75, v144, s10
	v_add3_u32 v74, v74, v145, s10
	v_add3_u32 v85, v85, v132, s10
	v_add3_u32 v84, v84, v133, s10
	v_add3_u32 v87, v87, v118, s10
	v_add3_u32 v86, v86, v119, s10
	v_rcp_f32_e32 v143, v187
	v_add3_u32 v188, v0, v1, s10
	v_lshl_or_b32 v3, v3, 16, v170
	v_lshl_or_b32 v2, v176, 16, v169
	v_lshl_or_b32 v1, v171, 16, v168
	v_lshl_or_b32 v0, v177, 16, v167
	v_lshl_or_b32 v7, v178, 16, v166
	v_lshl_or_b32 v6, v173, 16, v165
	v_lshl_or_b32 v5, v172, 16, v164
	v_lshl_or_b32 v4, v4, 16, v163
	v_lshl_or_b32 v11, v179, 16, v162
	s_waitcnt vmcnt(2)
	v_lshl_or_b32 v10, v180, 16, v159
	s_waitcnt vmcnt(1)
	v_lshl_or_b32 v8, v8, 16, v157
	s_waitcnt vmcnt(0)
	v_lshl_or_b32 v15, v181, 16, v156
	v_lshl_or_b32 v14, v174, 16, v14
	v_lshl_or_b32 v12, v175, 16, v12
	s_movk_i32 s16, 0x50
	v_add3_u32 v67, v151, v67, s10
	ds_write_b16_d16_hi v17, v150 offset:5472
	ds_write_b16_d16_hi v17, v67 offset:5616
	ds_write_b16_d16_hi v17, v74 offset:5184
	ds_write_b16_d16_hi v17, v75 offset:5328
	v_and_b32_e32 v75, 0xffff0000, v75
	v_and_b32_e32 v74, 0xffff0000, v74
	ds_write_b16_d16_hi v17, v84 offset:4896
	ds_write_b16_d16_hi v17, v85 offset:5040
	v_and_b32_e32 v85, 0xffff0000, v85
	v_and_b32_e32 v84, 0xffff0000, v84
	ds_write_b16_d16_hi v17, v86 offset:4608
	ds_write_b16_d16_hi v17, v87 offset:4752
	v_and_b32_e32 v87, 0xffff0000, v87
	v_and_b32_e32 v86, 0xffff0000, v86
	global_load_ushort v118, v[76:77], off offset:3072
	s_nop 0
	global_load_ushort v102, v[102:103], off offset:3072
	s_nop 0
	global_load_ushort v103, v[78:79], off offset:1024
	global_load_ushort v119, v[82:83], off offset:1024
	global_load_ushort v123, v[82:83], off offset:2048
	s_nop 0
	global_load_ushort v78, v[78:79], off
	s_nop 0
	global_load_ushort v79, v[76:77], off offset:2048
	global_load_ushort v82, v[124:125], off offset:3584
	s_mov_b32 s5, 0xb215000
	v_add_co_u32_e32 v76, vcc, s5, v18
	v_pk_mul_f32 v[138:139], v[138:139], v[140:141]
	s_nop 0
	v_addc_co_u32_e32 v77, vcc, 0, v19, vcc
	global_load_ushort v83, v[76:77], off
	s_nop 0
	global_load_ushort v76, v[76:77], off offset:3584
	s_nop 0
	global_load_ushort v77, v[124:125], off offset:2560
	s_nop 0
	global_load_ushort v114, v[114:115], off offset:512
	s_nop 0
	global_load_ushort v115, v[112:113], off offset:1536
	global_load_ushort v144, v[108:109], off offset:1536
	ds_write_b16_d16_hi v17, v88 offset:1152
	ds_write_b16_d16_hi v17, v95 offset:1296
	ds_write_b16_d16_hi v17, v182 offset:1440
	ds_write_b16_d16_hi v17, v183 offset:1584
	ds_write_b16_d16_hi v17, v184 offset:1728
	ds_write_b16_d16_hi v17, v185 offset:1872
	ds_write_b16_d16_hi v17, v186 offset:2016
	ds_write_b16_d16_hi v17, v188 offset:2160
	global_load_ushort v88, v[112:113], off offset:512
	global_load_ushort v95, v[108:109], off offset:2560
	v_pk_mul_f32 v[128:129], v[128:129], v[130:131]
	v_pk_mul_f32 v[116:117], v[116:117], v[120:121]
	v_pk_mul_f32 v[104:105], v[104:105], v[106:107]
	v_pk_mul_f32 v[138:139], v[80:81], v[138:139] op_sel_hi:[0,1]
	v_pk_mul_f32 v[128:129], v[80:81], v[128:129] op_sel_hi:[0,1]
	v_pk_mul_f32 v[116:117], v[80:81], v[116:117] op_sel_hi:[0,1]
	v_pk_mul_f32 v[104:105], v[80:81], v[104:105] op_sel_hi:[0,1]
	v_pk_mul_f32 v[138:139], v[138:139], v[142:143]
	v_pk_mul_f32 v[128:129], v[128:129], v[136:137]
	v_pk_mul_f32 v[116:117], v[116:117], v[126:127]
	v_pk_mul_f32 v[104:105], v[104:105], v[110:111]
	v_and_b32_sdwa v140, v138, v239 dst_sel:DWORD dst_unused:UNUSED_PAD src0_sel:WORD_1 src1_sel:DWORD
	v_and_b32_sdwa v130, v129, v239 dst_sel:DWORD dst_unused:UNUSED_PAD src0_sel:WORD_1 src1_sel:DWORD
	v_and_b32_sdwa v131, v128, v239 dst_sel:DWORD dst_unused:UNUSED_PAD src0_sel:WORD_1 src1_sel:DWORD
	v_and_b32_sdwa v120, v117, v239 dst_sel:DWORD dst_unused:UNUSED_PAD src0_sel:WORD_1 src1_sel:DWORD
	v_and_b32_sdwa v121, v116, v239 dst_sel:DWORD dst_unused:UNUSED_PAD src0_sel:WORD_1 src1_sel:DWORD
	v_and_b32_sdwa v106, v105, v239 dst_sel:DWORD dst_unused:UNUSED_PAD src0_sel:WORD_1 src1_sel:DWORD
	v_and_b32_sdwa v107, v104, v239 dst_sel:DWORD dst_unused:UNUSED_PAD src0_sel:WORD_1 src1_sel:DWORD
	v_add3_u32 v142, v138, v140, s10
	v_add3_u32 v129, v129, v130, s10
	v_add3_u32 v128, v128, v131, s10
	v_add3_u32 v117, v117, v120, s10
	v_add3_u32 v116, v116, v121, s10
	v_add3_u32 v105, v105, v106, s10
	v_add3_u32 v104, v104, v107, s10
	s_waitcnt vmcnt(15)
	v_lshlrev_b32_e32 v108, 16, v118
	s_waitcnt vmcnt(14)
	v_lshlrev_b32_e32 v113, 16, v102
	s_waitcnt vmcnt(10)
	v_lshlrev_b32_e32 v118, 16, v78
	v_max_f32_e32 v78, v108, v108
	s_waitcnt vmcnt(9)
	v_lshlrev_b32_e32 v112, 16, v79
	s_waitcnt vmcnt(8)
	v_lshlrev_b32_e32 v79, 16, v82
	v_med3_f32 v78, v78, s9, v244
	v_lshlrev_b32_e32 v82, 16, v103
	v_max_f32_e32 v79, v79, v79
	v_mul_f32_e32 v78, 0xbfb8aa3b, v78
	s_waitcnt vmcnt(5)
	v_lshlrev_b32_e32 v122, 16, v77
	v_lshlrev_b32_e32 v77, 16, v83
	v_lshlrev_b32_e32 v124, 16, v76
	v_max_f32_e32 v76, v82, v82
	s_waitcnt vmcnt(3)
	v_lshlrev_b32_e32 v82, 16, v115
	v_med3_f32 v79, v79, s9, v244
	v_exp_f32_e32 v102, v78
	v_max_f32_e32 v77, v77, v77
	v_max_f32_e32 v82, v82, v82
	v_mul_f32_e32 v79, 0xbfb8aa3b, v79
	v_lshlrev_b32_e32 v83, 16, v114
	v_med3_f32 v76, v76, s9, v244
	v_med3_f32 v77, v77, s9, v244
	v_med3_f32 v82, v82, s9, v244
	v_exp_f32_e32 v103, v79
	v_max_f32_e32 v83, v83, v83
	v_mul_f32_e32 v76, 0xbfb8aa3b, v76
	v_mul_f32_e32 v77, 0xbfb8aa3b, v77
	v_mul_f32_e32 v82, 0xbfb8aa3b, v82
	v_med3_f32 v83, v83, s9, v244
	v_exp_f32_e32 v76, v76
	v_exp_f32_e32 v78, v77
	v_exp_f32_e32 v77, v82
	v_add_f32_e32 v82, 1.0, v102
	v_mul_f32_e32 v79, 0xbfb8aa3b, v83
	v_rcp_f32_e32 v114, v82
	v_exp_f32_e32 v79, v79
	v_add_f32_e32 v83, 1.0, v103
	v_rcp_f32_e32 v115, v83
	v_add_f32_e32 v108, 1.0, v76
	v_add_f32_e32 v83, 1.0, v78
	v_rcp_f32_e32 v82, v108
	v_rcp_f32_e32 v108, v83
	v_fma_f32 v83, v80, v114, v149
	v_add_f32_e32 v109, 1.0, v79
	v_mul_f32_e32 v83, v187, v83
	v_rcp_f32_e32 v109, v109
	v_fma_f32 v125, v80, v115, v149
	v_max_f32_e32 v83, 0xda24260, v83
	v_rcp_f32_e32 v134, v83
	v_mul_f32_e32 v112, v83, v112
	v_mul_f32_e32 v83, v83, v125
	v_fma_f32 v132, v80, v108, v149
	v_bfe_u32 v125, v112, 16, 1
	v_max_f32_e32 v83, 0xda24260, v83
	v_add3_u32 v146, v112, v125, s10
	v_rcp_f32_e32 v135, v83
	v_mul_f32_e32 v112, v83, v122
	v_mul_f32_e32 v83, v83, v132
	v_fma_f32 v133, v80, v109, v149
	v_bfe_u32 v122, v112, 16, 1
	v_max_f32_e32 v83, 0xda24260, v83
	v_add3_u32 v147, v112, v122, s10
	v_rcp_f32_e32 v132, v83
	v_mul_f32_e32 v112, v83, v113
	v_mul_f32_e32 v83, v83, v133
	v_fma_f32 v145, v80, v82, v149
	v_bfe_u32 v113, v112, 16, 1
	v_max_f32_e32 v83, 0xda24260, v83
	v_add3_u32 v151, v112, v113, s10
	v_rcp_f32_e32 v133, v83
	v_mul_f32_e32 v112, v83, v124
	v_mul_f32_e32 v83, v83, v145
	v_max_f32_e32 v124, 0xda24260, v83
	v_add_f32_e32 v83, 1.0, v77
	v_rcp_f32_e32 v83, v83
	v_bfe_u32 v113, v112, 16, 1
	v_add3_u32 v152, v112, v113, s10
	v_mul_f32_e32 v112, v124, v118
	v_bfe_u32 v113, v112, 16, 1
	v_add3_u32 v153, v112, v113, s10
	v_fma_f32 v112, v80, v83, v149
	v_mul_f32_e32 v113, v124, v112
	v_lshlrev_b32_e32 v112, 16, v123
	v_max_f32_e32 v112, v112, v112
	v_med3_f32 v112, v112, s9, v244
	v_mul_f32_e32 v112, 0xbfb8aa3b, v112
	v_exp_f32_e32 v112, v112
	v_max_f32_e32 v113, 0xda24260, v113
	s_waitcnt vmcnt(1)
	v_lshlrev_b32_e32 v88, 16, v88
	s_waitcnt vmcnt(0)
	v_lshlrev_b32_e32 v95, 16, v95
	v_add_f32_e32 v118, 1.0, v112
	v_rcp_f32_e32 v118, v118
	v_mul_f32_e32 v88, v113, v88
	v_max_f32_e32 v95, v95, v95
	v_rcp_f32_e32 v122, v124
	v_bfe_u32 v124, v88, 16, 1
	v_med3_f32 v95, v95, s9, v244
	v_add3_u32 v88, v88, v124, s10
	v_fma_f32 v124, v80, v118, v149
	v_mul_f32_e32 v95, 0xbfb8aa3b, v95
	v_rcp_f32_e32 v123, v113
	v_mul_f32_e32 v124, v113, v124
	v_exp_f32_e32 v113, v95
	v_lshlrev_b32_e32 v125, 16, v119
	v_max_f32_e32 v95, 0xda24260, v124
	v_mul_f32_e32 v125, v95, v125
	v_add_f32_e32 v119, 1.0, v113
	v_rcp_f32_e32 v119, v119
	v_bfe_u32 v145, v125, 16, 1
	v_add3_u32 v154, v125, v145, s10
	v_rcp_f32_e32 v124, v95
	v_fma_f32 v125, v80, v119, v149
	v_mul_f32_e32 v95, v95, v125
	v_max_f32_e32 v95, 0xda24260, v95
	v_lshlrev_b32_e32 v144, 16, v144
	v_mul_f32_e32 v144, v95, v144
	v_bfe_u32 v145, v144, 16, 1
	v_add3_u32 v155, v144, v145, s10
	v_and_b32_e32 v145, 0xffff0000, v67
	v_and_b32_sdwa v67, v139, v239 dst_sel:DWORD dst_unused:UNUSED_PAD src0_sel:WORD_1 src1_sel:DWORD
	v_rcp_f32_e32 v125, v95
	v_and_b32_e32 v144, 0xffff0000, v150
	v_add3_u32 v67, v139, v67, s10
	ds_write_b16_d16_hi v17, v142 offset:6624
	ds_write_b16_d16_hi v17, v67 offset:6768
	ds_write_b16_d16_hi v17, v128 offset:6336
	ds_write_b16_d16_hi v17, v129 offset:6480
	v_and_b32_e32 v129, 0xffff0000, v129
	v_and_b32_e32 v128, 0xffff0000, v128
	ds_write_b16_d16_hi v17, v116 offset:6048
	ds_write_b16_d16_hi v17, v117 offset:6192
	v_and_b32_e32 v117, 0xffff0000, v117
	v_and_b32_e32 v116, 0xffff0000, v116
	ds_write_b16_d16_hi v17, v104 offset:5760
	ds_write_b16_d16_hi v17, v105 offset:5904
	v_and_b32_e32 v105, 0xffff0000, v105
	v_and_b32_e32 v104, 0xffff0000, v104
	global_load_ushort v106, v[20:21], off offset:3072
	s_nop 0
	global_load_ushort v68, v[68:69], off offset:3072
	s_nop 0
	global_load_ushort v69, v[22:23], off offset:1024
	global_load_ushort v139, v[24:25], off offset:1024
	global_load_ushort v131, v[24:25], off offset:2048
	s_nop 0
	global_load_ushort v22, v[22:23], off
	s_nop 0
	global_load_ushort v20, v[20:21], off offset:2048
	s_nop 0
	global_load_ushort v21, v[72:73], off offset:3584
	s_mov_b32 s4, 0xb21e000
	v_add_co_u32_e32 v18, vcc, s4, v18
	s_waitcnt vmcnt(6)
	v_lshlrev_b32_e32 v68, 16, v68
	v_addc_co_u32_e32 v19, vcc, 0, v19, vcc
	global_load_ushort v23, v[18:19], off
	s_nop 0
	global_load_ushort v18, v[18:19], off offset:3584
	s_nop 0
	global_load_ushort v19, v[72:73], off offset:2560
	global_load_ushort v24, v[70:71], off offset:512
	global_load_ushort v25, v[64:65], off offset:1536
	s_nop 0
	global_load_ushort v70, v[62:63], off offset:1536
	ds_write_b16_d16_hi v17, v146 offset:2304
	ds_write_b16_d16_hi v17, v147 offset:2448
	ds_write_b16_d16_hi v17, v151 offset:2592
	ds_write_b16_d16_hi v17, v152 offset:2736
	ds_write_b16_d16_hi v17, v153 offset:2880
	ds_write_b16_d16_hi v17, v88 offset:3024
	ds_write_b16_d16_hi v17, v154 offset:3168
	ds_write_b16_d16_hi v17, v155 offset:3312
	global_load_ushort v64, v[64:65], off offset:512
	s_nop 0
	global_load_ushort v62, v[62:63], off offset:2560
	v_lshlrev_b32_e32 v63, 16, v106
	s_waitcnt vmcnt(9)
	v_lshlrev_b32_e32 v65, 16, v20
	s_waitcnt vmcnt(8)
	v_lshlrev_b32_e32 v20, 16, v21
	v_lshlrev_b32_e32 v21, 16, v69
	v_lshlrev_b32_e32 v69, 16, v22
	v_max_f32_e32 v22, v63, v63
	v_med3_f32 v22, v22, s9, v244
	v_max_f32_e32 v20, v20, v20
	v_mul_f32_e32 v22, 0xbfb8aa3b, v22
	v_med3_f32 v20, v20, s9, v244
	v_mul_f32_e32 v20, 0xbfb8aa3b, v20
	s_waitcnt vmcnt(6)
	v_lshlrev_b32_e32 v71, 16, v18
	s_waitcnt vmcnt(5)
	v_lshlrev_b32_e32 v63, 16, v19
	v_lshlrev_b32_e32 v19, 16, v23
	s_waitcnt vmcnt(4)
	v_lshlrev_b32_e32 v23, 16, v24
	v_exp_f32_e32 v24, v22
	v_max_f32_e32 v18, v21, v21
	s_waitcnt vmcnt(3)
	v_lshlrev_b32_e32 v21, 16, v25
	v_max_f32_e32 v19, v19, v19
	v_max_f32_e32 v23, v23, v23
	v_max_f32_e32 v21, v21, v21
	v_med3_f32 v19, v19, s9, v244
	v_med3_f32 v23, v23, s9, v244
	v_exp_f32_e32 v25, v20
	v_med3_f32 v21, v21, s9, v244
	v_mul_f32_e32 v19, 0xbfb8aa3b, v19
	v_mul_f32_e32 v22, 0xbfb8aa3b, v23
	v_med3_f32 v18, v18, s9, v244
	v_mul_f32_e32 v23, 0xbfb8aa3b, v21
	v_exp_f32_e32 v20, v19
	v_exp_f32_e32 v21, v22
	v_add_f32_e32 v22, 1.0, v24
	v_mul_f32_e32 v18, 0xbfb8aa3b, v18
	v_rcp_f32_e32 v106, v22
	v_exp_f32_e32 v18, v18
	v_exp_f32_e32 v19, v23
	v_add_f32_e32 v23, 1.0, v25
	v_rcp_f32_e32 v107, v23
	v_add_f32_e32 v23, 1.0, v20
	v_rcp_f32_e32 v110, v23
	v_fma_f32 v23, v80, v106, v149
	v_add_f32_e32 v72, 1.0, v18
	v_add_f32_e32 v73, 1.0, v21
	v_mul_f32_e32 v23, v95, v23
	v_rcp_f32_e32 v22, v72
	v_rcp_f32_e32 v111, v73
	v_fma_f32 v72, v80, v107, v149
	v_max_f32_e32 v23, 0xda24260, v23
	v_rcp_f32_e32 v120, v23
	v_mul_f32_e32 v65, v23, v65
	v_mul_f32_e32 v23, v23, v72
	v_fma_f32 v88, v80, v110, v149
	v_max_f32_e32 v23, 0xda24260, v23
	v_bfe_u32 v72, v65, 16, 1
	v_rcp_f32_e32 v121, v23
	v_mul_f32_e32 v63, v23, v63
	v_mul_f32_e32 v23, v23, v88
	v_fma_f32 v95, v80, v111, v149
	v_add3_u32 v143, v65, v72, s10
	v_bfe_u32 v65, v63, 16, 1
	v_max_f32_e32 v23, 0xda24260, v23
	v_add3_u32 v146, v63, v65, s10
	v_rcp_f32_e32 v126, v23
	v_mul_f32_e32 v63, v23, v68
	v_mul_f32_e32 v23, v23, v95
	v_fma_f32 v73, v80, v22, v149
	v_bfe_u32 v65, v63, 16, 1
	v_max_f32_e32 v23, 0xda24260, v23
	v_add3_u32 v95, v63, v65, s10
	v_rcp_f32_e32 v127, v23
	v_mul_f32_e32 v63, v23, v71
	v_mul_f32_e32 v23, v23, v73
	v_bfe_u32 v65, v63, 16, 1
	v_max_f32_e32 v68, 0xda24260, v23
	v_add3_u32 v147, v63, v65, s10
	v_mul_f32_e32 v63, v68, v69
	v_bfe_u32 v65, v63, 16, 1
	v_add3_u32 v150, v63, v65, s10
	v_lshlrev_b32_e32 v65, 16, v131
	v_max_f32_e32 v65, v65, v65
	v_med3_f32 v65, v65, s9, v244
	v_add_f32_e32 v23, 1.0, v19
	v_mul_f32_e32 v65, 0xbfb8aa3b, v65
	v_rcp_f32_e32 v23, v23
	v_exp_f32_e32 v136, v65
	s_waitcnt vmcnt(0)
	v_lshlrev_b32_e32 v62, 16, v62
	v_max_f32_e32 v62, v62, v62
	v_fma_f32 v63, v80, v23, v149
	v_add_f32_e32 v65, 1.0, v136
	v_med3_f32 v62, v62, s9, v244
	v_mul_f32_e32 v63, v68, v63
	v_rcp_f32_e32 v138, v65
	v_mul_f32_e32 v62, 0xbfb8aa3b, v62
	v_max_f32_e32 v63, 0xda24260, v63
	v_lshlrev_b32_e32 v64, 16, v64
	v_exp_f32_e32 v137, v62
	v_mul_f32_e32 v64, v63, v64
	v_bfe_u32 v65, v64, 16, 1
	v_add3_u32 v151, v64, v65, s10
	v_fma_f32 v64, v80, v138, v149
	v_rcp_f32_e32 v131, v63
	v_mul_f32_e32 v63, v63, v64
	v_add_f32_e32 v64, 1.0, v137
	v_max_f32_e32 v62, 0xda24260, v63
	v_lshlrev_b32_e32 v63, 16, v139
	v_rcp_f32_e32 v139, v64
	v_mul_f32_e32 v63, v62, v63
	v_bfe_u32 v64, v63, 16, 1
	v_add3_u32 v152, v63, v64, s10
	v_fma_f32 v63, v80, v139, v149
	v_rcp_f32_e32 v140, v62
	v_mul_f32_e32 v62, v62, v63
	v_max_f32_e32 v88, 0xda24260, v62
	v_lshlrev_b32_e32 v62, 16, v70
	v_mul_f32_e32 v62, v88, v62
	v_bfe_u32 v63, v62, 16, 1
	v_add3_u32 v153, v62, v63, s10
	v_pk_mul_f32 v[62:63], v[88:89], v[86:87] op_sel_hi:[0,1]
	v_pk_mul_f32 v[64:65], v[88:89], v[84:85] op_sel_hi:[0,1]
	v_rcp_f32_e32 v130, v68
	v_cvt_pk_bf16_f32 v62, v62, v63
	v_cvt_pk_bf16_f32 v63, v64, v65
	v_pk_mul_f32 v[64:65], v[88:89], v[74:75] op_sel_hi:[0,1]
	v_pk_mul_f32 v[68:69], v[88:89], v[144:145] op_sel_hi:[0,1]
	v_cvt_pk_bf16_f32 v64, v64, v65
	v_cvt_pk_bf16_f32 v65, v68, v69
	v_pk_mul_f32 v[68:69], v[88:89], v[104:105] op_sel_hi:[0,1]
	v_pk_mul_f32 v[70:71], v[88:89], v[116:117] op_sel_hi:[0,1]
	v_and_b32_e32 v73, 0xffff0000, v67
	v_and_b32_e32 v72, 0xffff0000, v142
	v_cvt_pk_bf16_f32 v68, v68, v69
	v_cvt_pk_bf16_f32 v69, v70, v71
	v_pk_mul_f32 v[70:71], v[88:89], v[128:129] op_sel_hi:[0,1]
	v_pk_mul_f32 v[72:73], v[88:89], v[72:73] op_sel_hi:[0,1]
	v_cvt_pk_bf16_f32 v70, v70, v71
	v_cvt_pk_bf16_f32 v71, v72, v73
	v_pk_mul_f32 v[72:73], v[102:103], v[114:115]
	v_rcp_f32_e32 v141, v88
	v_pk_mul_f32 v[72:73], v[80:81], v[72:73] op_sel_hi:[0,1]
	v_pk_mul_f32 v[72:73], v[72:73], v[134:135]
	s_nop 0
	v_and_b32_sdwa v67, v73, v239 dst_sel:DWORD dst_unused:UNUSED_PAD src0_sel:WORD_1 src1_sel:DWORD
	v_and_b32_sdwa v74, v72, v239 dst_sel:DWORD dst_unused:UNUSED_PAD src0_sel:WORD_1 src1_sel:DWORD
	v_add3_u32 v67, v73, v67, s10
	v_add3_u32 v72, v72, v74, s10
	v_pk_mul_f32 v[74:75], v[78:79], v[108:109]
	ds_write_b16_d16_hi v17, v72 offset:6912
	ds_write_b16_d16_hi v17, v67 offset:7056
	v_and_b32_e32 v73, 0xffff0000, v67
	v_and_b32_e32 v72, 0xffff0000, v72
	v_pk_mul_f32 v[74:75], v[80:81], v[74:75] op_sel_hi:[0,1]
	v_pk_mul_f32 v[72:73], v[88:89], v[72:73] op_sel_hi:[0,1]
	v_pk_mul_f32 v[74:75], v[74:75], v[132:133]
	v_cvt_pk_bf16_f32 v72, v72, v73
	v_and_b32_sdwa v67, v75, v239 dst_sel:DWORD dst_unused:UNUSED_PAD src0_sel:WORD_1 src1_sel:DWORD
	v_and_b32_sdwa v73, v74, v239 dst_sel:DWORD dst_unused:UNUSED_PAD src0_sel:WORD_1 src1_sel:DWORD
	v_add3_u32 v67, v75, v67, s10
	v_add3_u32 v73, v74, v73, s10
	v_and_b32_e32 v75, 0xffff0000, v67
	v_and_b32_e32 v74, 0xffff0000, v73
	v_pk_mul_f32 v[74:75], v[88:89], v[74:75] op_sel_hi:[0,1]
	ds_write_b16_d16_hi v17, v73 offset:7200
	ds_write_b16_d16_hi v17, v67 offset:7344
	v_cvt_pk_bf16_f32 v73, v74, v75
	v_pk_mul_f32 v[74:75], v[76:77], v[82:83]
	s_nop 0
	v_pk_mul_f32 v[74:75], v[80:81], v[74:75] op_sel_hi:[0,1]
	v_pk_mul_f32 v[74:75], v[74:75], v[122:123]
	s_nop 0
	v_and_b32_sdwa v67, v75, v239 dst_sel:DWORD dst_unused:UNUSED_PAD src0_sel:WORD_1 src1_sel:DWORD
	v_and_b32_sdwa v76, v74, v239 dst_sel:DWORD dst_unused:UNUSED_PAD src0_sel:WORD_1 src1_sel:DWORD
	v_add3_u32 v67, v75, v67, s10
	v_add3_u32 v74, v74, v76, s10
	v_pk_mul_f32 v[76:77], v[112:113], v[118:119]
	ds_write_b16_d16_hi v17, v74 offset:7488
	ds_write_b16_d16_hi v17, v67 offset:7632
	v_and_b32_e32 v75, 0xffff0000, v67
	v_and_b32_e32 v74, 0xffff0000, v74
	v_pk_mul_f32 v[76:77], v[80:81], v[76:77] op_sel_hi:[0,1]
	v_pk_mul_f32 v[74:75], v[88:89], v[74:75] op_sel_hi:[0,1]
	v_pk_mul_f32 v[76:77], v[76:77], v[124:125]
	v_cvt_pk_bf16_f32 v74, v74, v75
	v_and_b32_sdwa v75, v76, v239 dst_sel:DWORD dst_unused:UNUSED_PAD src0_sel:WORD_1 src1_sel:DWORD
	v_and_b32_sdwa v67, v77, v239 dst_sel:DWORD dst_unused:UNUSED_PAD src0_sel:WORD_1 src1_sel:DWORD
	v_add3_u32 v75, v76, v75, s10
	v_add3_u32 v67, v77, v67, s10
	ds_write_b16_d16_hi v17, v75 offset:7776
	ds_write_b16_d16_hi v17, v67 offset:7920
	v_pk_mul_f32 v[24:25], v[24:25], v[106:107]
	v_and_b32_e32 v77, 0xffff0000, v67
	v_and_b32_e32 v76, 0xffff0000, v75
	v_pk_mul_f32 v[24:25], v[80:81], v[24:25] op_sel_hi:[0,1]
	v_pk_mul_f32 v[76:77], v[88:89], v[76:77] op_sel_hi:[0,1]
	v_pk_mul_f32 v[24:25], v[24:25], v[120:121]
	v_cvt_pk_bf16_f32 v75, v76, v77
	v_and_b32_sdwa v67, v25, v239 dst_sel:DWORD dst_unused:UNUSED_PAD src0_sel:WORD_1 src1_sel:DWORD
	v_and_b32_sdwa v76, v24, v239 dst_sel:DWORD dst_unused:UNUSED_PAD src0_sel:WORD_1 src1_sel:DWORD
	v_add3_u32 v25, v25, v67, s10
	v_add3_u32 v24, v24, v76, s10
	v_pk_mul_f32 v[20:21], v[20:21], v[110:111]
	ds_write_b16_d16_hi v17, v143 offset:3456
	ds_write_b16_d16_hi v17, v146 offset:3600
	ds_write_b16_d16_hi v17, v95 offset:3744
	ds_write_b16_d16_hi v17, v147 offset:3888
	ds_write_b16_d16_hi v17, v150 offset:4032
	ds_write_b16_d16_hi v17, v151 offset:4176
	ds_write_b16_d16_hi v17, v152 offset:4320
	ds_write_b16_d16_hi v17, v153 offset:4464
	ds_write_b16_d16_hi v17, v24 offset:8064
	ds_write_b16_d16_hi v17, v25 offset:8208
	v_and_b32_e32 v25, 0xffff0000, v25
	v_and_b32_e32 v24, 0xffff0000, v24
	v_pk_mul_f32 v[20:21], v[80:81], v[20:21] op_sel_hi:[0,1]
	v_pk_mul_f32 v[24:25], v[88:89], v[24:25] op_sel_hi:[0,1]
	v_pk_mul_f32 v[20:21], v[20:21], v[126:127]
	v_cvt_pk_bf16_f32 v76, v24, v25
	v_and_b32_sdwa v24, v21, v239 dst_sel:DWORD dst_unused:UNUSED_PAD src0_sel:WORD_1 src1_sel:DWORD
	v_and_b32_sdwa v25, v20, v239 dst_sel:DWORD dst_unused:UNUSED_PAD src0_sel:WORD_1 src1_sel:DWORD
	v_add3_u32 v21, v21, v24, s10
	v_add3_u32 v20, v20, v25, s10
	v_pk_mul_f32 v[18:19], v[18:19], v[22:23]
	ds_write_b16_d16_hi v17, v20 offset:8352
	ds_write_b16_d16_hi v17, v21 offset:8496
	v_and_b32_e32 v21, 0xffff0000, v21
	v_and_b32_e32 v20, 0xffff0000, v20
	v_pk_mul_f32 v[18:19], v[80:81], v[18:19] op_sel_hi:[0,1]
	v_pk_mul_f32 v[20:21], v[88:89], v[20:21] op_sel_hi:[0,1]
	v_pk_mul_f32 v[18:19], v[18:19], v[130:131]
	v_cvt_pk_bf16_f32 v77, v20, v21
	v_and_b32_sdwa v20, v19, v239 dst_sel:DWORD dst_unused:UNUSED_PAD src0_sel:WORD_1 src1_sel:DWORD
	v_and_b32_sdwa v21, v18, v239 dst_sel:DWORD dst_unused:UNUSED_PAD src0_sel:WORD_1 src1_sel:DWORD
	v_add3_u32 v19, v19, v20, s10
	v_add3_u32 v18, v18, v21, s10
	ds_write_b16_d16_hi v17, v18 offset:8640
	ds_write_b16_d16_hi v17, v19 offset:8784
	v_and_b32_e32 v19, 0xffff0000, v19
	v_and_b32_e32 v18, 0xffff0000, v18
	v_pk_mul_f32 v[18:19], v[88:89], v[18:19] op_sel_hi:[0,1]
	v_cvt_pk_bf16_f32 v78, v18, v19
	v_pk_mul_f32 v[18:19], v[136:137], v[138:139]
	s_nop 0
	v_pk_mul_f32 v[18:19], v[80:81], v[18:19] op_sel_hi:[0,1]
	v_pk_mul_f32 v[18:19], v[18:19], v[140:141]
	s_nop 0
	v_and_b32_sdwa v21, v18, v239 dst_sel:DWORD dst_unused:UNUSED_PAD src0_sel:WORD_1 src1_sel:DWORD
	v_and_b32_sdwa v20, v19, v239 dst_sel:DWORD dst_unused:UNUSED_PAD src0_sel:WORD_1 src1_sel:DWORD
	v_add3_u32 v18, v18, v21, s10
	v_add3_u32 v19, v19, v20, s10
	ds_write_b16_d16_hi v17, v18 offset:8928
	ds_write_b16_d16_hi v17, v19 offset:9072
	v_and_b32_e32 v19, 0xffff0000, v19
	v_and_b32_e32 v18, 0xffff0000, v18
	v_pk_mul_f32 v[18:19], v[88:89], v[18:19] op_sel_hi:[0,1]
	v_cvt_pk_bf16_f32 v79, v18, v19
	v_lshl_add_u32 v16, v16, 2, v92
	ds_write_b128 v66, v[62:65] offset:9216
	ds_write_b128 v66, v[68:71] offset:9232
	ds_write_b128 v66, v[72:75] offset:9248
	ds_write_b128 v66, v[76:79] offset:9264
	ds_write_b32 v16, v88 offset:19456
	ds_write_b128 v66, v[12:15] offset:14336
	ds_write_b128 v66, v[8:11] offset:14352
	ds_write_b128 v66, v[4:7] offset:14368
	ds_write_b128 v66, v[0:3] offset:14384
	s_waitcnt lgkmcnt(0)
	v_mov_b64_e32 v[242:243], s[44:45]
	s_movk_i32 s101, 0x1200
	v_mad_i64_i32 v[242:243], s[98:99], v93, s101, v[242:243]
	v_lshl_add_u64 v[242:243], v[242:243], 0, v[90:91]
	v_mov_b32_e32 v248, v94
	v_mov_b32_e32 v249, 0
	v_lshl_add_u64 v[242:243], v[248:249], 1, v[242:243]
	v_mul_u32_u24_e32 v248, 0x5556, v94
	v_lshrrev_b32_e32 v248, 16, v248
	v_mul_u32_u24_e32 v250, 3, v248
	v_sub_u32_e32 v250, v94, v250
	v_add_u32_e32 v248, 32, v248
	v_mul_u32_u24_e32 v248, 0x1200, v248
	v_lshl_add_u32 v248, v250, 9, v248
	v_add_u32_e32 v248, 0xb200800, v248
	v_lshl_add_u64 v[250:251], v[242:243], 0, v[248:249]
	global_load_dword v196, v[250:251], off
	v_add_u32_e32 v248, 64, v94
	v_mul_u32_u24_e32 v250, 0x5556, v248
	v_lshrrev_b32_e32 v250, 16, v250
	v_mul_u32_u24_e32 v251, 3, v250
	v_sub_u32_e32 v251, v248, v251
	v_add_u32_e32 v250, 32, v250
	v_mul_u32_u24_e32 v250, 0x1200, v250
	v_lshl_add_u32 v250, v251, 9, v250
	v_add_u32_e32 v248, 0xb200800, v250
	v_lshl_add_u64 v[250:251], v[242:243], 0, v[248:249]
	global_load_dword v196, v[250:251], off
	s_movk_i32 s17, 0x90
	v_mad_u32_u24 v72, v35, s17, v92
	v_lshlrev_b32_e32 v73, 4, v81
	v_add_u32_e32 v66, v72, v73
	ds_read_b128 v[0:3], v66 offset:4608
	ds_read_b128 v[4:7], v66
	ds_read_b128 v[18:21], v66 offset:32
	ds_read_b128 v[22:25], v66 offset:4640
	ds_read_b128 v[62:65], v66 offset:4672
	s_waitcnt lgkmcnt(3)
	v_mfma_f32_32x32x16_bf16 v[2:17], v[0:3], v[4:7], 0
	v_lshlrev_b32_e32 v70, 2, v81
	v_cmp_le_i32_e32 vcc, v70, v35
	v_or_b32_e32 v74, 2, v70
	v_or_b32_e32 v75, 3, v70
	v_or_b32_e32 v88, v93, v35
	v_add_u32_e32 v76, 8, v70
	v_lshlrev_b64 v[0:1], 11, v[88:89]
	s_waitcnt lgkmcnt(1)
	v_mfma_f32_32x32x16_bf16 v[2:17], v[22:25], v[18:21], v[2:17]
	ds_read_b128 v[18:21], v66 offset:64
	ds_read_b128 v[22:25], v66 offset:4704
	ds_read_b128 v[66:69], v66 offset:96
	v_lshl_add_u64 v[0:1], s[2:3], 0, v[0:1]
	v_ashrrev_i32_e32 v71, 31, v70
	v_lshl_add_u64 v[0:1], v[0:1], 0, v[90:91]
	v_lshl_add_u64 v[84:85], v[70:71], 1, v[0:1]
	v_add_u32_e32 v0, 16, v70
	s_waitcnt lgkmcnt(2)
	v_mfma_f32_32x32x16_bf16 v[2:17], v[62:65], v[18:21], v[2:17]
	v_add_u32_e32 v18, 9, v70
	v_add_u32_e32 v19, 10, v70
	v_add_u32_e32 v20, 11, v70
	v_lshlrev_b32_e32 v138, 16, v42
	v_and_b32_e32 v139, 0xffff0000, v42
	v_lshlrev_b32_e32 v42, 16, v43
	v_and_b32_e32 v43, 0xffff0000, v43
	s_waitcnt lgkmcnt(0)
	v_mfma_f32_32x32x16_bf16 v[2:17], v[22:25], v[66:69], v[2:17]
	v_lshlrev_b32_e32 v140, 16, v36
	v_and_b32_e32 v141, 0xffff0000, v36
	v_lshlrev_b32_e32 v142, 16, v37
	v_and_b32_e32 v143, 0xffff0000, v37
	v_cvt_pk_bf16_f32 v130, v138, v139
	v_cvt_pk_bf16_f32 v131, v42, v43
	v_cvt_pk_bf16_f32 v132, v140, v141
	s_nop 4
	v_cndmask_b32_e32 v21, 0, v2, vcc
	v_cmp_lt_i32_e32 vcc, v70, v35
	v_cvt_pk_bf16_f32 v133, v142, v143
	v_add_u32_e32 v95, v92, v73
	v_cndmask_b32_e32 v22, 0, v3, vcc
	v_cmp_le_i32_e32 vcc, v74, v35
	v_lshlrev_b32_e32 v74, 3, v81
	v_add_u32_e32 v88, v72, v74
	v_cndmask_b32_e32 v4, 0, v4, vcc
	v_cmp_le_i32_e32 vcc, v75, v35
	v_mad_u32_u24 v144, v35, s16, v95
	v_cvt_pk_bf16_f32 v36, v44, v45
	v_cndmask_b32_e32 v5, 0, v5, vcc
	v_cmp_le_i32_e32 vcc, v76, v35
	v_cvt_pk_bf16_f32 v37, v46, v47
	v_lshlrev_b32_e32 v78, 16, v60
	v_cndmask_b32_e32 v6, 0, v6, vcc
	v_cmp_le_i32_e32 vcc, v18, v35
	v_cvt_pk_bf16_f32 v18, v21, v22
	v_and_b32_e32 v79, 0xffff0000, v60
	v_cndmask_b32_e32 v7, 0, v7, vcc
	v_cmp_le_i32_e32 vcc, v19, v35
	v_cvt_pk_bf16_f32 v19, v4, v5
	v_lshlrev_b32_e32 v82, 16, v61
	v_cndmask_b32_e32 v8, 0, v8, vcc
	v_cmp_le_i32_e32 vcc, v20, v35
	v_cvt_pk_bf16_f32 v20, v6, v7
	v_and_b32_e32 v83, 0xffff0000, v61
	v_cndmask_b32_e32 v9, 0, v9, vcc
	v_cmp_le_i32_e32 vcc, v0, v35
	v_add_u32_e32 v0, 17, v70
	v_cvt_pk_bf16_f32 v21, v8, v9
	v_cndmask_b32_e32 v23, 0, v10, vcc
	v_cmp_le_i32_e32 vcc, v0, v35
	v_add_u32_e32 v0, 18, v70
	v_add_u32_e32 v10, 26, v70
	v_cndmask_b32_e32 v24, 0, v11, vcc
	v_cmp_le_i32_e32 vcc, v0, v35
	v_add_u32_e32 v0, 19, v70
	v_cvt_pk_bf16_f32 v22, v23, v24
	v_cndmask_b32_e32 v25, 0, v12, vcc
	v_cmp_le_i32_e32 vcc, v0, v35
	v_add_u32_e32 v0, 24, v70
	v_lshlrev_b32_e32 v60, 16, v58
	v_cndmask_b32_e32 v68, 0, v13, vcc
	v_cmp_le_i32_e32 vcc, v0, v35
	v_add_u32_e32 v0, 25, v70
	v_add_u32_e32 v70, 27, v70
	v_cndmask_b32_e32 v69, 0, v14, vcc
	v_cmp_le_i32_e32 vcc, v0, v35
	v_mul_u32_u24_e32 v0, 0x50, v35
	v_add3_u32 v81, v92, v74, v0
	v_add_u32_e32 v11, 0x3800, v81
	ds_read2_b64 v[0:3], v11 offset1:2
	ds_read2_b64 v[64:67], v11 offset0:4 offset1:6
	v_cndmask_b32_e32 v71, 0, v15, vcc
	v_cmp_le_i32_e32 vcc, v10, v35
	s_waitcnt lgkmcnt(1)
	v_mfma_f32_32x32x16_bf16 v[0:15], v[0:3], v[18:21], 0
	v_cndmask_b32_e32 v16, 0, v16, vcc
	v_cmp_le_i32_e32 vcc, v70, v35
	v_cvt_pk_bf16_f32 v23, v25, v68
	v_cvt_pk_bf16_f32 v24, v69, v71
	v_cndmask_b32_e32 v17, 0, v17, vcc
	v_cvt_pk_bf16_f32 v25, v16, v17
	ds_read2_b64 v[106:109], v88 offset1:2
	ds_read2_b64 v[110:113], v88 offset0:4 offset1:6
	ds_read2_b64 v[114:117], v88 offset0:8 offset1:10
	ds_read2_b64 v[118:121], v88 offset0:12 offset1:14
	s_waitcnt lgkmcnt(4)
	v_mfma_f32_32x32x16_bf16 v[0:15], v[64:67], v[22:25], v[0:15]
	v_cvt_pk_bf16_f32 v35, v40, v41
	v_and_b32_e32 v61, 0xffff0000, v58
	v_lshlrev_b32_e32 v58, 16, v59
	v_and_b32_e32 v59, 0xffff0000, v59
	v_cvt_pk_bf16_f32 v122, v78, v79
	v_cvt_pk_bf16_f32 v123, v82, v83
	v_cvt_pk_bf16_f32 v124, v60, v61
	s_waitcnt lgkmcnt(3)
	v_mfma_f32_32x32x16_bf16 v[0:15], v[130:133], v[106:109], v[0:15]
	v_lshlrev_b32_e32 v106, 16, v34
	v_and_b32_e32 v107, 0xffff0000, v34
	v_cvt_pk_bf16_f32 v34, v106, v107
	v_cvt_pk_bf16_f32 v125, v58, v59
	v_lshlrev_b32_e32 v86, 16, v56
	v_and_b32_e32 v87, 0xffff0000, v56
	v_lshlrev_b32_e32 v56, 16, v57
	s_waitcnt lgkmcnt(2)
	v_mfma_f32_32x32x16_bf16 v[0:15], v[34:37], v[110:113], v[0:15]
	v_and_b32_e32 v57, 0xffff0000, v57
	v_lshlrev_b32_e32 v102, 16, v54
	v_and_b32_e32 v103, 0xffff0000, v54
	v_lshlrev_b32_e32 v104, 16, v55
	v_and_b32_e32 v105, 0xffff0000, v55
	v_cvt_pk_bf16_f32 v126, v86, v87
	v_cvt_pk_bf16_f32 v127, v56, v57
	s_waitcnt lgkmcnt(1)
	v_mfma_f32_32x32x16_bf16 v[0:15], v[122:125], v[114:117], v[0:15]
	v_cvt_pk_bf16_f32 v128, v102, v103
	v_cvt_pk_bf16_f32 v129, v104, v105
	s_mov_b64 s[2:3], 0x16f00600
	v_lshl_add_u64 v[62:63], v[84:85], 0, s[2:3]
	s_mov_b32 s2, 0x16f00000
	v_lshlrev_b32_e32 v16, 16, v26
	v_and_b32_e32 v17, 0xffff0000, v26
	s_waitcnt lgkmcnt(0)
	v_mfma_f32_32x32x16_bf16 v[0:15], v[126:129], v[118:121], v[0:15]
	v_lshlrev_b32_e32 v64, 16, v27
	v_and_b32_e32 v65, 0xffff0000, v27
	v_lshlrev_b32_e32 v66, 16, v28
	v_and_b32_e32 v67, 0xffff0000, v28
	v_lshlrev_b32_e32 v68, 16, v29
	v_and_b32_e32 v69, 0xffff0000, v29
	v_lshlrev_b32_e32 v70, 16, v30
	s_nop 4
	v_cvt_pk_bf16_f32 v0, v0, v1
	v_cvt_pk_bf16_f32 v1, v2, v3
	v_add_co_u32_e32 v2, vcc, s2, v84
	v_and_b32_e32 v71, 0xffff0000, v30
	s_nop 0
	v_addc_co_u32_e32 v3, vcc, 0, v85, vcc
	global_store_dwordx2 v[2:3], v[0:1], off offset:1536
	v_cvt_pk_bf16_f32 v0, v4, v5
	v_cvt_pk_bf16_f32 v1, v6, v7
	global_store_dwordx2 v[62:63], v[0:1], off offset:16
	v_cvt_pk_bf16_f32 v0, v8, v9
	v_cvt_pk_bf16_f32 v1, v10, v11
	v_lshlrev_b32_e32 v72, 16, v31
	v_and_b32_e32 v73, 0xffff0000, v31
	v_lshlrev_b32_e32 v74, 16, v32
	v_and_b32_e32 v75, 0xffff0000, v32
	v_lshlrev_b32_e32 v76, 16, v33
	v_and_b32_e32 v77, 0xffff0000, v33
	v_lshlrev_b32_e32 v54, 16, v52
	v_and_b32_e32 v55, 0xffff0000, v52
	v_lshlrev_b32_e32 v52, 16, v53
	v_and_b32_e32 v53, 0xffff0000, v53
	v_lshlrev_b32_e32 v130, 16, v50
	v_and_b32_e32 v131, 0xffff0000, v50
	v_lshlrev_b32_e32 v50, 16, v51
	v_and_b32_e32 v51, 0xffff0000, v51
	v_lshlrev_b32_e32 v132, 16, v48
	v_and_b32_e32 v133, 0xffff0000, v48
	v_lshlrev_b32_e32 v48, 16, v49
	v_and_b32_e32 v49, 0xffff0000, v49
	v_lshlrev_b32_e32 v114, 16, v38
	v_and_b32_e32 v115, 0xffff0000, v38
	v_lshlrev_b32_e32 v116, 16, v39
	v_and_b32_e32 v117, 0xffff0000, v39
	global_store_dwordx2 v[62:63], v[0:1], off offset:32
	v_cvt_pk_bf16_f32 v0, v12, v13
	v_cvt_pk_bf16_f32 v1, v14, v15
	v_cvt_pk_bf16_f32 v26, v16, v17
	v_cvt_pk_bf16_f32 v27, v64, v65
	v_cvt_pk_bf16_f32 v28, v66, v67
	v_cvt_pk_bf16_f32 v29, v68, v69
	v_cvt_pk_bf16_f32 v30, v70, v71
	v_cvt_pk_bf16_f32 v31, v72, v73
	v_cvt_pk_bf16_f32 v32, v74, v75
	v_cvt_pk_bf16_f32 v33, v76, v77
	v_cvt_pk_bf16_f32 v134, v54, v55
	v_cvt_pk_bf16_f32 v135, v52, v53
	v_cvt_pk_bf16_f32 v136, v130, v131
	v_cvt_pk_bf16_f32 v137, v50, v51
	v_cvt_pk_bf16_f32 v34, v132, v133
	v_cvt_pk_bf16_f32 v35, v48, v49
	v_cvt_pk_bf16_f32 v36, v114, v115
	v_cvt_pk_bf16_f32 v37, v116, v117
	global_store_dwordx2 v[62:63], v[0:1], off offset:48
	v_add_u32_e32 v38, 0x4000, v81
	ds_read2_b64 v[0:3], v38 offset0:64 offset1:66
	s_waitcnt lgkmcnt(0)
	v_mfma_f32_32x32x16_bf16 v[0:15], v[0:3], v[18:21], 0
	ds_read2_b64 v[18:21], v38 offset0:68 offset1:70
	s_waitcnt lgkmcnt(0)
	v_mfma_f32_32x32x16_bf16 v[0:15], v[18:21], v[22:25], v[0:15]
	ds_read2_b64 v[18:21], v88 offset1:2
	s_waitcnt lgkmcnt(0)
	v_mfma_f32_32x32x16_bf16 v[0:15], v[134:137], v[18:21], v[0:15]
	ds_read2_b64 v[18:21], v88 offset0:4 offset1:6
	s_waitcnt lgkmcnt(0)
	v_mfma_f32_32x32x16_bf16 v[0:15], v[34:37], v[18:21], v[0:15]
	ds_read2_b64 v[18:21], v88 offset0:8 offset1:10
	s_waitcnt lgkmcnt(0)
	v_mfma_f32_32x32x16_bf16 v[0:15], v[26:29], v[18:21], v[0:15]
	ds_read2_b64 v[18:21], v88 offset0:12 offset1:14
	s_waitcnt lgkmcnt(0)
	v_mfma_f32_32x32x16_bf16 v[0:15], v[30:33], v[18:21], v[0:15]
	s_nop 11
	v_cvt_pk_bf16_f32 v0, v0, v1
	v_cvt_pk_bf16_f32 v1, v2, v3
	v_cvt_pk_bf16_f32 v2, v4, v5
	v_cvt_pk_bf16_f32 v3, v6, v7
	v_cvt_pk_bf16_f32 v4, v8, v9
	v_cvt_pk_bf16_f32 v5, v10, v11
	v_cvt_pk_bf16_f32 v6, v12, v13
	v_cvt_pk_bf16_f32 v7, v14, v15
	global_store_dwordx2 v[62:63], v[0:1], off offset:64
	global_store_dwordx2 v[62:63], v[2:3], off offset:80
	global_store_dwordx2 v[62:63], v[4:5], off offset:96
	global_store_dwordx2 v[62:63], v[6:7], off offset:112
	ds_read_b128 v[0:3], v95 offset:19456
	ds_read_b128 v[4:7], v95 offset:19488
	ds_read_b128 v[8:11], v95 offset:19520
	ds_read_b128 v[12:15], v95 offset:19552
	ds_read_b128 v[18:21], v144 offset:9216
	s_waitcnt lgkmcnt(4)
	v_pk_mul_f32 v[34:35], v[2:3], v[42:43]
	ds_read_b128 v[22:25], v144 offset:14336
	s_waitcnt lgkmcnt(3)
	v_pk_mul_f32 v[42:43], v[10:11], v[40:41]
	v_pk_mul_f32 v[40:41], v[8:9], v[106:107]
	ds_read_b128 v[26:29], v144 offset:9248
	ds_read_b128 v[106:109], v144 offset:14368
	ds_read_b128 v[110:113], v144 offset:16896
	v_pk_mul_f32 v[32:33], v[0:1], v[138:139]
	v_pk_mul_f32 v[38:39], v[6:7], v[142:143]
	v_pk_mul_f32 v[36:37], v[4:5], v[140:141]
	s_waitcnt lgkmcnt(5)
	v_pk_mul_f32 v[46:47], v[14:15], v[46:47]
	v_pk_mul_f32 v[44:45], v[12:13], v[44:45]
	v_pk_mul_f32 v[0:1], v[0:1], v[54:55]
	v_pk_mul_f32 v[2:3], v[2:3], v[52:53]
	v_pk_mul_f32 v[4:5], v[4:5], v[130:131]
	v_pk_mul_f32 v[6:7], v[6:7], v[50:51]
	v_pk_mul_f32 v[8:9], v[8:9], v[132:133]
	v_pk_mul_f32 v[10:11], v[10:11], v[48:49]
	v_pk_mul_f32 v[12:13], v[12:13], v[114:115]
	v_pk_mul_f32 v[14:15], v[14:15], v[116:117]
	s_waitcnt lgkmcnt(3)
	v_mfma_f32_32x32x16_bf16 v[32:47], v[18:21], v[22:25], v[32:47]
	ds_read_b128 v[114:117], v144 offset:16928
	s_waitcnt lgkmcnt(1)
	v_mfma_f32_32x32x16_bf16 v[0:15], v[18:21], v[110:113], v[0:15]
	v_mfma_f32_32x32x16_bf16 v[32:47], v[26:29], v[106:109], v[32:47]
	s_waitcnt lgkmcnt(0)
	v_mfma_f32_32x32x16_bf16 v[0:15], v[26:29], v[114:117], v[0:15]
	ds_read_b128 v[18:21], v95 offset:19584
	ds_read_b128 v[26:29], v95 offset:19616
	ds_read_b128 v[118:121], v95 offset:19648
	ds_read_b128 v[122:125], v95 offset:19680
	ds_read_b128 v[126:129], v144 offset:11776
	s_waitcnt lgkmcnt(4)
	v_pk_mul_f32 v[50:51], v[20:21], v[82:83]
	v_pk_mul_f32 v[48:49], v[18:19], v[78:79]
	s_waitcnt lgkmcnt(3)
	v_pk_mul_f32 v[54:55], v[28:29], v[58:59]
	v_pk_mul_f32 v[52:53], v[26:27], v[60:61]
	s_waitcnt lgkmcnt(2)
	v_pk_mul_f32 v[58:59], v[120:121], v[56:57]
	v_pk_mul_f32 v[56:57], v[118:119], v[86:87]
	s_waitcnt lgkmcnt(1)
	v_pk_mul_f32 v[62:63], v[124:125], v[104:105]
	v_pk_mul_f32 v[60:61], v[122:123], v[102:103]
	ds_read_b128 v[82:85], v144 offset:11808
	v_pk_mul_f32 v[16:17], v[18:19], v[16:17]
	s_waitcnt lgkmcnt(1)
	v_mfma_f32_32x32x16_bf16 v[48:63], v[126:129], v[22:25], v[48:63]
	v_mul_f32_e64 v18, v20, v64
	v_mul_f32_e64 v19, v21, v65
	v_mul_f32_e64 v20, v26, v66
	v_mul_f32_e64 v21, v27, v67
	v_mul_f32_e64 v22, v28, v68
	v_mul_f32_e64 v23, v29, v69
	v_pk_mul_f32 v[24:25], v[118:119], v[70:71]
	v_pk_mul_f32 v[26:27], v[120:121], v[72:73]
	v_pk_mul_f32 v[28:29], v[122:123], v[74:75]
	v_pk_mul_f32 v[30:31], v[124:125], v[76:77]
	s_waitcnt lgkmcnt(0)
	s_waitcnt lgkmcnt(0)
	v_mfma_f32_32x32x16_bf16 v[48:63], v[82:85], v[106:109], v[48:63]
	v_mfma_f32_32x32x16_bf16 v[16:31], v[126:129], v[110:113], v[16:31]
	v_mfma_f32_32x32x16_bf16 v[16:31], v[82:85], v[114:117], v[16:31]
	v_mov_b32_e32 v82, v94
	s_mov_b64 s[16:17], s[44:45]
	v_or_b32_e32 v95, 32, v93
	v_and_b32_e32 v124, 31, v82
	v_ashrrev_i32_e32 v125, 5, v82
	v_mov_b64_e32 v[64:65], s[16:17]
	s_movk_i32 s2, 0x1200
	v_mad_i64_i32 v[64:65], s[2:3], v95, s2, v[64:65]
	v_ashrrev_i32_e32 v83, 31, v82
	v_lshl_add_u64 v[64:65], v[64:65], 0, v[90:91]
	v_lshl_add_u64 v[64:65], v[82:83], 1, v[64:65]
	v_lshl_add_u64 v[114:115], v[64:65], 0, s[0:1]
	global_load_ushort v88, v[114:115], off offset:2560
	global_load_ushort v81, v[114:115], off offset:3072
	v_add_co_u32_e32 v112, vcc, s7, v64
	s_mov_b32 s0, 0xb20f000
	s_nop 0
	v_addc_co_u32_e32 v113, vcc, 0, v65, vcc
	global_load_ushort v126, v[112:113], off offset:3584
	v_add_co_u32_e32 v110, vcc, s11, v64
	v_lshl_add_u32 v83, v82, 1, v92
	s_nop 0
	v_addc_co_u32_e32 v111, vcc, 0, v65, vcc
	v_add_co_u32_e32 v108, vcc, s12, v64
	s_waitcnt vmcnt(1)
	v_lshlrev_b32_e32 v81, 16, v81
	v_max_f32_e32 v81, v81, v81
	v_med3_f32 v81, v81, s9, v244
	v_mul_f32_e32 v81, 0xbfb8aa3b, v81
	v_exp_f32_e32 v81, v81
	v_addc_co_u32_e32 v109, vcc, 0, v65, vcc
	v_add_co_u32_e32 v106, vcc, s13, v64
	v_add_f32_e32 v116, 1.0, v81
	v_rcp_f32_e32 v116, v116
	v_addc_co_u32_e32 v107, vcc, 0, v65, vcc
	v_add_co_u32_e32 v104, vcc, s14, v64
	v_fma_f32 v117, v80, v116, v149
	v_max_f32_e32 v183, 0xda24260, v117
	v_mul_f32_e32 v81, v81, v116
	v_rcp_f32_e32 v116, v183
	v_mul_f32_e32 v81, v80, v81
	v_addc_co_u32_e32 v105, vcc, 0, v65, vcc
	v_mul_f32_e32 v81, v81, v116
	v_bfe_u32 v116, v81, 16, 1
	v_add3_u32 v133, v81, v116, s10
	global_load_ushort v81, v[114:115], off offset:2048
	global_load_ushort v127, v[110:111], off offset:512
	global_load_ushort v128, v[108:109], off offset:1536
	global_load_ushort v129, v[106:107], off offset:2560
	global_load_ushort v130, v[104:105], off offset:3584
	v_add_co_u32_e32 v102, vcc, s15, v64
	s_waitcnt vmcnt(4)
	v_lshlrev_b32_e32 v81, 16, v81
	v_addc_co_u32_e32 v103, vcc, 0, v65, vcc
	v_add_co_u32_e32 v86, vcc, s18, v64
	global_load_ushort v131, v[102:103], off offset:512
	s_nop 0
	v_addc_co_u32_e32 v87, vcc, 0, v65, vcc
	v_add_co_u32_e32 v74, vcc, s19, v64
	global_load_ushort v132, v[86:87], off offset:1536
	s_nop 0
	v_addc_co_u32_e32 v75, vcc, 0, v65, vcc
	v_add_co_u32_e32 v78, vcc, s21, v64
	global_load_ushort v134, v[74:75], off offset:2560
	s_nop 0
	v_addc_co_u32_e32 v79, vcc, 0, v65, vcc
	v_add_co_u32_e32 v76, vcc, s30, v64
	global_load_ushort v135, v[78:79], off offset:3584
	s_nop 0
	v_addc_co_u32_e32 v77, vcc, 0, v65, vcc
	v_add_co_u32_e32 v84, vcc, s31, v64
	v_mul_f32_e32 v81, v183, v81
	s_nop 0
	v_addc_co_u32_e32 v85, vcc, 0, v65, vcc
	v_add_co_u32_e32 v66, vcc, s34, v64
	global_load_ushort v137, v[84:85], off offset:1536
	global_load_ushort v136, v[76:77], off offset:512
	v_addc_co_u32_e32 v67, vcc, 0, v65, vcc
	v_add_co_u32_e32 v72, vcc, s35, v64
	global_load_ushort v138, v[66:67], off offset:2560
	s_nop 0
	v_addc_co_u32_e32 v73, vcc, 0, v65, vcc
	v_add_co_u32_e32 v68, vcc, s36, v64
	global_load_ushort v139, v[72:73], off offset:3584
	s_nop 0
	v_addc_co_u32_e32 v69, vcc, 0, v65, vcc
	v_add_co_u32_e32 v70, vcc, s37, v64
	global_load_ushort v140, v[68:69], off offset:512
	s_nop 0
	v_addc_co_u32_e32 v71, vcc, 0, v65, vcc
	v_add_co_u32_e32 v116, vcc, s40, v64
	global_load_ushort v141, v[70:71], off offset:1536
	s_nop 0
	v_addc_co_u32_e32 v117, vcc, 0, v65, vcc
	global_load_ushort v187, v[116:117], off offset:3584
	global_load_ushort v182, v[116:117], off offset:2560
	v_bfe_u32 v114, v81, 16, 1
	v_add3_u32 v188, v81, v114, s10
	v_add_co_u32_e32 v114, vcc, s41, v64
	s_nop 1
	v_addc_co_u32_e32 v115, vcc, 0, v65, vcc
	v_add_co_u32_e32 v118, vcc, s46, v64
	s_nop 1
	v_addc_co_u32_e32 v119, vcc, 0, v65, vcc
	global_load_ushort v180, v[118:119], off offset:-4096
	global_load_ushort v176, v[112:113], off offset:3072
	global_load_ushort v175, v[118:119], off offset:512
	global_load_ushort v170, v[114:115], off offset:3584
	global_load_ushort v181, v[110:111], off offset:1024
	global_load_ushort v178, v[110:111], off
	v_add_co_u32_e32 v120, vcc, s28, v64
	s_nop 1
	v_addc_co_u32_e32 v121, vcc, 0, v65, vcc
	v_add_co_u32_e32 v122, vcc, s29, v64
	global_load_ushort v186, v[120:121], off offset:1536
	global_load_ushort v185, v[120:121], off offset:512
	global_load_ushort v184, v[108:109], off offset:2048
	global_load_ushort v179, v[108:109], off offset:1024
	v_addc_co_u32_e32 v123, vcc, 0, v65, vcc
	v_add_co_u32_e32 v190, vcc, s42, v64
	global_load_ushort v177, v[122:123], off offset:2560
	global_load_ushort v173, v[122:123], off offset:1536
	global_load_ushort v174, v[106:107], off offset:3072
	global_load_ushort v172, v[106:107], off offset:2048
	v_addc_co_u32_e32 v191, vcc, 0, v65, vcc
	v_add_co_u32_e32 v106, vcc, s6, v64
	global_load_ushort v171, v[190:191], off offset:3584
	global_load_ushort v169, v[190:191], off offset:2560
	v_addc_co_u32_e32 v107, vcc, 0, v65, vcc
	v_add_co_u32_e32 v154, vcc, s49, v64
	s_waitcnt vmcnt(4)
	v_lshlrev_b32_e32 v173, 16, v173
	v_addc_co_u32_e32 v155, vcc, 0, v65, vcc
	v_add_co_u32_e32 v192, vcc, s0, v64
	s_mov_b32 s0, 0xb211000
	s_nop 0
	v_addc_co_u32_e32 v193, vcc, 0, v65, vcc
	v_add_co_u32_e32 v194, vcc, s0, v64
	s_mov_b32 s0, 0xb21a000
	s_nop 0
	v_addc_co_u32_e32 v195, vcc, 0, v65, vcc
	v_add_co_u32_e32 v108, vcc, s43, v64
	global_load_ushort v166, v[154:155], off offset:-4096
	global_load_ushort v164, v[104:105], off offset:3072
	global_load_ushort v167, v[154:155], off offset:512
	global_load_ushort v158, v[106:107], off offset:3584
	global_load_ushort v168, v[102:103], off offset:1024
	global_load_ushort v163, v[102:103], off
	v_addc_co_u32_e32 v109, vcc, 0, v65, vcc
	v_add_co_u32_e32 v110, vcc, s47, v64
	global_load_ushort v165, v[192:193], off offset:1536
	global_load_ushort v157, v[192:193], off offset:512
	global_load_ushort v162, v[86:87], off offset:2048
	global_load_ushort v156, v[86:87], off offset:1024
	v_addc_co_u32_e32 v111, vcc, 0, v65, vcc
	v_add_co_u32_e32 v112, vcc, s48, v64
	global_load_ushort v159, v[194:195], off offset:2560
	global_load_ushort v81, v[194:195], off offset:1536
	v_addc_co_u32_e32 v113, vcc, 0, v65, vcc
	v_add_co_u32_e32 v114, vcc, s0, v64
	s_mov_b32 s0, 0xb223000
	s_nop 0
	v_addc_co_u32_e32 v115, vcc, 0, v65, vcc
	v_add_co_u32_e32 v86, vcc, s0, v64
	s_mov_b32 s0, 0xb221000
	s_nop 0
	v_addc_co_u32_e32 v87, vcc, 0, v65, vcc
	v_add_co_u32_e32 v102, vcc, s0, v64
	s_mov_b32 s0, 0xb21f000
	s_nop 0
	v_addc_co_u32_e32 v103, vcc, 0, v65, vcc
	v_add_co_u32_e32 v104, vcc, s0, v64
	global_load_ushort v142, v[86:87], off offset:2048
	global_load_ushort v143, v[102:103], off offset:1024
	global_load_ushort v145, v[68:69], off offset:-4096
	v_addc_co_u32_e32 v105, vcc, 0, v65, vcc
	v_add_co_u32_e32 v106, vcc, s97, v64
	s_nop 1
	v_addc_co_u32_e32 v107, vcc, 0, v65, vcc
	global_load_ushort v146, v[106:107], off offset:3072
	global_load_ushort v147, v[114:115], off offset:2048
	global_load_ushort v150, v[112:113], off offset:1024
	global_load_ushort v151, v[76:77], off offset:-4096
	global_load_ushort v152, v[108:109], off offset:3072
	global_load_ushort v153, v[194:195], off offset:2048
	global_load_ushort v144, v[192:193], off offset:1024
	s_nop 0
	global_load_ushort v154, v[154:155], off
	s_nop 0
	global_load_ushort v155, v[190:191], off offset:3072
	s_nop 0
	global_load_ushort v122, v[122:123], off offset:2048
	s_nop 0
	global_load_ushort v120, v[120:121], off offset:1024
	s_nop 0
	global_load_ushort v118, v[118:119], off
	s_nop 0
	global_load_ushort v121, v[116:117], off offset:3072
	v_lshlrev_b32_e32 v116, 16, v187
	v_max_f32_e32 v116, v116, v116
	v_med3_f32 v116, v116, s9, v244
	v_mul_f32_e32 v116, 0xbfb8aa3b, v116
	v_exp_f32_e32 v116, v116
	ds_write_b16_d16_hi v83, v188
	ds_write_b16_d16_hi v83, v133 offset:4608
	v_add_f32_e32 v117, 1.0, v116
	v_rcp_f32_e32 v117, v117
	s_nop 0
	v_fma_f32 v119, v80, v117, v149
	v_mul_f32_e32 v116, v116, v117
	v_mul_f32_e32 v117, v183, v119
	v_max_f32_e32 v117, 0xda24260, v117
	v_rcp_f32_e32 v119, v117
	v_mul_f32_e32 v116, v80, v116
	v_mul_f32_e32 v116, v116, v119
	v_bfe_u32 v119, v116, 16, 1
	v_add3_u32 v119, v116, v119, s10
	v_lshlrev_b32_e32 v116, 16, v182
	v_mul_f32_e32 v116, v117, v116
	v_bfe_u32 v123, v116, 16, 1
	v_add3_u32 v116, v116, v123, s10
	ds_write_b16_d16_hi v83, v116 offset:144
	ds_write_b16_d16_hi v83, v119 offset:4752
	v_lshlrev_b32_e32 v116, 16, v180
	v_max_f32_e32 v116, v116, v116
	v_med3_f32 v116, v116, s9, v244
	v_mul_f32_e32 v116, 0xbfb8aa3b, v116
	v_exp_f32_e32 v116, v116
	s_nop 0
	v_add_f32_e32 v123, 1.0, v116
	v_rcp_f32_e32 v123, v123
	s_nop 0
	v_fma_f32 v180, v80, v123, v149
	v_mul_f32_e32 v117, v117, v180
	v_max_f32_e32 v117, 0xda24260, v117
	v_mul_f32_e32 v116, v116, v123
	v_rcp_f32_e32 v123, v117
	v_mul_f32_e32 v116, v80, v116
	v_mul_f32_e32 v116, v116, v123
	v_bfe_u32 v123, v116, 16, 1
	v_add3_u32 v116, v116, v123, s10
	v_lshlrev_b32_e32 v123, 16, v176
	v_mul_f32_e32 v123, v117, v123
	v_bfe_u32 v176, v123, 16, 1
	v_add3_u32 v123, v123, v176, s10
	ds_write_b16_d16_hi v83, v123 offset:288
	ds_write_b16_d16_hi v83, v116 offset:4896
	v_lshlrev_b32_e32 v123, 16, v175
	v_max_f32_e32 v123, v123, v123
	v_med3_f32 v123, v123, s9, v244
	v_mul_f32_e32 v123, 0xbfb8aa3b, v123
	v_exp_f32_e32 v123, v123
	s_nop 0
	v_add_f32_e32 v175, 1.0, v123
	v_rcp_f32_e32 v175, v175
	s_nop 0
	v_fma_f32 v176, v80, v175, v149
	v_mul_f32_e32 v117, v117, v176
	v_mul_f32_e32 v123, v123, v175
	v_max_f32_e32 v175, 0xda24260, v117
	v_rcp_f32_e32 v117, v175
	v_mul_f32_e32 v123, v80, v123
	v_mul_f32_e32 v117, v123, v117
	v_bfe_u32 v123, v117, 16, 1
	v_add3_u32 v117, v117, v123, s10
	v_lshlrev_b32_e32 v123, 16, v170
	v_mul_f32_e32 v123, v175, v123
	v_bfe_u32 v170, v123, 16, 1
	v_add3_u32 v123, v123, v170, s10
	ds_write_b16_d16_hi v83, v123 offset:432
	ds_write_b16_d16_hi v83, v117 offset:5040
	v_lshlrev_b32_e32 v123, 16, v181
	v_max_f32_e32 v123, v123, v123
	v_med3_f32 v123, v123, s9, v244
	v_mul_f32_e32 v123, 0xbfb8aa3b, v123
	v_exp_f32_e32 v123, v123
	s_nop 0
	v_add_f32_e32 v170, 1.0, v123
	v_rcp_f32_e32 v170, v170
	s_nop 0
	v_fma_f32 v176, v80, v170, v149
	v_mul_f32_e32 v123, v123, v170
	v_mul_f32_e32 v170, v175, v176
	v_max_f32_e32 v170, 0xda24260, v170
	v_rcp_f32_e32 v175, v170
	v_mul_f32_e32 v123, v80, v123
	v_mul_f32_e32 v123, v123, v175
	v_bfe_u32 v175, v123, 16, 1
	v_add3_u32 v123, v123, v175, s10
	v_lshlrev_b32_e32 v175, 16, v178
	v_mul_f32_e32 v175, v170, v175
	v_bfe_u32 v176, v175, 16, 1
	v_add3_u32 v175, v175, v176, s10
	ds_write_b16_d16_hi v83, v175 offset:576
	ds_write_b16_d16_hi v83, v123 offset:5184
	v_lshlrev_b32_e32 v175, 16, v186
	v_max_f32_e32 v175, v175, v175
	v_med3_f32 v175, v175, s9, v244
	v_mul_f32_e32 v175, 0xbfb8aa3b, v175
	v_exp_f32_e32 v175, v175
	s_nop 0
	v_add_f32_e32 v176, 1.0, v175
	v_rcp_f32_e32 v176, v176
	s_nop 0
	v_fma_f32 v178, v80, v176, v149
	v_mul_f32_e32 v170, v170, v178
	v_max_f32_e32 v170, 0xda24260, v170
	v_mul_f32_e32 v175, v175, v176
	v_rcp_f32_e32 v176, v170
	v_mul_f32_e32 v175, v80, v175
	v_mul_f32_e32 v175, v175, v176
	v_bfe_u32 v176, v175, 16, 1
	v_add3_u32 v175, v175, v176, s10
	v_lshlrev_b32_e32 v176, 16, v185
	v_mul_f32_e32 v176, v170, v176
	v_bfe_u32 v178, v176, 16, 1
	v_add3_u32 v176, v176, v178, s10
	ds_write_b16_d16_hi v83, v176 offset:720
	ds_write_b16_d16_hi v83, v175 offset:5328
	v_lshlrev_b32_e32 v176, 16, v184
	v_max_f32_e32 v176, v176, v176
	v_med3_f32 v176, v176, s9, v244
	v_mul_f32_e32 v176, 0xbfb8aa3b, v176
	v_exp_f32_e32 v176, v176
	s_nop 0
	v_add_f32_e32 v178, 1.0, v176
	v_rcp_f32_e32 v178, v178
	s_nop 0
	v_fma_f32 v180, v80, v178, v149
	v_mul_f32_e32 v170, v170, v180
	v_mul_f32_e32 v176, v176, v178
	v_max_f32_e32 v178, 0xda24260, v170
	v_rcp_f32_e32 v170, v178
	v_mul_f32_e32 v176, v80, v176
	v_mul_f32_e32 v170, v176, v170
	v_bfe_u32 v176, v170, 16, 1
	v_add3_u32 v170, v170, v176, s10
	v_lshlrev_b32_e32 v176, 16, v179
	v_mul_f32_e32 v176, v178, v176
	v_bfe_u32 v179, v176, 16, 1
	v_add3_u32 v176, v176, v179, s10
	ds_write_b16_d16_hi v83, v176 offset:864
	ds_write_b16_d16_hi v83, v170 offset:5472
	v_lshlrev_b32_e32 v176, 16, v177
	v_max_f32_e32 v176, v176, v176
	v_med3_f32 v176, v176, s9, v244
	v_mul_f32_e32 v176, 0xbfb8aa3b, v176
	v_exp_f32_e32 v176, v176
	s_nop 0
	v_add_f32_e32 v177, 1.0, v176
	v_rcp_f32_e32 v177, v177
	s_nop 0
	v_fma_f32 v179, v80, v177, v149
	v_mul_f32_e32 v176, v176, v177
	v_mul_f32_e32 v177, v178, v179
	v_max_f32_e32 v177, 0xda24260, v177
	v_rcp_f32_e32 v178, v177
	v_mul_f32_e32 v176, v80, v176
	v_mul_f32_e32 v173, v177, v173
	v_mul_f32_e32 v176, v176, v178
	v_bfe_u32 v178, v176, 16, 1
	v_add3_u32 v176, v176, v178, s10
	v_bfe_u32 v178, v173, 16, 1
	v_add3_u32 v173, v173, v178, s10
	ds_write_b16_d16_hi v83, v173 offset:1008
	ds_write_b16_d16_hi v83, v176 offset:5616
	s_waitcnt vmcnt(31)
	v_lshlrev_b32_e32 v173, 16, v174
	v_max_f32_e32 v173, v173, v173
	v_med3_f32 v173, v173, s9, v244
	v_mul_f32_e32 v173, 0xbfb8aa3b, v173
	v_exp_f32_e32 v173, v173
	s_waitcnt vmcnt(29)
	v_lshlrev_b32_e32 v171, 16, v171
	v_max_f32_e32 v171, v171, v171
	v_med3_f32 v171, v171, s9, v244
	v_add_f32_e32 v174, 1.0, v173
	v_rcp_f32_e32 v174, v174
	v_mul_f32_e32 v171, 0xbfb8aa3b, v171
	v_exp_f32_e32 v178, v171
	v_lshlrev_b32_e32 v172, 16, v172
	v_fma_f32 v171, v80, v174, v149
	v_mul_f32_e32 v171, v177, v171
	v_max_f32_e32 v177, 0xda24260, v171
	v_rcp_f32_e32 v171, v177
	v_mul_f32_e32 v173, v173, v174
	v_mul_f32_e32 v173, v80, v173
	v_mul_f32_e32 v172, v177, v172
	v_mul_f32_e32 v171, v173, v171
	v_bfe_u32 v173, v171, 16, 1
	v_add3_u32 v171, v171, v173, s10
	v_add_f32_e32 v173, 1.0, v178
	v_rcp_f32_e32 v173, v173
	v_bfe_u32 v174, v172, 16, 1
	v_add3_u32 v172, v172, v174, s10
	ds_write_b16_d16_hi v83, v172 offset:1152
	v_fma_f32 v172, v80, v173, v149
	v_mul_f32_e32 v172, v177, v172
	v_max_f32_e32 v174, 0xda24260, v172
	v_rcp_f32_e32 v172, v174
	v_mul_f32_e32 v173, v178, v173
	v_mul_f32_e32 v173, v80, v173
	s_waitcnt vmcnt(28)
	v_lshlrev_b32_e32 v169, 16, v169
	v_mul_f32_e32 v172, v173, v172
	v_bfe_u32 v173, v172, 16, 1
	v_mul_f32_e32 v169, v174, v169
	ds_write_b16_d16_hi v83, v171 offset:5760
	v_add3_u32 v172, v172, v173, s10
	v_bfe_u32 v173, v169, 16, 1
	v_add3_u32 v169, v169, v173, s10
	global_load_ushort v173, v[74:75], off offset:3072
	global_load_ushort v177, v[108:109], off offset:2560
	s_nop 0
	global_load_ushort v78, v[78:79], off offset:3072
	s_nop 0
	global_load_ushort v79, v[76:77], off offset:1024
	global_load_ushort v178, v[84:85], off offset:2048
	s_nop 0
	global_load_ushort v85, v[84:85], off offset:1024
	s_nop 0
	global_load_ushort v76, v[76:77], off
	s_nop 0
	global_load_ushort v77, v[74:75], off offset:2048
	s_waitcnt vmcnt(35)
	v_lshlrev_b32_e32 v74, 16, v166
	v_max_f32_e32 v74, v74, v74
	v_med3_f32 v74, v74, s9, v244
	v_mul_f32_e32 v74, 0xbfb8aa3b, v74
	v_exp_f32_e32 v84, v74
	v_add_co_u32_e32 v74, vcc, s5, v64
	s_waitcnt vmcnt(32)
	v_lshlrev_b32_e32 v158, 16, v158
	v_addc_co_u32_e32 v75, vcc, 0, v65, vcc
	v_add_f32_e32 v166, 1.0, v84
	global_load_ushort v108, v[108:109], off offset:3584
	s_nop 0
	global_load_ushort v109, v[74:75], off
	s_nop 0
	global_load_ushort v110, v[110:111], off offset:512
	s_nop 0
	global_load_ushort v74, v[74:75], off offset:3584
	s_nop 0
	global_load_ushort v75, v[112:113], off offset:1536
	global_load_ushort v111, v[114:115], off offset:2560
	s_nop 0
	global_load_ushort v114, v[114:115], off offset:1536
	s_nop 0
	global_load_ushort v112, v[112:113], off offset:512
	v_rcp_f32_e32 v166, v166
	s_waitcnt vmcnt(37)
	v_lshlrev_b32_e32 v165, 16, v165
	v_max_f32_e32 v165, v165, v165
	v_med3_f32 v165, v165, s9, v244
	v_fma_f32 v113, v80, v166, v149
	v_mul_f32_e32 v113, v174, v113
	v_mul_f32_e32 v84, v84, v166
	v_lshlrev_b32_e32 v166, 16, v167
	v_max_f32_e32 v113, 0xda24260, v113
	v_max_f32_e32 v166, v166, v166
	v_rcp_f32_e32 v115, v113
	v_med3_f32 v166, v166, s9, v244
	v_mul_f32_e32 v166, 0xbfb8aa3b, v166
	v_exp_f32_e32 v166, v166
	v_mul_f32_e32 v84, v80, v84
	v_mul_f32_e32 v84, v84, v115
	v_bfe_u32 v115, v84, 16, 1
	v_add3_u32 v84, v84, v115, s10
	v_lshlrev_b32_e32 v115, 16, v164
	v_add_f32_e32 v164, 1.0, v166
	v_rcp_f32_e32 v164, v164
	v_mul_f32_e32 v115, v113, v115
	v_bfe_u32 v167, v115, 16, 1
	v_add3_u32 v115, v115, v167, s10
	ds_write_b16_d16_hi v83, v115 offset:1440
	v_fma_f32 v115, v80, v164, v149
	v_mul_f32_e32 v113, v113, v115
	v_mul_f32_e32 v164, v166, v164
	v_lshlrev_b32_e32 v166, 16, v168
	v_max_f32_e32 v113, 0xda24260, v113
	v_max_f32_e32 v166, v166, v166
	v_rcp_f32_e32 v115, v113
	v_med3_f32 v166, v166, s9, v244
	v_mul_f32_e32 v166, 0xbfb8aa3b, v166
	v_exp_f32_e32 v166, v166
	v_mul_f32_e32 v164, v80, v164
	v_mul_f32_e32 v115, v164, v115
	v_bfe_u32 v164, v115, 16, 1
	v_add3_u32 v115, v115, v164, s10
	v_add_f32_e32 v164, 1.0, v166
	v_rcp_f32_e32 v164, v164
	v_mul_f32_e32 v158, v113, v158
	v_bfe_u32 v167, v158, 16, 1
	v_add3_u32 v158, v158, v167, s10
	ds_write_b16_d16_hi v83, v158 offset:1584
	v_fma_f32 v158, v80, v164, v149
	v_mul_f32_e32 v113, v113, v158
	v_max_f32_e32 v113, 0xda24260, v113
	v_rcp_f32_e32 v158, v113
	v_mul_f32_e32 v165, 0xbfb8aa3b, v165
	v_mul_f32_e32 v164, v166, v164
	v_exp_f32_e32 v165, v165
	v_mul_f32_e32 v164, v80, v164
	v_mul_f32_e32 v158, v164, v158
	v_bfe_u32 v164, v158, 16, 1
	v_add3_u32 v158, v158, v164, s10
	v_add_f32_e32 v164, 1.0, v165
	v_lshlrev_b32_e32 v163, 16, v163
	v_rcp_f32_e32 v164, v164
	v_mul_f32_e32 v163, v113, v163
	v_bfe_u32 v166, v163, 16, 1
	v_add3_u32 v163, v163, v166, s10
	ds_write_b16_d16_hi v83, v163 offset:1728
	v_fma_f32 v163, v80, v164, v149
	v_mul_f32_e32 v113, v113, v163
	s_waitcnt vmcnt(35)
	v_lshlrev_b32_e32 v162, 16, v162
	v_max_f32_e32 v113, 0xda24260, v113
	v_max_f32_e32 v162, v162, v162
	v_rcp_f32_e32 v163, v113
	v_med3_f32 v162, v162, s9, v244
	v_mul_f32_e32 v162, 0xbfb8aa3b, v162
	v_mul_f32_e32 v164, v165, v164
	v_exp_f32_e32 v162, v162
	v_mul_f32_e32 v164, v80, v164
	v_mul_f32_e32 v163, v164, v163
	v_bfe_u32 v164, v163, 16, 1
	v_add3_u32 v163, v163, v164, s10
	v_add_f32_e32 v164, 1.0, v162
	v_lshlrev_b32_e32 v157, 16, v157
	v_rcp_f32_e32 v164, v164
	v_mul_f32_e32 v157, v113, v157
	v_bfe_u32 v165, v157, 16, 1
	v_add3_u32 v157, v157, v165, s10
	ds_write_b16_d16_hi v83, v157 offset:1872
	v_fma_f32 v157, v80, v164, v149
	v_mul_f32_e32 v113, v113, v157
	s_waitcnt vmcnt(33)
	v_lshlrev_b32_e32 v159, 16, v159
	v_max_f32_e32 v113, 0xda24260, v113
	v_max_f32_e32 v159, v159, v159
	v_rcp_f32_e32 v157, v113
	v_med3_f32 v159, v159, s9, v244
	v_mul_f32_e32 v159, 0xbfb8aa3b, v159
	v_mul_f32_e32 v162, v162, v164
	v_exp_f32_e32 v159, v159
	v_mul_f32_e32 v162, v80, v162
	v_mul_f32_e32 v157, v162, v157
	v_bfe_u32 v162, v157, 16, 1
	v_add3_u32 v157, v157, v162, s10
	v_add_f32_e32 v162, 1.0, v159
	v_lshlrev_b32_e32 v156, 16, v156
	v_rcp_f32_e32 v162, v162
	v_mul_f32_e32 v156, v113, v156
	v_bfe_u32 v164, v156, 16, 1
	v_add3_u32 v156, v156, v164, s10
	ds_write_b16_d16_hi v83, v156 offset:2016
	v_fma_f32 v156, v80, v162, v149
	v_mul_f32_e32 v113, v113, v156
	v_max_f32_e32 v113, 0xda24260, v113
	v_rcp_f32_e32 v156, v113
	v_mul_f32_e32 v159, v159, v162
	v_mul_f32_e32 v159, v80, v159
	s_waitcnt vmcnt(32)
	v_lshlrev_b32_e32 v81, 16, v81
	v_mul_f32_e32 v156, v159, v156
	v_bfe_u32 v159, v156, 16, 1
	v_mul_f32_e32 v81, v113, v81
	v_add3_u32 v159, v156, v159, s10
	v_bfe_u32 v156, v81, 16, 1
	v_add3_u32 v81, v81, v156, s10
	ds_write_b16_d16_hi v83, v169 offset:1296
	ds_write_b16_d16_hi v83, v172 offset:5904
	ds_write_b16_d16_hi v83, v84 offset:6048
	ds_write_b16_d16_hi v83, v115 offset:6192
	ds_write_b16_d16_hi v83, v158 offset:6336
	ds_write_b16_d16_hi v83, v163 offset:6480
	ds_write_b16_d16_hi v83, v157 offset:6624
	ds_write_b16_d16_hi v83, v81 offset:2160
	ds_write_b16_d16_hi v83, v159 offset:6768
	s_waitcnt vmcnt(15)
	v_lshlrev_b32_e32 v81, 16, v173
	v_max_f32_e32 v81, v81, v81
	v_med3_f32 v81, v81, s9, v244
	v_mul_f32_e32 v81, 0xbfb8aa3b, v81
	v_exp_f32_e32 v81, v81
	s_waitcnt vmcnt(7)
	v_lshlrev_b32_e32 v108, 16, v108
	v_max_f32_e32 v108, v108, v108
	v_med3_f32 v108, v108, s9, v244
	v_add_f32_e32 v156, 1.0, v81
	v_rcp_f32_e32 v156, v156
	v_mul_f32_e32 v108, 0xbfb8aa3b, v108
	v_exp_f32_e32 v108, v108
	v_lshlrev_b32_e32 v77, 16, v77
	v_fma_f32 v162, v80, v156, v149
	v_mul_f32_e32 v113, v113, v162
	v_max_f32_e32 v113, 0xda24260, v113
	v_rcp_f32_e32 v162, v113
	v_mul_f32_e32 v81, v81, v156
	v_mul_f32_e32 v81, v80, v81
	v_mul_f32_e32 v77, v113, v77
	v_mul_f32_e32 v81, v81, v162
	v_bfe_u32 v156, v81, 16, 1
	v_add3_u32 v156, v81, v156, s10
	v_add_f32_e32 v81, 1.0, v108
	v_rcp_f32_e32 v81, v81
	v_bfe_u32 v162, v77, 16, 1
	v_add3_u32 v77, v77, v162, s10
	ds_write_b16_d16_hi v83, v77 offset:2304
	v_fma_f32 v77, v80, v81, v149
	ds_write_b16_d16_hi v83, v156 offset:6912
	v_mul_f32_e32 v77, v113, v77
	global_load_ushort v162, v[66:67], off offset:3072
	global_load_ushort v164, v[72:73], off offset:3072
	global_load_ushort v165, v[68:69], off offset:1024
	global_load_ushort v166, v[70:71], off offset:2048
	global_load_ushort v167, v[86:87], off offset:1536
	global_load_ushort v168, v[70:71], off offset:1024
	global_load_ushort v169, v[68:69], off
	global_load_ushort v173, v[66:67], off offset:2048
	s_waitcnt vmcnt(14)
	v_lshlrev_b32_e32 v66, 16, v109
	v_max_f32_e32 v77, 0xda24260, v77
	v_max_f32_e32 v66, v66, v66
	v_rcp_f32_e32 v113, v77
	v_med3_f32 v66, v66, s9, v244
	v_mul_f32_e32 v66, 0xbfb8aa3b, v66
	v_mul_f32_e32 v81, v108, v81
	v_exp_f32_e32 v66, v66
	v_mul_f32_e32 v81, v80, v81
	v_mul_f32_e32 v81, v81, v113
	v_bfe_u32 v108, v81, 16, 1
	v_add_co_u32_e32 v64, vcc, s4, v64
	v_add3_u32 v108, v81, v108, s10
	v_lshlrev_b32_e32 v81, 16, v177
	v_addc_co_u32_e32 v65, vcc, 0, v65, vcc
	v_add_f32_e32 v67, 1.0, v66
	global_load_ushort v174, v[106:107], off offset:3584
	global_load_ushort v177, v[64:65], off
	global_load_ushort v179, v[64:65], off offset:3584
	s_nop 0
	global_load_ushort v106, v[106:107], off offset:2560
	s_nop 0
	global_load_ushort v104, v[104:105], off offset:512
	s_nop 0
	global_load_ushort v180, v[102:103], off offset:1536
	s_nop 0
	global_load_ushort v102, v[102:103], off offset:512
	s_nop 0
	global_load_ushort v86, v[86:87], off offset:2560
	v_rcp_f32_e32 v67, v67
	v_mul_f32_e32 v81, v77, v81
	v_bfe_u32 v113, v81, 16, 1
	v_add3_u32 v81, v81, v113, s10
	v_fma_f32 v64, v80, v67, v149
	v_mul_f32_e32 v64, v77, v64
	v_mul_f32_e32 v66, v66, v67
	s_waitcnt vmcnt(21)
	v_lshlrev_b32_e32 v67, 16, v110
	v_max_f32_e32 v64, 0xda24260, v64
	v_max_f32_e32 v67, v67, v67
	v_rcp_f32_e32 v65, v64
	v_med3_f32 v67, v67, s9, v244
	v_mul_f32_e32 v67, 0xbfb8aa3b, v67
	v_exp_f32_e32 v67, v67
	v_mul_f32_e32 v66, v80, v66
	v_mul_f32_e32 v65, v66, v65
	v_bfe_u32 v66, v65, 16, 1
	v_add3_u32 v181, v65, v66, s10
	v_add_f32_e32 v66, 1.0, v67
	v_lshlrev_b32_e32 v65, 16, v78
	v_rcp_f32_e32 v66, v66
	v_mul_f32_e32 v65, v64, v65
	v_bfe_u32 v68, v65, 16, 1
	v_add3_u32 v65, v65, v68, s10
	ds_write_b16_d16_hi v83, v65 offset:2592
	v_fma_f32 v65, v80, v66, v149
	v_mul_f32_e32 v66, v67, v66
	v_lshlrev_b32_e32 v67, 16, v79
	v_mul_f32_e32 v64, v64, v65
	v_max_f32_e32 v67, v67, v67
	v_max_f32_e32 v64, 0xda24260, v64
	v_med3_f32 v67, v67, s9, v244
	v_rcp_f32_e32 v65, v64
	v_mul_f32_e32 v67, 0xbfb8aa3b, v67
	v_exp_f32_e32 v67, v67
	v_mul_f32_e32 v66, v80, v66
	v_mul_f32_e32 v65, v66, v65
	v_bfe_u32 v66, v65, 16, 1
	v_add_f32_e32 v68, 1.0, v67
	v_add3_u32 v65, v65, v66, s10
	s_waitcnt vmcnt(20)
	v_lshlrev_b32_e32 v66, 16, v74
	v_rcp_f32_e32 v68, v68
	v_mul_f32_e32 v66, v64, v66
	v_bfe_u32 v69, v66, 16, 1
	v_add3_u32 v66, v66, v69, s10
	ds_write_b16_d16_hi v83, v66 offset:2736
	v_fma_f32 v66, v80, v68, v149
	v_mul_f32_e32 v64, v64, v66
	v_mul_f32_e32 v67, v67, v68
	s_waitcnt vmcnt(19)
	v_lshlrev_b32_e32 v68, 16, v75
	v_max_f32_e32 v64, 0xda24260, v64
	v_max_f32_e32 v68, v68, v68
	v_rcp_f32_e32 v66, v64
	v_med3_f32 v68, v68, s9, v244
	v_mul_f32_e32 v68, 0xbfb8aa3b, v68
	v_exp_f32_e32 v68, v68
	v_mul_f32_e32 v67, v80, v67
	v_mul_f32_e32 v66, v67, v66
	v_bfe_u32 v67, v66, 16, 1
	v_add3_u32 v182, v66, v67, s10
	v_add_f32_e32 v67, 1.0, v68
	v_lshlrev_b32_e32 v66, 16, v76
	v_rcp_f32_e32 v67, v67
	v_mul_f32_e32 v66, v64, v66
	v_bfe_u32 v69, v66, 16, 1
	v_add3_u32 v66, v66, v69, s10
	ds_write_b16_d16_hi v83, v66 offset:2880
	v_fma_f32 v66, v80, v67, v149
	v_mul_f32_e32 v67, v68, v67
	v_lshlrev_b32_e32 v68, 16, v178
	v_mul_f32_e32 v64, v64, v66
	v_max_f32_e32 v68, v68, v68
	v_max_f32_e32 v64, 0xda24260, v64
	v_med3_f32 v68, v68, s9, v244
	v_rcp_f32_e32 v66, v64
	v_mul_f32_e32 v68, 0xbfb8aa3b, v68
	v_exp_f32_e32 v68, v68
	v_mul_f32_e32 v67, v80, v67
	v_mul_f32_e32 v66, v67, v66
	v_bfe_u32 v67, v66, 16, 1
	v_add_f32_e32 v69, 1.0, v68
	v_add3_u32 v66, v66, v67, s10
	s_waitcnt vmcnt(16)
	v_lshlrev_b32_e32 v67, 16, v112
	v_rcp_f32_e32 v69, v69
	v_mul_f32_e32 v67, v64, v67
	v_bfe_u32 v70, v67, 16, 1
	v_add3_u32 v67, v67, v70, s10
	ds_write_b16_d16_hi v83, v67 offset:3024
	v_fma_f32 v67, v80, v69, v149
	v_mul_f32_e32 v64, v64, v67
	v_mul_f32_e32 v68, v68, v69
	v_lshlrev_b32_e32 v69, 16, v111
	v_max_f32_e32 v64, 0xda24260, v64
	v_max_f32_e32 v69, v69, v69
	v_rcp_f32_e32 v67, v64
	v_med3_f32 v69, v69, s9, v244
	v_mul_f32_e32 v69, 0xbfb8aa3b, v69
	v_exp_f32_e32 v69, v69
	v_mul_f32_e32 v68, v80, v68
	v_mul_f32_e32 v67, v68, v67
	v_bfe_u32 v68, v67, 16, 1
	v_add3_u32 v178, v67, v68, s10
	v_add_f32_e32 v68, 1.0, v69
	v_lshlrev_b32_e32 v67, 16, v85
	v_rcp_f32_e32 v68, v68
	v_mul_f32_e32 v67, v64, v67
	v_bfe_u32 v70, v67, 16, 1
	v_add3_u32 v67, v67, v70, s10
	ds_write_b16_d16_hi v83, v67 offset:3168
	v_fma_f32 v67, v80, v68, v149
	v_mul_f32_e32 v64, v64, v67
	v_max_f32_e32 v76, 0xda24260, v64
	v_rcp_f32_e32 v64, v76
	v_mul_f32_e32 v67, v69, v68
	v_mul_f32_e32 v67, v80, v67
	ds_write_b16_d16_hi v83, v81 offset:2448
	v_mul_f32_e32 v64, v67, v64
	v_bfe_u32 v67, v64, 16, 1
	v_add3_u32 v64, v64, v67, s10
	v_lshlrev_b32_e32 v67, 16, v114
	v_mul_f32_e32 v67, v76, v67
	v_bfe_u32 v68, v67, 16, 1
	v_add3_u32 v67, v67, v68, s10
	ds_write_b16_d16_hi v83, v108 offset:7056
	ds_write_b16_d16_hi v83, v181 offset:7200
	ds_write_b16_d16_hi v83, v65 offset:7344
	ds_write_b16_d16_hi v83, v182 offset:7488
	ds_write_b16_d16_hi v83, v66 offset:7632
	ds_write_b16_d16_hi v83, v178 offset:7776
	ds_write_b16_d16_hi v83, v67 offset:3312
	ds_write_b16_d16_hi v83, v64 offset:7920
	s_waitcnt vmcnt(15)
	v_lshlrev_b32_e32 v72, 16, v162
	v_max_f32_e32 v72, v72, v72
	v_med3_f32 v72, v72, s9, v244
	v_mul_f32_e32 v72, 0xbfb8aa3b, v72
	v_and_b32_e32 v103, 0xffff0000, v108
	v_exp_f32_e32 v108, v72
	v_lshl_or_b32 v78, v120, 16, v127
	s_waitcnt vmcnt(4)
	v_lshlrev_b32_e32 v106, 16, v106
	s_waitcnt vmcnt(3)
	v_lshlrev_b32_e32 v104, 16, v104
	v_add_f32_e32 v77, 1.0, v108
	v_rcp_f32_e32 v110, v77
	v_max_f32_e32 v104, v104, v104
	v_med3_f32 v104, v104, s9, v244
	v_mul_f32_e32 v104, 0xbfb8aa3b, v104
	v_fma_f32 v112, v80, v110, v149
	v_mul_f32_e32 v76, v76, v112
	v_max_f32_e32 v112, 0xda24260, v76
	v_lshl_or_b32 v76, v121, 16, v88
	v_mul_f32_e32 v88, v108, v110
	v_lshlrev_b32_e32 v110, 16, v174
	v_max_f32_e32 v110, v110, v110
	v_rcp_f32_e32 v114, v112
	v_med3_f32 v110, v110, s9, v244
	v_mul_f32_e32 v110, 0xbfb8aa3b, v110
	v_exp_f32_e32 v110, v110
	v_mul_f32_e32 v88, v80, v88
	v_mul_f32_e32 v88, v88, v114
	v_bfe_u32 v108, v88, 16, 1
	v_add3_u32 v120, v88, v108, s10
	v_add_f32_e32 v108, 1.0, v110
	v_lshlrev_b32_e32 v88, 16, v173
	v_rcp_f32_e32 v108, v108
	v_mul_f32_e32 v88, v112, v88
	v_bfe_u32 v114, v88, 16, 1
	v_add3_u32 v88, v88, v114, s10
	ds_write_b16_d16_hi v83, v88 offset:3456
	v_fma_f32 v88, v80, v108, v149
	v_mul_f32_e32 v88, v112, v88
	v_max_f32_e32 v88, 0xda24260, v88
	v_rcp_f32_e32 v112, v88
	v_mul_f32_e32 v108, v110, v108
	v_mul_f32_e32 v108, v80, v108
	v_mul_f32_e32 v106, v88, v106
	v_mul_f32_e32 v108, v108, v112
	v_bfe_u32 v110, v108, 16, 1
	v_add3_u32 v108, v108, v110, s10
	v_lshlrev_b32_e32 v110, 16, v177
	v_max_f32_e32 v110, v110, v110
	v_med3_f32 v110, v110, s9, v244
	v_mul_f32_e32 v110, 0xbfb8aa3b, v110
	v_exp_f32_e32 v110, v110
	v_bfe_u32 v114, v106, 16, 1
	v_add3_u32 v106, v106, v114, s10
	ds_write_b16_d16_hi v83, v106 offset:3600
	v_add_f32_e32 v112, 1.0, v110
	v_rcp_f32_e32 v112, v112
	v_and_b32_e32 v121, 0xffff0000, v108
	ds_write_b16_d16_hi v83, v108 offset:8208
	v_exp_f32_e32 v104, v104
	v_fma_f32 v106, v80, v112, v149
	v_mul_f32_e32 v88, v88, v106
	v_max_f32_e32 v88, 0xda24260, v88
	v_rcp_f32_e32 v106, v88
	v_mul_f32_e32 v108, v110, v112
	v_mul_f32_e32 v108, v80, v108
	v_lshl_or_b32 v79, v122, 16, v128
	v_mul_f32_e32 v106, v108, v106
	v_bfe_u32 v108, v106, 16, 1
	v_add3_u32 v122, v106, v108, s10
	v_add_f32_e32 v108, 1.0, v104
	v_lshlrev_b32_e32 v106, 16, v164
	v_rcp_f32_e32 v108, v108
	v_mul_f32_e32 v106, v88, v106
	v_bfe_u32 v110, v106, 16, 1
	v_add3_u32 v106, v106, v110, s10
	ds_write_b16_d16_hi v83, v106 offset:3744
	v_fma_f32 v106, v80, v108, v149
	v_mul_f32_e32 v88, v88, v106
	v_max_f32_e32 v88, 0xda24260, v88
	v_rcp_f32_e32 v106, v88
	v_mul_f32_e32 v104, v104, v108
	v_mul_f32_e32 v104, v80, v104
	v_lshlrev_b32_e32 v108, 16, v179
	v_mul_f32_e32 v104, v104, v106
	v_bfe_u32 v106, v104, 16, 1
	v_add3_u32 v104, v104, v106, s10
	v_lshlrev_b32_e32 v106, 16, v165
	v_max_f32_e32 v106, v106, v106
	v_med3_f32 v106, v106, s9, v244
	v_mul_f32_e32 v106, 0xbfb8aa3b, v106
	v_exp_f32_e32 v106, v106
	v_mul_f32_e32 v108, v88, v108
	v_bfe_u32 v112, v108, 16, 1
	v_add3_u32 v108, v108, v112, s10
	v_add_f32_e32 v110, 1.0, v106
	v_rcp_f32_e32 v110, v110
	ds_write_b16_d16_hi v83, v108 offset:3888
	v_lshl_or_b32 v74, v144, 16, v131
	v_and_b32_e32 v131, 0xffff0000, v104
	v_fma_f32 v108, v80, v110, v149
	v_mul_f32_e32 v88, v88, v108
	v_max_f32_e32 v88, 0xda24260, v88
	v_rcp_f32_e32 v108, v88
	ds_write_b16_d16_hi v83, v104 offset:8496
	v_mul_f32_e32 v104, v106, v110
	v_mul_f32_e32 v104, v80, v104
	v_mul_f32_e32 v104, v104, v108
	s_waitcnt vmcnt(2)
	v_lshlrev_b32_e32 v108, 16, v180
	v_max_f32_e32 v108, v108, v108
	v_med3_f32 v108, v108, s9, v244
	v_mul_f32_e32 v108, 0xbfb8aa3b, v108
	v_exp_f32_e32 v108, v108
	v_bfe_u32 v106, v104, 16, 1
	v_lshl_or_b32 v75, v153, 16, v132
	v_add3_u32 v132, v104, v106, s10
	v_add_f32_e32 v106, 1.0, v108
	v_lshlrev_b32_e32 v104, 16, v169
	v_rcp_f32_e32 v106, v106
	v_mul_f32_e32 v104, v88, v104
	v_bfe_u32 v110, v104, 16, 1
	v_add3_u32 v104, v104, v110, s10
	ds_write_b16_d16_hi v83, v104 offset:4032
	v_fma_f32 v104, v80, v106, v149
	v_mul_f32_e32 v88, v88, v104
	v_max_f32_e32 v88, 0xda24260, v88
	v_rcp_f32_e32 v104, v88
	v_mul_f32_e32 v106, v108, v106
	v_mul_f32_e32 v106, v80, v106
	s_waitcnt vmcnt(1)
	v_lshlrev_b32_e32 v102, 16, v102
	v_mul_f32_e32 v104, v106, v104
	v_bfe_u32 v106, v104, 16, 1
	v_add3_u32 v104, v104, v106, s10
	v_lshlrev_b32_e32 v106, 16, v166
	v_max_f32_e32 v106, v106, v106
	v_med3_f32 v106, v106, s9, v244
	v_mul_f32_e32 v106, 0xbfb8aa3b, v106
	v_exp_f32_e32 v106, v106
	v_mul_f32_e32 v102, v88, v102
	v_bfe_u32 v110, v102, 16, 1
	v_add3_u32 v102, v102, v110, s10
	v_add_f32_e32 v108, 1.0, v106
	v_rcp_f32_e32 v108, v108
	ds_write_b16_d16_hi v83, v102 offset:4176
	s_waitcnt vmcnt(0)
	v_lshlrev_b32_e32 v86, 16, v86
	v_max_f32_e32 v86, v86, v86
	v_fma_f32 v102, v80, v108, v149
	v_mul_f32_e32 v88, v88, v102
	v_max_f32_e32 v88, 0xda24260, v88
	v_rcp_f32_e32 v102, v88
	v_med3_f32 v86, v86, s9, v244
	v_mul_f32_e32 v86, 0xbfb8aa3b, v86
	v_lshl_or_b32 v69, v151, 16, v135
	v_and_b32_e32 v135, 0xffff0000, v104
	ds_write_b16_d16_hi v83, v104 offset:8784
	v_mul_f32_e32 v104, v106, v108
	v_exp_f32_e32 v86, v86
	v_mul_f32_e32 v104, v80, v104
	v_mul_f32_e32 v102, v104, v102
	v_bfe_u32 v104, v102, 16, 1
	v_lshl_or_b32 v70, v150, 16, v136
	v_add3_u32 v136, v102, v104, s10
	v_add_f32_e32 v104, 1.0, v86
	v_rcp_f32_e32 v104, v104
	v_lshlrev_b32_e32 v102, 16, v168
	v_mul_f32_e32 v102, v88, v102
	v_bfe_u32 v106, v102, 16, 1
	v_fmac_f32_e32 v149, v80, v104
	v_mul_f32_e32 v88, v88, v149
	v_add3_u32 v102, v102, v106, s10
	v_max_f32_e32 v88, 0xda24260, v88
	ds_write_b16_d16_hi v83, v102 offset:4320
	v_rcp_f32_e32 v102, v88
	v_mul_f32_e32 v86, v86, v104
	v_mul_f32_e32 v80, v80, v86
	v_and_b32_e32 v81, 0xffff0000, v64
	v_mul_f32_e32 v80, v80, v102
	v_bfe_u32 v86, v80, 16, 1
	v_add3_u32 v80, v80, v86, s10
	v_lshlrev_b32_e32 v86, 16, v167
	v_mul_f32_e32 v86, v88, v86
	v_bfe_u32 v102, v86, 16, 1
	v_add3_u32 v86, v86, v102, s10
	v_and_b32_e32 v85, 0xffff0000, v66
	v_and_b32_e32 v87, 0xffff0000, v65
	v_and_b32_e32 v105, 0xffff0000, v159
	v_and_b32_e32 v107, 0xffff0000, v163
	v_and_b32_e32 v109, 0xffff0000, v115
	v_and_b32_e32 v111, 0xffff0000, v172
	v_and_b32_e32 v113, 0xffff0000, v176
	v_and_b32_e32 v115, 0xffff0000, v175
	v_and_b32_e32 v117, 0xffff0000, v117
	v_and_b32_e32 v119, 0xffff0000, v119
	v_lshl_or_b32 v67, v142, 16, v141
	v_lshl_or_b32 v66, v143, 16, v140
	v_lshl_or_b32 v65, v145, 16, v139
	v_lshl_or_b32 v64, v146, 16, v138
	v_lshl_or_b32 v71, v147, 16, v137
	v_lshl_or_b32 v68, v152, 16, v134
	v_lshl_or_b32 v73, v154, 16, v130
	v_lshl_or_b32 v72, v155, 16, v129
	v_lshl_or_b32 v77, v118, 16, v126
	ds_write_b16_d16_hi v83, v120 offset:8064
	ds_write_b16_d16_hi v83, v122 offset:8352
	ds_write_b16_d16_hi v83, v132 offset:8640
	ds_write_b16_d16_hi v83, v136 offset:8928
	v_and_b32_e32 v137, 0xffff0000, v80
	ds_write_b16_d16_hi v83, v86 offset:4464
	ds_write_b16_d16_hi v83, v80 offset:9072
	v_and_b32_e32 v112, 0xffff0000, v170
	v_and_b32_e32 v104, 0xffff0000, v157
	v_and_b32_e32 v80, 0xffff0000, v178
	v_pk_mul_f32 v[112:113], v[88:89], v[112:113] op_sel_hi:[0,1]
	v_and_b32_e32 v108, 0xffff0000, v84
	v_pk_mul_f32 v[104:105], v[88:89], v[104:105] op_sel_hi:[0,1]
	v_and_b32_e32 v84, 0xffff0000, v182
	v_pk_mul_f32 v[80:81], v[88:89], v[80:81] op_sel_hi:[0,1]
	v_and_b32_e32 v120, 0xffff0000, v120
	v_cvt_pk_bf16_f32 v129, v112, v113
	v_cvt_pk_bf16_f32 v113, v104, v105
	v_pk_mul_f32 v[84:85], v[88:89], v[84:85] op_sel_hi:[0,1]
	v_cvt_pk_bf16_f32 v105, v80, v81
	v_pk_mul_f32 v[80:81], v[88:89], v[120:121] op_sel_hi:[0,1]
	v_and_b32_e32 v130, 0xffff0000, v122
	v_and_b32_e32 v102, 0xffff0000, v156
	v_and_b32_e32 v86, 0xffff0000, v181
	v_cvt_pk_bf16_f32 v104, v84, v85
	v_cvt_pk_bf16_f32 v84, v80, v81
	v_pk_mul_f32 v[80:81], v[88:89], v[130:131] op_sel_hi:[0,1]
	v_and_b32_e32 v134, 0xffff0000, v132
	v_and_b32_e32 v118, 0xffff0000, v133
	v_and_b32_e32 v116, 0xffff0000, v116
	v_and_b32_e32 v114, 0xffff0000, v123
	v_and_b32_e32 v110, 0xffff0000, v171
	v_and_b32_e32 v106, 0xffff0000, v158
	v_pk_mul_f32 v[102:103], v[88:89], v[102:103] op_sel_hi:[0,1]
	v_pk_mul_f32 v[86:87], v[88:89], v[86:87] op_sel_hi:[0,1]
	v_cvt_pk_bf16_f32 v85, v80, v81
	v_pk_mul_f32 v[80:81], v[88:89], v[134:135] op_sel_hi:[0,1]
	v_and_b32_e32 v136, 0xffff0000, v136
	s_movk_i32 s0, 0x50
	v_pk_mul_f32 v[118:119], v[88:89], v[118:119] op_sel_hi:[0,1]
	v_pk_mul_f32 v[116:117], v[88:89], v[116:117] op_sel_hi:[0,1]
	v_pk_mul_f32 v[114:115], v[88:89], v[114:115] op_sel_hi:[0,1]
	v_pk_mul_f32 v[110:111], v[88:89], v[110:111] op_sel_hi:[0,1]
	v_pk_mul_f32 v[108:109], v[88:89], v[108:109] op_sel_hi:[0,1]
	v_pk_mul_f32 v[106:107], v[88:89], v[106:107] op_sel_hi:[0,1]
	v_cvt_pk_bf16_f32 v102, v102, v103
	v_cvt_pk_bf16_f32 v103, v86, v87
	v_cvt_pk_bf16_f32 v86, v80, v81
	v_pk_mul_f32 v[80:81], v[88:89], v[136:137] op_sel_hi:[0,1]
	v_mad_u64_u32 v[138:139], s[2:3], v82, s0, v[92:93]
	v_cvt_pk_bf16_f32 v126, v118, v119
	v_cvt_pk_bf16_f32 v127, v116, v117
	v_cvt_pk_bf16_f32 v128, v114, v115
	v_cvt_pk_bf16_f32 v110, v110, v111
	v_cvt_pk_bf16_f32 v111, v108, v109
	v_cvt_pk_bf16_f32 v112, v106, v107
	v_cvt_pk_bf16_f32 v87, v80, v81
	v_lshl_add_u32 v80, v82, 2, v92
	ds_write_b128 v138, v[126:129] offset:9216
	ds_write_b128 v138, v[110:113] offset:9232
	ds_write_b128 v138, v[102:105] offset:9248
	ds_write_b128 v138, v[84:87] offset:9264
	ds_write_b32 v80, v88 offset:19456
	ds_write_b128 v138, v[76:79] offset:14336
	ds_write_b128 v138, v[72:75] offset:14352
	ds_write_b128 v138, v[68:71] offset:14368
	ds_write_b128 v138, v[64:67] offset:14384
	s_waitcnt lgkmcnt(0)
	v_mul_u32_u24_e32 v248, 0x1200, v94
	v_add_u32_e32 v248, 0xb200e00, v248
	v_mov_b32_e32 v249, 0
	v_lshl_add_u64 v[250:251], v[242:243], 0, v[248:249]
	global_load_dword v196, v[250:251], off
	v_lshrrev_b32_e32 v248, 1, v94
	v_and_b32_e32 v250, 1, v94
	v_mul_u32_u24_e32 v248, 0x1200, v248
	v_lshl_add_u32 v248, v250, 9, v248
	v_add_u32_e32 v248, 0xb200800, v248
	v_lshl_add_u64 v[250:251], v[242:243], 0, v[248:249]
	global_load_dword v196, v[250:251], off
	v_or_b32_e32 v88, v95, v124
	v_lshlrev_b64 v[64:65], 11, v[88:89]
	v_lshl_add_u64 v[64:65], s[16:17], 0, v[64:65]
	v_lshlrev_b32_e32 v80, 2, v125
	s_movk_i32 s48, 0x90
	v_lshl_add_u64 v[64:65], v[64:65], 0, v[90:91]
	v_ashrrev_i32_e32 v81, 31, v80
	v_mad_u32_u24 v88, v124, s48, v92
	v_lshl_add_u64 v[104:105], v[80:81], 1, v[64:65]
	v_lshl_add_u32 v81, v125, 4, v88
	ds_read_b128 v[64:67], v81 offset:4608
	ds_read_b128 v[68:71], v81
	ds_read_b128 v[82:85], v81 offset:32
	ds_read_b128 v[106:109], v81 offset:4640
	s_waitcnt lgkmcnt(2)
	v_mfma_f32_32x32x16_bf16 v[64:79], v[64:67], v[68:71], 0
	v_cmp_le_i32_e32 vcc, v80, v124
	v_cvt_pk_bf16_f32 v32, v32, v33
	v_cvt_pk_bf16_f32 v33, v34, v35
	v_cvt_pk_bf16_f32 v34, v36, v37
	v_cvt_pk_bf16_f32 v35, v38, v39
	v_cvt_pk_bf16_f32 v36, v48, v49
	v_cvt_pk_bf16_f32 v37, v50, v51
	s_waitcnt lgkmcnt(0)
	v_mfma_f32_32x32x16_bf16 v[64:79], v[106:109], v[82:85], v[64:79]
	ds_read_b128 v[82:85], v81 offset:4672
	ds_read_b128 v[106:109], v81 offset:64
	v_cvt_pk_bf16_f32 v38, v52, v53
	v_cvt_pk_bf16_f32 v39, v54, v55
	s_mov_b32 s6, 0x16f00000
	s_mov_b64 s[4:5], 0x16f00600
	v_lshl_add_u64 v[102:103], v[104:105], 0, s[4:5]
	s_waitcnt lgkmcnt(0)
	v_mfma_f32_32x32x16_bf16 v[64:79], v[82:85], v[106:109], v[64:79]
	ds_read_b128 v[82:85], v81 offset:4704
	ds_read_b128 v[106:109], v81 offset:96
	v_or_b32_e32 v81, 2, v80
	s_waitcnt lgkmcnt(0)
	v_mfma_f32_32x32x16_bf16 v[64:79], v[82:85], v[106:109], v[64:79]
	s_nop 11
	v_cndmask_b32_e32 v64, 0, v64, vcc
	v_cmp_lt_i32_e32 vcc, v80, v124
	s_nop 1
	v_cndmask_b32_e32 v65, 0, v65, vcc
	v_cmp_le_i32_e32 vcc, v81, v124
	v_or_b32_e32 v81, 3, v80
	v_cvt_pk_bf16_f32 v84, v64, v65
	v_cndmask_b32_e32 v66, 0, v66, vcc
	v_cmp_le_i32_e32 vcc, v81, v124
	v_add_u32_e32 v81, 8, v80
	v_lshlrev_b32_e32 v64, 3, v125
	v_cndmask_b32_e32 v67, 0, v67, vcc
	v_cmp_le_i32_e32 vcc, v81, v124
	v_add_u32_e32 v81, 9, v80
	v_mul_u32_u24_e32 v65, 0x50, v124
	v_cndmask_b32_e32 v68, 0, v68, vcc
	v_cmp_le_i32_e32 vcc, v81, v124
	v_add_u32_e32 v81, 10, v80
	v_add3_u32 v114, v92, v64, v65
	v_cndmask_b32_e32 v69, 0, v69, vcc
	v_cmp_le_i32_e32 vcc, v81, v124
	v_add_u32_e32 v81, 11, v80
	v_cvt_pk_bf16_f32 v86, v68, v69
	v_cndmask_b32_e32 v70, 0, v70, vcc
	v_cmp_le_i32_e32 vcc, v81, v124
	v_add_u32_e32 v81, 16, v80
	v_add_u32_e32 v68, 0x3800, v114
	v_cndmask_b32_e32 v71, 0, v71, vcc
	v_cmp_le_i32_e32 vcc, v81, v124
	v_add_u32_e32 v81, 17, v80
	v_cvt_pk_bf16_f32 v85, v66, v67
	v_cndmask_b32_e32 v72, 0, v72, vcc
	v_cmp_le_i32_e32 vcc, v81, v124
	v_add_u32_e32 v81, 18, v80
	v_add_u32_e32 v88, v88, v64
	v_cndmask_b32_e32 v73, 0, v73, vcc
	v_cmp_le_i32_e32 vcc, v81, v124
	v_add_u32_e32 v81, 19, v80
	ds_read2_b64 v[64:67], v68 offset1:2
	ds_read2_b64 v[106:109], v68 offset0:4 offset1:6
	v_cndmask_b32_e32 v74, 0, v74, vcc
	v_cmp_le_i32_e32 vcc, v81, v124
	v_add_u32_e32 v81, 24, v80
	v_cvt_pk_bf16_f32 v87, v70, v71
	v_cndmask_b32_e32 v75, 0, v75, vcc
	v_cmp_le_i32_e32 vcc, v81, v124
	v_add_u32_e32 v81, 25, v80
	s_nop 0
	v_cndmask_b32_e32 v76, 0, v76, vcc
	v_cmp_le_i32_e32 vcc, v81, v124
	v_add_u32_e32 v81, 26, v80
	v_add_u32_e32 v80, 27, v80
	v_cndmask_b32_e32 v77, 0, v77, vcc
	v_cmp_le_i32_e32 vcc, v81, v124
	v_cvt_pk_bf16_f32 v81, v74, v75
	v_cvt_pk_bf16_f32 v82, v76, v77
	v_cndmask_b32_e32 v78, 0, v78, vcc
	v_cmp_le_i32_e32 vcc, v80, v124
	v_cvt_pk_bf16_f32 v80, v72, v73
	s_nop 0
	v_cndmask_b32_e32 v79, 0, v79, vcc
	v_cvt_pk_bf16_f32 v83, v78, v79
	s_waitcnt lgkmcnt(1)
	v_mfma_f32_32x32x16_bf16 v[64:79], v[64:67], v[84:87], 0
	s_waitcnt lgkmcnt(0)
	v_mfma_f32_32x32x16_bf16 v[64:79], v[106:109], v[80:83], v[64:79]
	ds_read2_b64 v[106:109], v88 offset1:2
	ds_read2_b64 v[110:113], v88 offset0:4 offset1:6
	s_waitcnt lgkmcnt(1)
	v_mfma_f32_32x32x16_bf16 v[64:79], v[32:35], v[106:109], v[64:79]
	v_cvt_pk_bf16_f32 v32, v40, v41
	v_cvt_pk_bf16_f32 v33, v42, v43
	v_cvt_pk_bf16_f32 v34, v44, v45
	v_cvt_pk_bf16_f32 v35, v46, v47
	s_waitcnt lgkmcnt(0)
	s_nop 0
	v_mfma_f32_32x32x16_bf16 v[64:79], v[32:35], v[110:113], v[64:79]
	ds_read2_b64 v[32:35], v88 offset0:8 offset1:10
	s_waitcnt lgkmcnt(0)
	v_mfma_f32_32x32x16_bf16 v[64:79], v[36:39], v[32:35], v[64:79]
	ds_read2_b64 v[32:35], v88 offset0:12 offset1:14
	v_cvt_pk_bf16_f32 v36, v56, v57
	v_cvt_pk_bf16_f32 v37, v58, v59
	v_cvt_pk_bf16_f32 v38, v60, v61
	v_cvt_pk_bf16_f32 v39, v62, v63
	s_waitcnt lgkmcnt(0)
	s_nop 0
	v_mfma_f32_32x32x16_bf16 v[64:79], v[36:39], v[32:35], v[64:79]
	v_add_co_u32_e32 v34, vcc, s6, v104
	s_nop 1
	v_addc_co_u32_e32 v35, vcc, 0, v105, vcc
	s_nop 7
	v_cvt_pk_bf16_f32 v32, v64, v65
	v_cvt_pk_bf16_f32 v33, v66, v67
	global_store_dwordx2 v[34:35], v[32:33], off offset:1536
	v_cvt_pk_bf16_f32 v32, v68, v69
	v_cvt_pk_bf16_f32 v33, v70, v71
	global_store_dwordx2 v[102:103], v[32:33], off offset:16
	v_cvt_pk_bf16_f32 v32, v72, v73
	v_cvt_pk_bf16_f32 v33, v74, v75
	global_store_dwordx2 v[102:103], v[32:33], off offset:32
	v_cvt_pk_bf16_f32 v32, v76, v77
	v_cvt_pk_bf16_f32 v33, v78, v79
	global_store_dwordx2 v[102:103], v[32:33], off offset:48
	v_add_u32_e32 v48, 0x4000, v114
	ds_read2_b64 v[32:35], v48 offset0:64 offset1:66
	ds_read2_b64 v[48:51], v48 offset0:68 offset1:70
	ds_read2_b64 v[52:55], v88 offset1:2
	v_cvt_pk_bf16_f32 v0, v0, v1
	v_cvt_pk_bf16_f32 v1, v2, v3
	v_cvt_pk_bf16_f32 v2, v4, v5
	v_cvt_pk_bf16_f32 v3, v6, v7
	ds_read2_b64 v[4:7], v88 offset0:4 offset1:6
	v_cvt_pk_bf16_f32 v8, v8, v9
	v_cvt_pk_bf16_f32 v9, v10, v11
	s_waitcnt lgkmcnt(3)
	v_mfma_f32_32x32x16_bf16 v[32:47], v[32:35], v[84:87], 0
	v_cvt_pk_bf16_f32 v10, v12, v13
	v_cvt_pk_bf16_f32 v11, v14, v15
	v_cvt_pk_bf16_f32 v12, v16, v17
	v_cvt_pk_bf16_f32 v13, v18, v19
	v_cvt_pk_bf16_f32 v14, v20, v21
	v_cvt_pk_bf16_f32 v15, v22, v23
	s_waitcnt lgkmcnt(2)
	v_mfma_f32_32x32x16_bf16 v[32:47], v[48:51], v[80:83], v[32:47]
	s_waitcnt lgkmcnt(1)
	v_mfma_f32_32x32x16_bf16 v[32:47], v[0:3], v[52:55], v[32:47]
	ds_read2_b64 v[0:3], v88 offset0:8 offset1:10
	s_waitcnt lgkmcnt(1)
	v_mfma_f32_32x32x16_bf16 v[32:47], v[8:11], v[4:7], v[32:47]
	ds_read2_b64 v[4:7], v88 offset0:12 offset1:14
	v_cvt_pk_bf16_f32 v8, v24, v25
	v_cvt_pk_bf16_f32 v9, v26, v27
	v_cvt_pk_bf16_f32 v10, v28, v29
	v_cvt_pk_bf16_f32 v11, v30, v31
	s_waitcnt lgkmcnt(1)
	v_mfma_f32_32x32x16_bf16 v[32:47], v[12:15], v[0:3], v[32:47]
	s_waitcnt lgkmcnt(0)
	v_mfma_f32_32x32x16_bf16 v[32:47], v[8:11], v[4:7], v[32:47]
	s_nop 11
	v_cvt_pk_bf16_f32 v0, v32, v33
	v_cvt_pk_bf16_f32 v1, v34, v35
	v_cvt_pk_bf16_f32 v2, v36, v37
	v_cvt_pk_bf16_f32 v3, v38, v39
	v_cvt_pk_bf16_f32 v4, v40, v41
	v_cvt_pk_bf16_f32 v5, v42, v43
	v_cvt_pk_bf16_f32 v6, v44, v45
	v_cvt_pk_bf16_f32 v7, v46, v47
	global_store_dwordx2 v[102:103], v[0:1], off offset:64
	global_store_dwordx2 v[102:103], v[2:3], off offset:80
	global_store_dwordx2 v[102:103], v[4:5], off offset:96
	global_store_dwordx2 v[102:103], v[6:7], off offset:112
	s_waitcnt lgkmcnt(0)
	v_lshl_add_u64 v[0:1], s[44:45], 0, v[160:161]
	v_add_co_u32_e32 v2, vcc, s20, v0
	s_movk_i32 s11, 0x3000
	s_nop 0
	v_addc_co_u32_e32 v3, vcc, 0, v1, vcc
	v_add_co_u32_e32 v4, vcc, s11, v0
	s_movk_i32 s7, 0x4000
	s_nop 0
	v_addc_co_u32_e32 v5, vcc, 0, v1, vcc
	v_add_co_u32_e32 v0, vcc, s7, v0
	v_readlane_b32 s0, v255, 22
	s_nop 0
	v_addc_co_u32_e32 v1, vcc, 0, v1, vcc
	global_load_dword v24, v[2:3], off offset:3072
	global_load_dword v25, v[4:5], off offset:1024
	global_load_dword v26, v[4:5], off offset:3072
	global_load_dword v27, v[0:1], off offset:1024
	v_or_b32_e32 v0, 1, v148
	v_mad_i64_i32 v[0:1], s[2:3], v0, 36, v[96:97]
	v_lshlrev_b64 v[0:1], 13, v[0:1]
	v_readlane_b32 s1, v255, 23
	v_readlane_b32 s2, v255, 1
	v_readlane_b32 s3, v255, 2
	v_lshl_add_u64 v[0:1], s[0:1], 0, v[0:1]
	v_lshl_add_u64 v[0:1], v[0:1], 0, v[98:99]
	v_lshl_add_u64 v[0:1], v[0:1], 0, v[100:101]
	global_load_dwordx2 v[2:3], v[0:1], off
	global_load_dwordx2 v[4:5], v[0:1], off offset:16
	global_load_dwordx2 v[6:7], v[0:1], off offset:32
	global_load_dwordx2 v[8:9], v[0:1], off offset:48
	s_movk_i32 s0, 0x1000
	v_add_co_u32_e32 v10, vcc, s0, v0
	s_mov_b32 s1, 0xf149f2ca
	s_nop 0
	v_addc_co_u32_e32 v11, vcc, 0, v1, vcc
	global_load_dwordx2 v[12:13], v[10:11], off
	global_load_dwordx2 v[14:15], v[10:11], off offset:16
	global_load_dwordx2 v[16:17], v[10:11], off offset:32
	global_load_dwordx2 v[18:19], v[10:11], off offset:48
	global_load_dwordx2 v[20:21], v[0:1], off offset:64
	global_load_dwordx2 v[22:23], v[0:1], off offset:80
	global_load_dwordx2 v[58:59], v[0:1], off offset:96
	s_nop 0
	global_load_dwordx2 v[0:1], v[0:1], off offset:112
	s_nop 0
	global_load_dwordx2 v[64:65], v[10:11], off offset:64
	global_load_dwordx2 v[72:73], v[10:11], off offset:80
	global_load_dwordx2 v[76:77], v[10:11], off offset:96
	s_nop 0
	global_load_dwordx2 v[10:11], v[10:11], off offset:112
	s_mov_b64 s[40:41], s[44:45]
	s_mov_b64 s[12:13], s[44:45]
	s_waitcnt vmcnt(18)
	v_max3_f32 v28, v24, s1, v25
	s_waitcnt vmcnt(16)
	v_max3_f32 v28, v28, v26, v27
	v_sub_f32_e32 v25, v25, v28
	v_mul_f32_e32 v25, 0x3fb8aa3b, v25
	v_sub_f32_e32 v24, v24, v28
	v_sub_f32_e32 v26, v26, v28
	v_exp_f32_e32 v25, v25
	v_mul_f32_e32 v24, 0x3fb8aa3b, v24
	v_mul_f32_e32 v26, 0x3fb8aa3b, v26
	v_sub_f32_e32 v27, v27, v28
	v_exp_f32_e32 v50, v24
	v_exp_f32_e32 v51, v26
	v_mul_f32_e32 v27, 0x3fb8aa3b, v27
	v_exp_f32_e32 v52, v27
	s_waitcnt vmcnt(15)
	v_lshlrev_b32_e32 v32, 16, v2
	v_and_b32_e32 v33, 0xffff0000, v2
	v_add_f32_e32 v2, 0, v25
	v_cndmask_b32_e64 v2, v2, 0, s[2:3]
	v_readlane_b32 s2, v255, 3
	v_lshlrev_b32_e32 v34, 16, v3
	v_and_b32_e32 v35, 0xffff0000, v3
	s_waitcnt vmcnt(14)
	v_lshlrev_b32_e32 v36, 16, v4
	v_and_b32_e32 v37, 0xffff0000, v4
	v_add_f32_e32 v3, 0, v50
	v_add_f32_e32 v4, v51, v2
	v_readlane_b32 s3, v255, 4
	v_add_f32_e32 v3, v25, v3
	v_add_f32_e32 v3, v51, v3
	v_cndmask_b32_e64 v2, v4, v2, s[2:3]
	v_readlane_b32 s2, v255, 5
	v_add_f32_e32 v4, v52, v2
	v_readlane_b32 s3, v255, 6
	v_add_f32_e32 v3, v52, v3
	v_lshlrev_b32_e32 v38, 16, v5
	v_cndmask_b32_e64 v2, v4, v2, s[2:3]
	v_div_scale_f32 v4, s[2:3], v3, v3, v2
	v_and_b32_e32 v39, 0xffff0000, v5
	v_rcp_f32_e32 v5, v4
	s_waitcnt vmcnt(13)
	v_lshlrev_b32_e32 v42, 16, v7
	v_and_b32_e32 v43, 0xffff0000, v7
	v_lshlrev_b32_e32 v40, 16, v6
	v_fma_f32 v7, -v4, v5, 1.0
	v_and_b32_e32 v41, 0xffff0000, v6
	v_div_scale_f32 v6, vcc, v2, v3, v2
	v_fmac_f32_e32 v5, v7, v5
	v_mul_f32_e32 v7, v6, v5
	s_waitcnt vmcnt(12)
	v_lshlrev_b32_e32 v44, 16, v8
	v_and_b32_e32 v45, 0xffff0000, v8
	v_fma_f32 v8, -v4, v7, v6
	v_fmac_f32_e32 v7, v8, v5
	v_fma_f32 v4, -v4, v7, v6
	s_waitcnt vmcnt(9)
	v_lshlrev_b32_e32 v24, 16, v16
	v_and_b32_e32 v25, 0xffff0000, v16
	v_div_fmas_f32 v4, v4, v5, v7
	v_mov_b32_e32 v16, v94
	v_div_fixup_f32 v116, v4, v3, v2
	s_add_u32 s2, s40, 0xb200000
	v_lshlrev_b32_e32 v46, 16, v9
	v_and_b32_e32 v47, 0xffff0000, v9
	v_lshlrev_b32_e32 v26, 16, v12
	v_and_b32_e32 v27, 0xffff0000, v12
	v_lshlrev_b32_e32 v28, 16, v13
	v_and_b32_e32 v29, 0xffff0000, v13
	v_lshlrev_b32_e32 v30, 16, v14
	v_and_b32_e32 v31, 0xffff0000, v14
	v_lshlrev_b32_e32 v48, 16, v15
	v_and_b32_e32 v49, 0xffff0000, v15
	v_lshlrev_b32_e32 v84, 16, v17
	v_and_b32_e32 v85, 0xffff0000, v17
	s_waitcnt vmcnt(8)
	v_lshlrev_b32_e32 v86, 16, v18
	v_and_b32_e32 v87, 0xffff0000, v18
	v_lshlrev_b32_e32 v96, 16, v19
	v_and_b32_e32 v97, 0xffff0000, v19
	s_waitcnt vmcnt(7)
	v_lshlrev_b32_e32 v54, 16, v20
	v_and_b32_e32 v55, 0xffff0000, v20
	v_lshlrev_b32_e32 v50, 16, v21
	v_and_b32_e32 v51, 0xffff0000, v21
	s_waitcnt vmcnt(6)
	v_lshlrev_b32_e32 v52, 16, v22
	v_and_b32_e32 v53, 0xffff0000, v22
	v_lshlrev_b32_e32 v82, 16, v23
	v_and_b32_e32 v83, 0xffff0000, v23
	s_waitcnt vmcnt(5)
	v_lshlrev_b32_e32 v56, 16, v58
	v_and_b32_e32 v57, 0xffff0000, v58
	v_lshlrev_b32_e32 v58, 16, v59
	v_and_b32_e32 v59, 0xffff0000, v59
	s_waitcnt vmcnt(4)
	v_lshlrev_b32_e32 v60, 16, v0
	v_and_b32_e32 v61, 0xffff0000, v0
	v_lshlrev_b32_e32 v62, 16, v1
	v_and_b32_e32 v63, 0xffff0000, v1
	s_waitcnt vmcnt(3)
	v_lshlrev_b32_e32 v66, 16, v64
	v_and_b32_e32 v67, 0xffff0000, v64
	v_lshlrev_b32_e32 v68, 16, v65
	v_and_b32_e32 v69, 0xffff0000, v65
	s_waitcnt vmcnt(2)
	v_lshlrev_b32_e32 v70, 16, v72
	v_and_b32_e32 v71, 0xffff0000, v72
	v_lshlrev_b32_e32 v72, 16, v73
	v_and_b32_e32 v73, 0xffff0000, v73
	s_waitcnt vmcnt(1)
	v_lshlrev_b32_e32 v74, 16, v76
	v_and_b32_e32 v75, 0xffff0000, v76
	v_lshlrev_b32_e32 v76, 16, v77
	v_and_b32_e32 v77, 0xffff0000, v77
	s_waitcnt vmcnt(0)
	v_lshlrev_b32_e32 v78, 16, v10
	v_and_b32_e32 v79, 0xffff0000, v10
	v_lshlrev_b32_e32 v80, 16, v11
	v_and_b32_e32 v81, 0xffff0000, v11
	v_sub_f32_e32 v117, 1.0, v116
	v_and_b32_e32 v118, 31, v16
	v_ashrrev_i32_e32 v119, 5, v16
	s_addc_u32 s3, s41, 0
	v_mov_b64_e32 v[64:65], s[2:3]
	s_movk_i32 s1, 0x1200
	v_mad_i64_i32 v[0:1], s[2:3], v95, s1, v[64:65]
	v_ashrrev_i32_e32 v17, 31, v16
	v_lshl_add_u64 v[0:1], v[0:1], 0, v[90:91]
	v_lshl_add_u64 v[0:1], v[16:17], 1, v[0:1]
	s_mov_b32 s37, 0x23000
	v_add_co_u32_e32 v12, vcc, s37, v0
	s_movk_i32 s2, 0x5000
	s_nop 0
	v_addc_co_u32_e32 v13, vcc, 0, v1, vcc
	global_load_ushort v88, v[12:13], off offset:3072
	global_load_ushort v109, v[12:13], off offset:1536
	v_add_co_u32_e32 v2, vcc, s20, v0
	s_mov_b32 s28, 0x9000
	s_nop 0
	v_addc_co_u32_e32 v3, vcc, 0, v1, vcc
	v_add_co_u32_e32 v4, vcc, s2, v0
	s_movk_i32 s2, 0x7000
	s_nop 0
	v_addc_co_u32_e32 v5, vcc, 0, v1, vcc
	v_add_co_u32_e32 v6, vcc, s2, v0
	s_mov_b32 s29, 0xb000
	s_nop 0
	v_addc_co_u32_e32 v7, vcc, 0, v1, vcc
	v_add_co_u32_e32 v18, vcc, s28, v0
	s_mov_b32 s18, 0xe000
	s_nop 0
	v_addc_co_u32_e32 v19, vcc, 0, v1, vcc
	v_add_co_u32_e32 v20, vcc, s29, v0
	s_mov_b32 s2, 0x10000
	s_nop 0
	v_addc_co_u32_e32 v21, vcc, 0, v1, vcc
	v_add_co_u32_e32 v22, vcc, s18, v0
	s_mov_b32 s30, 0x17000
	s_nop 0
	v_addc_co_u32_e32 v23, vcc, 0, v1, vcc
	v_add_co_u32_e32 v98, vcc, s2, v0
	s_mov_b32 s2, 0x14000
	s_nop 0
	v_addc_co_u32_e32 v99, vcc, 0, v1, vcc
	v_add_co_u32_e32 v8, vcc, s51, v0
	s_mov_b32 s31, 0x19000
	s_nop 0
	v_addc_co_u32_e32 v9, vcc, 0, v1, vcc
	v_add_co_u32_e32 v10, vcc, s2, v0
	s_mov_b32 s34, 0x1b000
	s_nop 0
	v_addc_co_u32_e32 v11, vcc, 0, v1, vcc
	v_add_co_u32_e32 v14, vcc, s30, v0
	s_mov_b32 s35, 0x1d000
	s_nop 0
	v_addc_co_u32_e32 v15, vcc, 0, v1, vcc
	v_add_co_u32_e32 v100, vcc, s31, v0
	s_mov_b32 s19, 0x20000
	s_nop 0
	v_addc_co_u32_e32 v101, vcc, 0, v1, vcc
	v_add_co_u32_e32 v102, vcc, s34, v0
	s_mov_b32 s36, 0x22000
	s_nop 0
	v_addc_co_u32_e32 v103, vcc, 0, v1, vcc
	v_add_co_u32_e32 v104, vcc, s35, v0
	s_mov_b32 s21, 0x21000
	s_nop 0
	v_addc_co_u32_e32 v105, vcc, 0, v1, vcc
	v_add_co_u32_e32 v106, vcc, s19, v0
	s_mov_b32 s42, 0x1f000
	s_nop 0
	v_addc_co_u32_e32 v107, vcc, 0, v1, vcc
	v_add_co_u32_e32 v120, vcc, s36, v0
	s_mov_b32 s17, 0x1e000
	s_nop 0
	v_addc_co_u32_e32 v121, vcc, 0, v1, vcc
	v_add_co_u32_e32 v110, vcc, s21, v0
	s_mov_b32 s16, 0x1c000
	s_nop 0
	v_addc_co_u32_e32 v111, vcc, 0, v1, vcc
	global_load_ushort v113, v[110:111], off offset:512
	global_load_ushort v108, v[110:111], off offset:1024
	global_load_ushort v122, v[110:111], off offset:2048
	s_nop 0
	global_load_ushort v110, v[12:13], off offset:2048
	global_load_ushort v112, v[120:121], off offset:1536
	global_load_ushort v145, v[120:121], off offset:2560
	global_load_ushort v123, v[104:105], off offset:3584
	global_load_ushort v124, v[106:107], off offset:512
	global_load_ushort v154, v[120:121], off offset:1024
	global_load_ushort v155, v[106:107], off offset:1536
	global_load_ushort v156, v[106:107], off
	global_load_ushort v159, v[104:105], off offset:3072
	global_load_ushort v162, v[104:105], off
	global_load_ushort v166, v[102:103], off offset:3584
	s_waitcnt vmcnt(15)
	v_lshlrev_b32_e32 v12, 16, v88
	v_max_f32_e32 v12, v12, v12
	v_med3_f32 v12, v12, s9, v244
	v_mul_f32_e32 v12, 0xbfb8aa3b, v12
	v_exp_f32_e32 v88, v12
	v_add_co_u32_e32 v12, vcc, s42, v0
	s_mov_b32 s2, 0x1a000
	v_add_f32_e32 v111, 1.0, v88
	v_addc_co_u32_e32 v13, vcc, 0, v1, vcc
	v_rcp_f32_e32 v111, v111
	v_add_co_u32_e32 v136, vcc, s17, v0
	s_waitcnt vmcnt(14)
	v_lshlrev_b32_e32 v109, 16, v109
	v_addc_co_u32_e32 v137, vcc, 0, v1, vcc
	v_add_co_u32_e32 v134, vcc, s16, v0
	v_fma_f32 v114, v117, v111, v116
	s_nop 0
	v_addc_co_u32_e32 v135, vcc, 0, v1, vcc
	v_max_f32_e32 v152, 0xda24260, v114
	v_add_co_u32_e32 v120, vcc, s2, v0
	v_mul_f32_e32 v88, v88, v111
	v_rcp_f32_e32 v111, v152
	v_addc_co_u32_e32 v121, vcc, 0, v1, vcc
	s_mov_b32 s2, 0x18000
	v_add_co_u32_e32 v138, vcc, s2, v0
	s_mov_b32 s2, 0x16000
	s_nop 0
	v_addc_co_u32_e32 v139, vcc, 0, v1, vcc
	v_mul_f32_e32 v88, v117, v88
	v_mul_f32_e32 v109, v152, v109
	global_load_ushort v125, v[14:15], off offset:512
	global_load_ushort v127, v[100:101], off offset:1536
	global_load_ushort v128, v[102:103], off offset:2560
	global_load_ushort v167, v[102:103], off offset:2048
	global_load_ushort v169, v[100:101], off offset:2560
	global_load_ushort v172, v[100:101], off offset:1024
	global_load_ushort v168, v[14:15], off offset:1536
	global_load_ushort v164, v[14:15], off
	v_add_co_u32_e32 v14, vcc, s2, v0
	v_bfe_u32 v114, v109, 16, 1
	v_mul_f32_e32 v88, v88, v111
	v_addc_co_u32_e32 v15, vcc, 0, v1, vcc
	s_mov_b32 s43, 0x15000
	v_add3_u32 v153, v109, v114, s10
	v_bfe_u32 v109, v88, 16, 1
	v_add_co_u32_e32 v140, vcc, s43, v0
	v_add3_u32 v114, v88, v109, s10
	s_nop 0
	v_addc_co_u32_e32 v141, vcc, 0, v1, vcc
	global_load_ushort v126, v[22:23], off offset:512
	global_load_ushort v129, v[98:99], off offset:1536
	global_load_ushort v130, v[8:9], off offset:2560
	global_load_ushort v131, v[10:11], off offset:3584
	global_load_ushort v158, v[10:11], off offset:3072
	global_load_ushort v115, v[10:11], off
	global_load_ushort v111, v[8:9], off offset:3584
	global_load_ushort v109, v[8:9], off offset:2048
	global_load_ushort v173, v[12:13], off offset:1024
	global_load_ushort v174, v[136:137], off offset:3584
	global_load_ushort v175, v[134:135], off offset:2560
	global_load_ushort v176, v[120:121], off offset:1536
	global_load_ushort v133, v[120:121], off offset:2048
	s_nop 0
	global_load_ushort v134, v[134:135], off offset:3072
	s_nop 0
	global_load_ushort v177, v[136:137], off offset:512
	global_load_ushort v135, v[12:13], off
	global_load_ushort v178, v[120:121], off offset:3072
	global_load_ushort v171, v[138:139], off offset:2048
	global_load_ushort v170, v[138:139], off offset:512
	global_load_ushort v165, v[14:15], off offset:1024
	global_load_ushort v163, v[140:141], off offset:3584
	global_load_ushort v160, v[140:141], off offset:512
	global_load_ushort v137, v[14:15], off
	s_nop 0
	global_load_ushort v139, v[138:139], off offset:1024
	s_mov_b32 s44, 0x13000
	v_add_co_u32_e32 v146, vcc, s44, v0
	s_mov_b32 s45, 0x11000
	s_nop 0
	v_addc_co_u32_e32 v147, vcc, 0, v1, vcc
	v_add_co_u32_e32 v106, vcc, s45, v0
	s_mov_b32 s46, 0xf000
	s_nop 0
	v_addc_co_u32_e32 v107, vcc, 0, v1, vcc
	v_add_co_u32_e32 v102, vcc, s46, v0
	s_mov_b32 s47, 0xd000
	s_nop 0
	v_addc_co_u32_e32 v103, vcc, 0, v1, vcc
	v_add_co_u32_e32 v104, vcc, s47, v0
	s_mov_b32 s15, 0xa000
	s_nop 0
	v_addc_co_u32_e32 v105, vcc, 0, v1, vcc
	v_add_co_u32_e32 v100, vcc, s15, v0
	s_mov_b32 s14, 0x8000
	s_waitcnt vmcnt(40)
	v_lshlrev_b32_e32 v8, 16, v145
	v_max_f32_e32 v8, v8, v8
	v_med3_f32 v8, v8, s9, v244
	v_mul_f32_e32 v8, 0xbfb8aa3b, v8
	v_exp_f32_e32 v88, v8
	v_addc_co_u32_e32 v101, vcc, 0, v1, vcc
	v_lshlrev_b32_e32 v122, 16, v122
	v_add_f32_e32 v120, 1.0, v88
	v_rcp_f32_e32 v120, v120
	v_add_co_u32_e32 v10, vcc, s14, v0
	v_max_f32_e32 v122, v122, v122
	v_fma_f32 v121, v117, v120, v116
	v_mul_f32_e32 v121, v152, v121
	v_addc_co_u32_e32 v11, vcc, 0, v1, vcc
	v_max_f32_e32 v121, 0xda24260, v121
	v_med3_f32 v122, v122, s9, v244
	v_add_co_u32_e32 v12, vcc, s27, v0
	v_rcp_f32_e32 v152, v121
	v_mul_f32_e32 v122, 0xbfb8aa3b, v122
	v_addc_co_u32_e32 v13, vcc, 0, v1, vcc
	v_exp_f32_e32 v122, v122
	v_add_co_u32_e32 v14, vcc, s7, v0
	v_mul_f32_e32 v88, v88, v120
	s_nop 0
	v_addc_co_u32_e32 v15, vcc, 0, v1, vcc
	v_mul_f32_e32 v88, v117, v88
	v_add_co_u32_e32 v8, vcc, s0, v0
	v_mul_f32_e32 v88, v88, v152
	global_load_ushort v132, v[0:1], off offset:2560
	global_load_ushort v136, v[2:3], off offset:3584
	global_load_ushort v138, v[4:5], off offset:512
	global_load_ushort v140, v[6:7], off offset:1536
	global_load_ushort v141, v[18:19], off offset:2560
	global_load_ushort v143, v[20:21], off offset:3584
	global_load_ushort v144, v[22:23], off offset:-4096
	global_load_ushort v142, v[4:5], off offset:-4096
	v_addc_co_u32_e32 v9, vcc, 0, v1, vcc
	global_load_ushort v157, v[146:147], off offset:2560
	global_load_ushort v150, v[146:147], off offset:3072
	global_load_ushort v151, v[106:107], off offset:2048
	global_load_ushort v149, v[102:103], off offset:1024
	global_load_ushort v148, v[100:101], off offset:3072
	s_nop 0
	global_load_ushort v146, v[10:11], off offset:2048
	global_load_ushort v147, v[12:13], off offset:1024
	global_load_ushort v145, v[8:9], off offset:3072
	v_bfe_u32 v120, v88, 16, 1
	v_add_f32_e32 v152, 1.0, v122
	v_add3_u32 v88, v88, v120, s10
	s_waitcnt vmcnt(53)
	v_lshlrev_b32_e32 v120, 16, v154
	v_rcp_f32_e32 v152, v152
	v_lshl_add_u32 v17, v16, 1, v92
	v_mul_f32_e32 v120, v121, v120
	ds_write_b16_d16_hi v17, v153 offset:4464
	v_bfe_u32 v153, v120, 16, 1
	v_add3_u32 v120, v120, v153, s10
	ds_write_b16_d16_hi v17, v120 offset:4320
	v_fma_f32 v120, v117, v152, v116
	v_mul_f32_e32 v120, v121, v120
	v_mul_f32_e32 v122, v122, v152
	s_waitcnt vmcnt(52)
	v_lshlrev_b32_e32 v152, 16, v155
	v_max_f32_e32 v120, 0xda24260, v120
	v_max_f32_e32 v152, v152, v152
	v_rcp_f32_e32 v121, v120
	v_med3_f32 v152, v152, s9, v244
	v_mul_f32_e32 v152, 0xbfb8aa3b, v152
	v_exp_f32_e32 v152, v152
	v_mul_f32_e32 v122, v117, v122
	v_mul_f32_e32 v121, v122, v121
	v_bfe_u32 v122, v121, 16, 1
	v_add3_u32 v153, v121, v122, s10
	v_add_f32_e32 v121, 1.0, v152
	v_lshlrev_b32_e32 v113, 16, v113
	v_rcp_f32_e32 v121, v121
	v_mul_f32_e32 v113, v120, v113
	v_bfe_u32 v122, v113, 16, 1
	v_add3_u32 v113, v113, v122, s10
	ds_write_b16_d16_hi v17, v113 offset:4176
	v_fma_f32 v113, v117, v121, v116
	s_waitcnt vmcnt(31)
	v_lshlrev_b32_e32 v122, 16, v173
	v_mul_f32_e32 v113, v120, v113
	v_max_f32_e32 v122, v122, v122
	v_max_f32_e32 v113, 0xda24260, v113
	v_med3_f32 v122, v122, s9, v244
	v_rcp_f32_e32 v120, v113
	v_mul_f32_e32 v122, 0xbfb8aa3b, v122
	v_exp_f32_e32 v122, v122
	v_mul_f32_e32 v121, v152, v121
	v_mul_f32_e32 v121, v117, v121
	v_mul_f32_e32 v120, v121, v120
	v_bfe_u32 v121, v120, 16, 1
	v_add_f32_e32 v152, 1.0, v122
	v_add3_u32 v120, v120, v121, s10
	v_lshlrev_b32_e32 v121, 16, v156
	v_rcp_f32_e32 v152, v152
	v_mul_f32_e32 v121, v113, v121
	v_bfe_u32 v154, v121, 16, 1
	v_add3_u32 v121, v121, v154, s10
	ds_write_b16_d16_hi v17, v121 offset:4032
	v_fma_f32 v121, v117, v152, v116
	v_mul_f32_e32 v113, v113, v121
	v_mul_f32_e32 v122, v122, v152
	s_waitcnt vmcnt(25)
	v_lshlrev_b32_e32 v152, 16, v177
	v_max_f32_e32 v113, 0xda24260, v113
	v_max_f32_e32 v152, v152, v152
	v_rcp_f32_e32 v121, v113
	v_med3_f32 v152, v152, s9, v244
	v_mul_f32_e32 v152, 0xbfb8aa3b, v152
	v_exp_f32_e32 v152, v152
	v_mul_f32_e32 v122, v117, v122
	v_mul_f32_e32 v121, v122, v121
	v_bfe_u32 v122, v121, 16, 1
	v_add3_u32 v154, v121, v122, s10
	v_add_f32_e32 v122, 1.0, v152
	v_lshlrev_b32_e32 v121, 16, v174
	v_rcp_f32_e32 v122, v122
	v_mul_f32_e32 v121, v113, v121
	v_bfe_u32 v155, v121, 16, 1
	v_add3_u32 v121, v121, v155, s10
	ds_write_b16_d16_hi v17, v121 offset:3888
	v_fma_f32 v121, v117, v122, v116
	v_mul_f32_e32 v122, v152, v122
	v_lshlrev_b32_e32 v152, 16, v162
	v_mul_f32_e32 v113, v113, v121
	v_max_f32_e32 v152, v152, v152
	v_max_f32_e32 v113, 0xda24260, v113
	v_med3_f32 v152, v152, s9, v244
	v_rcp_f32_e32 v121, v113
	v_mul_f32_e32 v152, 0xbfb8aa3b, v152
	v_exp_f32_e32 v152, v152
	v_mul_f32_e32 v122, v117, v122
	v_mul_f32_e32 v121, v122, v121
	v_bfe_u32 v122, v121, 16, 1
	v_add_f32_e32 v155, 1.0, v152
	v_add3_u32 v121, v121, v122, s10
	v_lshlrev_b32_e32 v122, 16, v159
	v_rcp_f32_e32 v155, v155
	v_mul_f32_e32 v122, v113, v122
	v_bfe_u32 v156, v122, 16, 1
	v_add3_u32 v122, v122, v156, s10
	ds_write_b16_d16_hi v17, v122 offset:3744
	v_fma_f32 v122, v117, v155, v116
	v_mul_f32_e32 v113, v113, v122
	v_mul_f32_e32 v152, v152, v155
	v_lshlrev_b32_e32 v155, 16, v166
	v_max_f32_e32 v113, 0xda24260, v113
	v_max_f32_e32 v155, v155, v155
	v_rcp_f32_e32 v122, v113
	v_med3_f32 v155, v155, s9, v244
	v_mul_f32_e32 v155, 0xbfb8aa3b, v155
	v_exp_f32_e32 v156, v155
	v_mul_f32_e32 v152, v117, v152
	v_mul_f32_e32 v122, v152, v122
	v_bfe_u32 v152, v122, 16, 1
	v_add3_u32 v155, v122, v152, s10
	v_add_f32_e32 v152, 1.0, v156
	v_lshlrev_b32_e32 v122, 16, v175
	v_rcp_f32_e32 v152, v152
	v_mul_f32_e32 v122, v113, v122
	v_bfe_u32 v159, v122, 16, 1
	v_add3_u32 v122, v122, v159, s10
	ds_write_b16_d16_hi v17, v122 offset:3600
	v_fma_f32 v122, v117, v152, v116
	v_mul_f32_e32 v113, v113, v122
	v_max_f32_e32 v113, 0xda24260, v113
	v_rcp_f32_e32 v122, v113
	v_mul_f32_e32 v152, v156, v152
	v_mul_f32_e32 v152, v117, v152
	ds_write_b16_d16_hi v17, v114 offset:9072
	v_mul_f32_e32 v122, v152, v122
	v_bfe_u32 v152, v122, 16, 1
	v_add3_u32 v122, v122, v152, s10
	v_lshlrev_b32_e32 v152, 16, v167
	v_mul_f32_e32 v152, v113, v152
	v_bfe_u32 v156, v152, 16, 1
	v_add3_u32 v152, v152, v156, s10
	ds_write_b16_d16_hi v17, v88 offset:8928
	ds_write_b16_d16_hi v17, v153 offset:8784
	ds_write_b16_d16_hi v17, v120 offset:8640
	ds_write_b16_d16_hi v17, v154 offset:8496
	ds_write_b16_d16_hi v17, v121 offset:8352
	ds_write_b16_d16_hi v17, v155 offset:8208
	ds_write_b16_d16_hi v17, v152 offset:3456
	ds_write_b16_d16_hi v17, v122 offset:8064
	s_waitcnt vmcnt(23)
	v_lshlrev_b32_e32 v152, 16, v178
	v_max_f32_e32 v152, v152, v152
	v_med3_f32 v152, v152, s9, v244
	v_mul_f32_e32 v152, 0xbfb8aa3b, v152
	v_exp_f32_e32 v152, v152
	v_lshlrev_b32_e32 v109, 16, v109
	v_add_f32_e32 v156, 1.0, v152
	v_rcp_f32_e32 v156, v156
	s_nop 0
	v_fma_f32 v159, v117, v156, v116
	v_mul_f32_e32 v113, v113, v159
	v_max_f32_e32 v113, 0xda24260, v113
	v_mul_f32_e32 v152, v152, v156
	v_rcp_f32_e32 v156, v113
	v_mul_f32_e32 v152, v117, v152
	v_mul_f32_e32 v152, v152, v156
	v_bfe_u32 v156, v152, 16, 1
	v_add3_u32 v156, v152, v156, s10
	v_lshlrev_b32_e32 v152, 16, v176
	v_mul_f32_e32 v152, v113, v152
	v_bfe_u32 v159, v152, 16, 1
	v_add3_u32 v152, v152, v159, s10
	ds_write_b16_d16_hi v17, v152 offset:3312
	ds_write_b16_d16_hi v17, v156 offset:7920
	v_lshlrev_b32_e32 v152, 16, v169
	v_max_f32_e32 v152, v152, v152
	v_med3_f32 v152, v152, s9, v244
	v_mul_f32_e32 v152, 0xbfb8aa3b, v152
	v_exp_f32_e32 v152, v152
	s_nop 0
	v_add_f32_e32 v159, 1.0, v152
	v_rcp_f32_e32 v159, v159
	s_nop 0
	v_fma_f32 v162, v117, v159, v116
	v_mul_f32_e32 v113, v113, v162
	v_max_f32_e32 v173, 0xda24260, v113
	v_rcp_f32_e32 v113, v173
	v_mul_f32_e32 v152, v152, v159
	v_mul_f32_e32 v152, v117, v152
	v_mul_f32_e32 v113, v152, v113
	v_bfe_u32 v152, v113, 16, 1
	v_add3_u32 v152, v113, v152, s10
	v_lshlrev_b32_e32 v113, 16, v172
	v_mul_f32_e32 v113, v173, v113
	v_bfe_u32 v159, v113, 16, 1
	v_add3_u32 v172, v113, v159, s10
	global_load_ushort v169, v[106:107], off offset:3072
	global_load_ushort v167, v[106:107], off offset:1536
	global_load_ushort v166, v[98:99], off offset:2560
	global_load_ushort v162, v[98:99], off offset:1024
	global_load_ushort v159, v[102:103], off offset:2048
	global_load_ushort v113, v[102:103], off offset:512
	s_nop 0
	global_load_ushort v107, v[22:23], off offset:1536
	global_load_ushort v106, v[22:23], off
	s_nop 0
	global_load_ushort v104, v[104:105], off offset:1024
	v_add_co_u32_e32 v22, vcc, s50, v0
	s_nop 1
	v_addc_co_u32_e32 v23, vcc, 0, v1, vcc
	global_load_ushort v103, v[22:23], off offset:3584
	global_load_ushort v102, v[22:23], off offset:512
	global_load_ushort v99, v[20:21], off offset:3072
	global_load_ushort v98, v[20:21], off
	s_nop 0
	global_load_ushort v21, v[100:101], off offset:2560
	global_load_ushort v20, v[18:19], off offset:3584
	s_nop 0
	global_load_ushort v19, v[18:19], off offset:2048
	s_waitcnt vmcnt(38)
	v_lshlrev_b32_e32 v18, 16, v171
	v_max_f32_e32 v18, v18, v18
	v_med3_f32 v18, v18, s9, v244
	v_mul_f32_e32 v18, 0xbfb8aa3b, v18
	v_exp_f32_e32 v18, v18
	ds_write_b16_d16_hi v17, v172 offset:3168
	ds_write_b16_d16_hi v17, v152 offset:7776
	v_add_f32_e32 v22, 1.0, v18
	v_rcp_f32_e32 v22, v22
	s_nop 0
	v_fma_f32 v23, v117, v22, v116
	v_mul_f32_e32 v18, v18, v22
	v_mul_f32_e32 v22, v173, v23
	v_max_f32_e32 v22, 0xda24260, v22
	v_rcp_f32_e32 v23, v22
	v_mul_f32_e32 v18, v117, v18
	v_mul_f32_e32 v18, v18, v23
	v_bfe_u32 v23, v18, 16, 1
	v_add3_u32 v23, v18, v23, s10
	s_waitcnt vmcnt(37)
	v_lshlrev_b32_e32 v18, 16, v170
	v_mul_f32_e32 v18, v22, v18
	v_bfe_u32 v100, v18, 16, 1
	v_add3_u32 v18, v18, v100, s10
	ds_write_b16_d16_hi v17, v18 offset:3024
	ds_write_b16_d16_hi v17, v23 offset:7632
	v_lshlrev_b32_e32 v18, 16, v168
	v_max_f32_e32 v18, v18, v18
	v_med3_f32 v18, v18, s9, v244
	v_mul_f32_e32 v18, 0xbfb8aa3b, v18
	v_exp_f32_e32 v18, v18
	s_nop 0
	v_add_f32_e32 v100, 1.0, v18
	v_rcp_f32_e32 v100, v100
	s_nop 0
	v_fma_f32 v101, v117, v100, v116
	v_mul_f32_e32 v22, v22, v101
	v_max_f32_e32 v22, 0xda24260, v22
	v_mul_f32_e32 v18, v18, v100
	v_rcp_f32_e32 v100, v22
	v_mul_f32_e32 v18, v117, v18
	v_mul_f32_e32 v18, v18, v100
	v_bfe_u32 v100, v18, 16, 1
	v_add3_u32 v18, v18, v100, s10
	v_lshlrev_b32_e32 v100, 16, v164
	v_mul_f32_e32 v100, v22, v100
	v_bfe_u32 v101, v100, 16, 1
	v_add3_u32 v100, v100, v101, s10
	ds_write_b16_d16_hi v17, v100 offset:2880
	ds_write_b16_d16_hi v17, v18 offset:7488
	s_waitcnt vmcnt(36)
	v_lshlrev_b32_e32 v100, 16, v165
	v_max_f32_e32 v100, v100, v100
	v_med3_f32 v100, v100, s9, v244
	v_mul_f32_e32 v100, 0xbfb8aa3b, v100
	v_exp_f32_e32 v100, v100
	s_nop 0
	v_add_f32_e32 v101, 1.0, v100
	v_rcp_f32_e32 v101, v101
	s_nop 0
	v_fma_f32 v105, v117, v101, v116
	v_mul_f32_e32 v22, v22, v105
	v_max_f32_e32 v22, 0xda24260, v22
	v_mul_f32_e32 v100, v100, v101
	v_rcp_f32_e32 v101, v22
	v_mul_f32_e32 v100, v117, v100
	v_mul_f32_e32 v100, v100, v101
	v_bfe_u32 v101, v100, 16, 1
	v_add3_u32 v101, v100, v101, s10
	s_waitcnt vmcnt(35)
	v_lshlrev_b32_e32 v100, 16, v163
	v_mul_f32_e32 v100, v22, v100
	v_bfe_u32 v105, v100, 16, 1
	v_add3_u32 v100, v100, v105, s10
	ds_write_b16_d16_hi v17, v100 offset:2736
	ds_write_b16_d16_hi v17, v101 offset:7344
	s_waitcnt vmcnt(34)
	v_lshlrev_b32_e32 v100, 16, v160
	v_max_f32_e32 v100, v100, v100
	v_med3_f32 v100, v100, s9, v244
	v_mul_f32_e32 v100, 0xbfb8aa3b, v100
	v_exp_f32_e32 v100, v100
	s_nop 0
	v_add_f32_e32 v105, 1.0, v100
	v_rcp_f32_e32 v105, v105
	s_nop 0
	v_fma_f32 v160, v117, v105, v116
	v_mul_f32_e32 v22, v22, v160
	v_mul_f32_e32 v100, v100, v105
	v_max_f32_e32 v105, 0xda24260, v22
	v_rcp_f32_e32 v22, v105
	v_mul_f32_e32 v100, v117, v100
	v_mul_f32_e32 v22, v100, v22
	v_bfe_u32 v100, v22, 16, 1
	v_add3_u32 v22, v22, v100, s10
	v_lshlrev_b32_e32 v100, 16, v158
	v_mul_f32_e32 v100, v105, v100
	v_bfe_u32 v158, v100, 16, 1
	v_add3_u32 v100, v100, v158, s10
	ds_write_b16_d16_hi v17, v100 offset:2592
	ds_write_b16_d16_hi v17, v22 offset:7200
	v_lshlrev_b32_e32 v100, 16, v115
	v_max_f32_e32 v100, v100, v100
	v_med3_f32 v100, v100, s9, v244
	v_mul_f32_e32 v100, 0xbfb8aa3b, v100
	v_exp_f32_e32 v100, v100
	s_nop 0
	v_add_f32_e32 v115, 1.0, v100
	v_rcp_f32_e32 v115, v115
	s_nop 0
	v_fma_f32 v158, v117, v115, v116
	v_mul_f32_e32 v105, v105, v158
	v_mul_f32_e32 v100, v100, v115
	v_max_f32_e32 v115, 0xda24260, v105
	v_rcp_f32_e32 v105, v115
	v_mul_f32_e32 v100, v117, v100
	v_mul_f32_e32 v100, v100, v105
	v_bfe_u32 v105, v100, 16, 1
	v_add3_u32 v105, v100, v105, s10
	s_waitcnt vmcnt(23)
	v_lshlrev_b32_e32 v100, 16, v157
	v_mul_f32_e32 v100, v115, v100
	v_bfe_u32 v157, v100, 16, 1
	v_add3_u32 v100, v100, v157, s10
	ds_write_b16_d16_hi v17, v100 offset:2448
	ds_write_b16_d16_hi v17, v105 offset:7056
	v_lshlrev_b32_e32 v100, 16, v111
	v_max_f32_e32 v100, v100, v100
	v_med3_f32 v100, v100, s9, v244
	v_mul_f32_e32 v100, 0xbfb8aa3b, v100
	v_exp_f32_e32 v100, v100
	s_nop 0
	v_add_f32_e32 v111, 1.0, v100
	v_rcp_f32_e32 v111, v111
	s_nop 0
	v_fma_f32 v157, v117, v111, v116
	v_mul_f32_e32 v100, v100, v111
	v_mul_f32_e32 v111, v115, v157
	v_max_f32_e32 v111, 0xda24260, v111
	v_rcp_f32_e32 v115, v111
	v_mul_f32_e32 v100, v117, v100
	v_mul_f32_e32 v109, v111, v109
	v_mul_f32_e32 v100, v100, v115
	v_bfe_u32 v115, v100, 16, 1
	v_add3_u32 v100, v100, v115, s10
	v_bfe_u32 v115, v109, 16, 1
	v_add3_u32 v109, v109, v115, s10
	ds_write_b16_d16_hi v17, v109 offset:2304
	ds_write_b16_d16_hi v17, v100 offset:6912
	s_waitcnt vmcnt(15)
	v_lshlrev_b32_e32 v109, 16, v169
	v_max_f32_e32 v109, v109, v109
	v_med3_f32 v109, v109, s9, v244
	v_mul_f32_e32 v109, 0xbfb8aa3b, v109
	v_exp_f32_e32 v109, v109
	s_nop 0
	v_add_f32_e32 v115, 1.0, v109
	v_rcp_f32_e32 v115, v115
	s_nop 0
	v_fma_f32 v157, v117, v115, v116
	v_mul_f32_e32 v111, v111, v157
	v_max_f32_e32 v111, 0xda24260, v111
	v_mul_f32_e32 v109, v109, v115
	v_rcp_f32_e32 v115, v111
	v_mul_f32_e32 v109, v117, v109
	v_mul_f32_e32 v109, v109, v115
	v_bfe_u32 v115, v109, 16, 1
	v_add3_u32 v109, v109, v115, s10
	s_waitcnt vmcnt(14)
	v_lshlrev_b32_e32 v115, 16, v167
	v_mul_f32_e32 v115, v111, v115
	v_bfe_u32 v157, v115, 16, 1
	v_add3_u32 v115, v115, v157, s10
	ds_write_b16_d16_hi v17, v115 offset:2160
	ds_write_b16_d16_hi v17, v109 offset:6768
	s_waitcnt vmcnt(13)
	v_lshlrev_b32_e32 v115, 16, v166
	v_max_f32_e32 v115, v115, v115
	v_med3_f32 v115, v115, s9, v244
	v_mul_f32_e32 v115, 0xbfb8aa3b, v115
	v_exp_f32_e32 v115, v115
	global_load_ushort v175, v[10:11], off offset:3072
	global_load_ushort v173, v[10:11], off offset:1536
	global_load_ushort v174, v[6:7], off offset:2560
	global_load_ushort v171, v[6:7], off offset:1024
	global_load_ushort v172, v[12:13], off offset:2048
	global_load_ushort v169, v[12:13], off offset:512
	global_load_ushort v170, v[4:5], off offset:1536
	global_load_ushort v166, v[4:5], off
	global_load_ushort v168, v[14:15], off offset:1024
	v_add_co_u32_e32 v4, vcc, s11, v0
	v_add_f32_e32 v157, 1.0, v115
	v_rcp_f32_e32 v157, v157
	v_addc_co_u32_e32 v5, vcc, 0, v1, vcc
	v_fma_f32 v158, v117, v157, v116
	v_mul_f32_e32 v111, v111, v158
	v_max_f32_e32 v111, 0xda24260, v111
	v_mul_f32_e32 v115, v115, v157
	v_rcp_f32_e32 v157, v111
	v_mul_f32_e32 v115, v117, v115
	v_mul_f32_e32 v115, v115, v157
	v_bfe_u32 v157, v115, 16, 1
	v_add3_u32 v157, v115, v157, s10
	s_waitcnt vmcnt(21)
	v_lshlrev_b32_e32 v115, 16, v162
	v_mul_f32_e32 v115, v111, v115
	v_bfe_u32 v158, v115, 16, 1
	v_add3_u32 v115, v115, v158, s10
	global_load_ushort v165, v[4:5], off offset:3584
	global_load_ushort v167, v[4:5], off offset:512
	global_load_ushort v163, v[2:3], off offset:3072
	global_load_ushort v164, v[2:3], off
	global_load_ushort v160, v[8:9], off offset:2560
	global_load_ushort v162, v[0:1], off offset:3584
	global_load_ushort v158, v[0:1], off offset:2048
	s_waitcnt vmcnt(27)
	v_lshlrev_b32_e32 v0, 16, v159
	v_max_f32_e32 v0, v0, v0
	v_med3_f32 v0, v0, s9, v244
	v_mul_f32_e32 v0, 0xbfb8aa3b, v0
	v_exp_f32_e32 v0, v0
	ds_write_b16_d16_hi v17, v115 offset:2016
	ds_write_b16_d16_hi v17, v157 offset:6624
	v_add_f32_e32 v1, 1.0, v0
	v_rcp_f32_e32 v1, v1
	s_nop 0
	v_fma_f32 v2, v117, v1, v116
	v_mul_f32_e32 v0, v0, v1
	v_mul_f32_e32 v1, v111, v2
	v_max_f32_e32 v1, 0xda24260, v1
	v_rcp_f32_e32 v2, v1
	v_mul_f32_e32 v0, v117, v0
	v_mul_f32_e32 v0, v0, v2
	v_bfe_u32 v2, v0, 16, 1
	v_add3_u32 v0, v0, v2, s10
	s_waitcnt vmcnt(26)
	v_lshlrev_b32_e32 v2, 16, v113
	v_mul_f32_e32 v2, v1, v2
	v_bfe_u32 v3, v2, 16, 1
	v_add3_u32 v2, v2, v3, s10
	ds_write_b16_d16_hi v17, v2 offset:1872
	ds_write_b16_d16_hi v17, v0 offset:6480
	s_waitcnt vmcnt(25)
	v_lshlrev_b32_e32 v2, 16, v107
	v_max_f32_e32 v2, v2, v2
	v_med3_f32 v2, v2, s9, v244
	v_mul_f32_e32 v2, 0xbfb8aa3b, v2
	v_exp_f32_e32 v2, v2
	s_nop 0
	v_add_f32_e32 v3, 1.0, v2
	v_rcp_f32_e32 v3, v3
	s_nop 0
	v_fma_f32 v4, v117, v3, v116
	v_mul_f32_e32 v1, v1, v4
	v_max_f32_e32 v1, 0xda24260, v1
	v_mul_f32_e32 v2, v2, v3
	v_rcp_f32_e32 v3, v1
	v_mul_f32_e32 v2, v117, v2
	v_mul_f32_e32 v2, v2, v3
	v_bfe_u32 v3, v2, 16, 1
	v_add3_u32 v159, v2, v3, s10
	s_waitcnt vmcnt(24)
	v_lshlrev_b32_e32 v2, 16, v106
	v_mul_f32_e32 v2, v1, v2
	v_bfe_u32 v3, v2, 16, 1
	v_add3_u32 v2, v2, v3, s10
	ds_write_b16_d16_hi v17, v2 offset:1728
	ds_write_b16_d16_hi v17, v159 offset:6336
	s_waitcnt vmcnt(23)
	v_lshlrev_b32_e32 v2, 16, v104
	v_max_f32_e32 v2, v2, v2
	v_med3_f32 v2, v2, s9, v244
	v_mul_f32_e32 v2, 0xbfb8aa3b, v2
	v_exp_f32_e32 v2, v2
	s_nop 0
	v_add_f32_e32 v3, 1.0, v2
	v_rcp_f32_e32 v3, v3
	s_nop 0
	v_fma_f32 v4, v117, v3, v116
	v_mul_f32_e32 v1, v1, v4
	v_max_f32_e32 v1, 0xda24260, v1
	v_mul_f32_e32 v2, v2, v3
	v_rcp_f32_e32 v3, v1
	v_mul_f32_e32 v2, v117, v2
	v_mul_f32_e32 v2, v2, v3
	v_bfe_u32 v3, v2, 16, 1
	v_add3_u32 v2, v2, v3, s10
	s_waitcnt vmcnt(22)
	v_lshlrev_b32_e32 v3, 16, v103
	v_mul_f32_e32 v3, v1, v3
	v_bfe_u32 v4, v3, 16, 1
	v_add3_u32 v3, v3, v4, s10
	ds_write_b16_d16_hi v17, v3 offset:1584
	ds_write_b16_d16_hi v17, v2 offset:6192
	s_waitcnt vmcnt(21)
	v_lshlrev_b32_e32 v3, 16, v102
	v_max_f32_e32 v3, v3, v3
	v_med3_f32 v3, v3, s9, v244
	v_mul_f32_e32 v3, 0xbfb8aa3b, v3
	v_exp_f32_e32 v3, v3
	s_nop 0
	v_add_f32_e32 v4, 1.0, v3
	v_rcp_f32_e32 v4, v4
	s_nop 0
	v_fma_f32 v5, v117, v4, v116
	v_mul_f32_e32 v1, v1, v5
	v_max_f32_e32 v1, 0xda24260, v1
	v_mul_f32_e32 v3, v3, v4
	v_rcp_f32_e32 v4, v1
	v_mul_f32_e32 v3, v117, v3
	v_mul_f32_e32 v3, v3, v4
	v_bfe_u32 v4, v3, 16, 1
	v_add3_u32 v102, v3, v4, s10
	s_waitcnt vmcnt(20)
	v_lshlrev_b32_e32 v3, 16, v99
	v_mul_f32_e32 v3, v1, v3
	v_bfe_u32 v4, v3, 16, 1
	v_add3_u32 v3, v3, v4, s10
	ds_write_b16_d16_hi v17, v3 offset:1440
	ds_write_b16_d16_hi v17, v102 offset:6048
	s_waitcnt vmcnt(19)
	v_lshlrev_b32_e32 v3, 16, v98
	v_max_f32_e32 v3, v3, v3
	v_med3_f32 v3, v3, s9, v244
	v_mul_f32_e32 v3, 0xbfb8aa3b, v3
	v_exp_f32_e32 v3, v3
	s_nop 0
	v_add_f32_e32 v4, 1.0, v3
	v_rcp_f32_e32 v4, v4
	s_nop 0
	v_fma_f32 v5, v117, v4, v116
	v_mul_f32_e32 v1, v1, v5
	v_max_f32_e32 v1, 0xda24260, v1
	v_mul_f32_e32 v3, v3, v4
	v_rcp_f32_e32 v4, v1
	v_mul_f32_e32 v3, v117, v3
	v_mul_f32_e32 v3, v3, v4
	v_bfe_u32 v4, v3, 16, 1
	v_add3_u32 v3, v3, v4, s10
	s_waitcnt vmcnt(18)
	v_lshlrev_b32_e32 v4, 16, v21
	v_mul_f32_e32 v4, v1, v4
	v_bfe_u32 v5, v4, 16, 1
	v_add3_u32 v4, v4, v5, s10
	ds_write_b16_d16_hi v17, v4 offset:1296
	ds_write_b16_d16_hi v17, v3 offset:5904
	s_waitcnt vmcnt(17)
	v_lshlrev_b32_e32 v4, 16, v20
	v_max_f32_e32 v4, v4, v4
	v_med3_f32 v4, v4, s9, v244
	v_mul_f32_e32 v4, 0xbfb8aa3b, v4
	v_exp_f32_e32 v4, v4
	s_nop 0
	v_add_f32_e32 v5, 1.0, v4
	v_rcp_f32_e32 v5, v5
	s_nop 0
	v_fma_f32 v6, v117, v5, v116
	v_mul_f32_e32 v1, v1, v6
	v_max_f32_e32 v12, 0xda24260, v1
	v_rcp_f32_e32 v1, v12
	v_mul_f32_e32 v4, v4, v5
	v_mul_f32_e32 v4, v117, v4
	v_mul_f32_e32 v1, v4, v1
	v_bfe_u32 v4, v1, 16, 1
	v_add3_u32 v20, v1, v4, s10
	s_waitcnt vmcnt(16)
	v_lshlrev_b32_e32 v1, 16, v19
	v_mul_f32_e32 v1, v12, v1
	v_bfe_u32 v4, v1, 16, 1
	v_add3_u32 v1, v1, v4, s10
	ds_write_b16_d16_hi v17, v1 offset:1152
	ds_write_b16_d16_hi v17, v20 offset:5760
	s_waitcnt vmcnt(15)
	v_lshlrev_b32_e32 v8, 16, v175
	v_max_f32_e32 v8, v8, v8
	v_med3_f32 v8, v8, s9, v244
	v_mul_f32_e32 v8, 0xbfb8aa3b, v8
	v_exp_f32_e32 v98, v8
	v_and_b32_e32 v113, 0xffff0000, v2
	v_lshl_or_b32 v2, v108, 16, v124
	v_and_b32_e32 v115, 0xffff0000, v3
	v_add_f32_e32 v13, 1.0, v98
	v_rcp_f32_e32 v104, v13
	v_lshl_or_b32 v3, v110, 16, v112
	v_lshl_or_b32 v11, v151, 16, v129
	v_and_b32_e32 v19, 0xffff0000, v114
	v_fma_f32 v106, v117, v104, v116
	v_mul_f32_e32 v12, v12, v106
	v_max_f32_e32 v106, 0xda24260, v12
	v_rcp_f32_e32 v108, v106
	v_mul_f32_e32 v98, v98, v104
	v_mul_f32_e32 v98, v117, v98
	v_lshl_or_b32 v7, v133, 16, v127
	v_mul_f32_e32 v98, v98, v108
	v_bfe_u32 v104, v98, 16, 1
	v_add3_u32 v98, v98, v104, s10
	s_waitcnt vmcnt(13)
	v_lshlrev_b32_e32 v104, 16, v174
	v_max_f32_e32 v104, v104, v104
	v_med3_f32 v104, v104, s9, v244
	v_mul_f32_e32 v104, 0xbfb8aa3b, v104
	v_exp_f32_e32 v104, v104
	v_lshlrev_b32_e32 v108, 16, v173
	v_mul_f32_e32 v108, v106, v108
	v_bfe_u32 v112, v108, 16, 1
	v_add_f32_e32 v110, 1.0, v104
	v_rcp_f32_e32 v110, v110
	v_add3_u32 v108, v108, v112, s10
	ds_write_b16_d16_hi v17, v108 offset:1008
	v_and_b32_e32 v129, 0xffff0000, v98
	v_fma_f32 v108, v117, v110, v116
	v_mul_f32_e32 v106, v106, v108
	v_max_f32_e32 v106, 0xda24260, v106
	v_rcp_f32_e32 v108, v106
	ds_write_b16_d16_hi v17, v98 offset:5616
	v_mul_f32_e32 v98, v104, v110
	v_mul_f32_e32 v98, v117, v98
	v_mul_f32_e32 v98, v98, v108
	s_waitcnt vmcnt(11)
	v_lshlrev_b32_e32 v108, 16, v172
	v_max_f32_e32 v108, v108, v108
	v_med3_f32 v108, v108, s9, v244
	v_mul_f32_e32 v108, 0xbfb8aa3b, v108
	v_exp_f32_e32 v108, v108
	v_bfe_u32 v104, v98, 16, 1
	v_add3_u32 v98, v98, v104, s10
	v_lshlrev_b32_e32 v104, 16, v171
	v_add_f32_e32 v110, 1.0, v108
	v_rcp_f32_e32 v110, v110
	v_mul_f32_e32 v104, v106, v104
	v_bfe_u32 v112, v104, 16, 1
	v_add3_u32 v104, v104, v112, s10
	ds_write_b16_d16_hi v17, v104 offset:864
	v_fma_f32 v104, v117, v110, v116
	v_mul_f32_e32 v104, v106, v104
	v_max_f32_e32 v104, 0xda24260, v104
	v_rcp_f32_e32 v106, v104
	v_mul_f32_e32 v108, v108, v110
	v_mul_f32_e32 v108, v117, v108
	s_waitcnt vmcnt(10)
	v_lshlrev_b32_e32 v110, 16, v169
	v_mul_f32_e32 v106, v108, v106
	v_bfe_u32 v108, v106, 16, 1
	v_add3_u32 v106, v106, v108, s10
	s_waitcnt vmcnt(9)
	v_lshlrev_b32_e32 v108, 16, v170
	v_max_f32_e32 v108, v108, v108
	v_med3_f32 v108, v108, s9, v244
	v_mul_f32_e32 v108, 0xbfb8aa3b, v108
	v_exp_f32_e32 v108, v108
	v_mul_f32_e32 v110, v104, v110
	v_bfe_u32 v114, v110, 16, 1
	v_add3_u32 v110, v110, v114, s10
	v_add_f32_e32 v112, 1.0, v108
	v_rcp_f32_e32 v112, v112
	ds_write_b16_d16_hi v17, v110 offset:720
	v_and_b32_e32 v127, 0xffff0000, v106
	ds_write_b16_d16_hi v17, v106 offset:5328
	v_fma_f32 v110, v117, v112, v116
	v_mul_f32_e32 v104, v104, v110
	v_max_f32_e32 v104, 0xda24260, v104
	v_rcp_f32_e32 v110, v104
	v_mul_f32_e32 v106, v108, v112
	v_mul_f32_e32 v106, v117, v106
	v_lshl_or_b32 v1, v135, 16, v123
	v_mul_f32_e32 v106, v106, v110
	s_waitcnt vmcnt(7)
	v_lshlrev_b32_e32 v110, 16, v168
	v_max_f32_e32 v110, v110, v110
	v_med3_f32 v110, v110, s9, v244
	v_mul_f32_e32 v110, 0xbfb8aa3b, v110
	v_exp_f32_e32 v110, v110
	v_bfe_u32 v108, v106, 16, 1
	v_add3_u32 v106, v106, v108, s10
	v_lshlrev_b32_e32 v108, 16, v166
	v_add_f32_e32 v112, 1.0, v110
	v_rcp_f32_e32 v112, v112
	v_mul_f32_e32 v108, v104, v108
	v_bfe_u32 v114, v108, 16, 1
	v_add3_u32 v108, v108, v114, s10
	ds_write_b16_d16_hi v17, v108 offset:576
	v_fma_f32 v108, v117, v112, v116
	v_mul_f32_e32 v104, v104, v108
	v_max_f32_e32 v104, 0xda24260, v104
	v_rcp_f32_e32 v108, v104
	v_mul_f32_e32 v110, v110, v112
	v_mul_f32_e32 v110, v117, v110
	s_waitcnt vmcnt(6)
	v_lshlrev_b32_e32 v112, 16, v165
	v_mul_f32_e32 v108, v110, v108
	v_bfe_u32 v110, v108, 16, 1
	v_add3_u32 v108, v108, v110, s10
	s_waitcnt vmcnt(5)
	v_lshlrev_b32_e32 v110, 16, v167
	v_max_f32_e32 v110, v110, v110
	v_med3_f32 v110, v110, s9, v244
	v_mul_f32_e32 v110, 0xbfb8aa3b, v110
	v_exp_f32_e32 v110, v110
	v_mul_f32_e32 v112, v104, v112
	v_bfe_u32 v123, v112, 16, 1
	v_add3_u32 v112, v112, v123, s10
	v_add_f32_e32 v114, 1.0, v110
	v_rcp_f32_e32 v114, v114
	ds_write_b16_d16_hi v17, v112 offset:432
	v_lshl_or_b32 v5, v137, 16, v131
	v_and_b32_e32 v131, 0xffff0000, v108
	v_fma_f32 v112, v117, v114, v116
	v_mul_f32_e32 v104, v104, v112
	v_max_f32_e32 v104, 0xda24260, v104
	v_rcp_f32_e32 v112, v104
	ds_write_b16_d16_hi v17, v108 offset:5040
	v_mul_f32_e32 v108, v110, v114
	v_mul_f32_e32 v108, v117, v108
	v_mul_f32_e32 v108, v108, v112
	s_waitcnt vmcnt(3)
	v_lshlrev_b32_e32 v112, 16, v164
	v_max_f32_e32 v112, v112, v112
	v_med3_f32 v112, v112, s9, v244
	v_mul_f32_e32 v112, 0xbfb8aa3b, v112
	v_exp_f32_e32 v112, v112
	v_bfe_u32 v110, v108, 16, 1
	v_add3_u32 v108, v108, v110, s10
	v_lshlrev_b32_e32 v110, 16, v163
	v_add_f32_e32 v114, 1.0, v112
	v_rcp_f32_e32 v114, v114
	v_mul_f32_e32 v110, v104, v110
	v_bfe_u32 v123, v110, 16, 1
	v_add3_u32 v110, v110, v123, s10
	ds_write_b16_d16_hi v17, v110 offset:288
	v_fma_f32 v110, v117, v114, v116
	v_mul_f32_e32 v104, v104, v110
	v_max_f32_e32 v104, 0xda24260, v104
	v_rcp_f32_e32 v110, v104
	v_mul_f32_e32 v112, v112, v114
	v_mul_f32_e32 v112, v117, v112
	s_waitcnt vmcnt(2)
	v_lshlrev_b32_e32 v114, 16, v160
	v_mul_f32_e32 v110, v112, v110
	v_bfe_u32 v112, v110, 16, 1
	v_add3_u32 v110, v110, v112, s10
	s_waitcnt vmcnt(1)
	v_lshlrev_b32_e32 v112, 16, v162
	v_max_f32_e32 v112, v112, v112
	v_med3_f32 v112, v112, s9, v244
	v_mul_f32_e32 v112, 0xbfb8aa3b, v112
	v_exp_f32_e32 v112, v112
	v_mul_f32_e32 v114, v104, v114
	v_bfe_u32 v124, v114, 16, 1
	v_add3_u32 v114, v114, v124, s10
	v_add_f32_e32 v123, 1.0, v112
	v_rcp_f32_e32 v123, v123
	ds_write_b16_d16_hi v17, v114 offset:144
	v_lshl_or_b32 v12, v145, 16, v132
	v_lshl_or_b32 v6, v139, 16, v125
	v_fma_f32 v114, v117, v123, v116
	v_mul_f32_e32 v104, v104, v114
	v_max_f32_e32 v132, 0xda24260, v104
	v_rcp_f32_e32 v104, v132
	v_and_b32_e32 v125, 0xffff0000, v110
	ds_write_b16_d16_hi v17, v110 offset:4752
	v_mul_f32_e32 v110, v112, v123
	v_mul_f32_e32 v110, v117, v110
	v_mul_f32_e32 v104, v110, v104
	v_bfe_u32 v110, v104, 16, 1
	v_add3_u32 v104, v104, v110, s10
	s_waitcnt vmcnt(0)
	v_lshlrev_b32_e32 v110, 16, v158
	v_mul_f32_e32 v110, v132, v110
	v_bfe_u32 v112, v110, 16, 1
	v_add3_u32 v110, v110, v112, s10
	v_and_b32_e32 v111, 0xffff0000, v0
	v_and_b32_e32 v109, 0xffff0000, v109
	v_and_b32_e32 v107, 0xffff0000, v105
	v_and_b32_e32 v105, 0xffff0000, v101
	v_and_b32_e32 v103, 0xffff0000, v23
	v_and_b32_e32 v101, 0xffff0000, v156
	v_and_b32_e32 v99, 0xffff0000, v155
	v_and_b32_e32 v23, 0xffff0000, v154
	v_and_b32_e32 v21, 0xffff0000, v153
	v_lshl_or_b32 v0, v134, 16, v128
	v_lshl_or_b32 v4, v150, 16, v130
	v_lshl_or_b32 v10, v149, 16, v126
	v_lshl_or_b32 v9, v144, 16, v143
	v_lshl_or_b32 v8, v148, 16, v141
	v_lshl_or_b32 v15, v146, 16, v140
	v_lshl_or_b32 v14, v147, 16, v138
	v_lshl_or_b32 v13, v142, 16, v136
	ds_write_b16_d16_hi v17, v98 offset:5472
	ds_write_b16_d16_hi v17, v106 offset:5184
	ds_write_b16_d16_hi v17, v108 offset:4896
	ds_write_b16_d16_hi v17, v110
	ds_write_b16_d16_hi v17, v104 offset:4608
	v_and_b32_e32 v124, 0xffff0000, v104
	v_and_b32_e32 v130, 0xffff0000, v108
	v_and_b32_e32 v126, 0xffff0000, v106
	v_and_b32_e32 v128, 0xffff0000, v98
	s_movk_i32 s0, 0x50
	v_pk_mul_f32 v[124:125], v[132:133], v[124:125] op_sel_hi:[0,1]
	v_pk_mul_f32 v[130:131], v[132:133], v[130:131] op_sel_hi:[0,1]
	v_pk_mul_f32 v[126:127], v[132:133], v[126:127] op_sel_hi:[0,1]
	v_pk_mul_f32 v[128:129], v[132:133], v[128:129] op_sel_hi:[0,1]
	v_and_b32_e32 v114, 0xffff0000, v20
	v_and_b32_e32 v112, 0xffff0000, v102
	v_and_b32_e32 v110, 0xffff0000, v159
	v_and_b32_e32 v108, 0xffff0000, v157
	v_and_b32_e32 v106, 0xffff0000, v100
	v_and_b32_e32 v104, 0xffff0000, v22
	v_and_b32_e32 v102, 0xffff0000, v18
	v_and_b32_e32 v100, 0xffff0000, v152
	v_and_b32_e32 v98, 0xffff0000, v122
	v_and_b32_e32 v22, 0xffff0000, v121
	v_and_b32_e32 v20, 0xffff0000, v120
	v_and_b32_e32 v18, 0xffff0000, v88
	v_mad_u64_u32 v[134:135], s[2:3], v16, s0, v[92:93]
	v_cvt_pk_bf16_f32 v124, v124, v125
	v_cvt_pk_bf16_f32 v125, v130, v131
	v_cvt_pk_bf16_f32 v126, v126, v127
	v_cvt_pk_bf16_f32 v127, v128, v129
	v_pk_mul_f32 v[114:115], v[132:133], v[114:115] op_sel_hi:[0,1]
	v_pk_mul_f32 v[112:113], v[132:133], v[112:113] op_sel_hi:[0,1]
	v_pk_mul_f32 v[110:111], v[132:133], v[110:111] op_sel_hi:[0,1]
	v_pk_mul_f32 v[108:109], v[132:133], v[108:109] op_sel_hi:[0,1]
	v_pk_mul_f32 v[106:107], v[132:133], v[106:107] op_sel_hi:[0,1]
	v_pk_mul_f32 v[104:105], v[132:133], v[104:105] op_sel_hi:[0,1]
	v_pk_mul_f32 v[102:103], v[132:133], v[102:103] op_sel_hi:[0,1]
	v_pk_mul_f32 v[100:101], v[132:133], v[100:101] op_sel_hi:[0,1]
	v_pk_mul_f32 v[98:99], v[132:133], v[98:99] op_sel_hi:[0,1]
	v_pk_mul_f32 v[22:23], v[132:133], v[22:23] op_sel_hi:[0,1]
	v_pk_mul_f32 v[20:21], v[132:133], v[20:21] op_sel_hi:[0,1]
	v_pk_mul_f32 v[18:19], v[132:133], v[18:19] op_sel_hi:[0,1]
	ds_write_b128 v134, v[124:127] offset:9216
	v_cvt_pk_bf16_f32 v124, v114, v115
	v_cvt_pk_bf16_f32 v125, v112, v113
	v_cvt_pk_bf16_f32 v126, v110, v111
	v_cvt_pk_bf16_f32 v127, v108, v109
	v_cvt_pk_bf16_f32 v106, v106, v107
	v_cvt_pk_bf16_f32 v107, v104, v105
	v_cvt_pk_bf16_f32 v108, v102, v103
	v_cvt_pk_bf16_f32 v109, v100, v101
	v_cvt_pk_bf16_f32 v98, v98, v99
	v_cvt_pk_bf16_f32 v99, v22, v23
	v_cvt_pk_bf16_f32 v100, v20, v21
	v_cvt_pk_bf16_f32 v101, v18, v19
	v_lshl_add_u32 v16, v16, 2, v92
	ds_write_b128 v134, v[124:127] offset:9232
	ds_write_b128 v134, v[106:109] offset:9248
	ds_write_b128 v134, v[98:101] offset:9264
	ds_write_b32 v16, v132 offset:19456
	ds_write_b128 v134, v[12:15] offset:14336
	ds_write_b128 v134, v[8:11] offset:14352
	ds_write_b128 v134, v[4:7] offset:14368
	ds_write_b128 v134, v[0:3] offset:14384
	s_waitcnt lgkmcnt(0)
	v_or_b32_e32 v88, v95, v118
	v_lshlrev_b64 v[0:1], 11, v[88:89]
	v_lshlrev_b32_e32 v100, 2, v119
	v_lshl_add_u64 v[0:1], s[40:41], 0, v[0:1]
	v_ashrrev_i32_e32 v101, 31, v100
	v_mad_u32_u24 v106, v118, s48, v92
	v_lshlrev_b32_e32 v95, 4, v119
	v_lshl_add_u64 v[0:1], v[0:1], 0, v[90:91]
	v_lshlrev_b64 v[102:103], 1, v[100:101]
	v_add_u32_e32 v107, v106, v95
	v_lshl_add_u64 v[104:105], v[0:1], 0, v[102:103]
	ds_read_b128 v[0:3], v107 offset:4608
	ds_read_b128 v[4:7], v107
	ds_read_b128 v[16:19], v107 offset:32
	ds_read_b128 v[20:23], v107 offset:4640
	s_waitcnt lgkmcnt(2)
	v_mfma_f32_32x32x16_bf16 v[0:15], v[0:3], v[4:7], 0
	v_cmp_ge_i32_e32 vcc, v100, v118
	v_cvt_pk_bf16_f32 v120, v32, v33
	v_cvt_pk_bf16_f32 v121, v34, v35
	v_cvt_pk_bf16_f32 v122, v36, v37
	v_cvt_pk_bf16_f32 v123, v38, v39
	v_lshl_add_u64 v[98:99], v[104:105], 0, s[4:5]
	global_load_dwordx2 v[196:197], v[98:99], off
	global_load_dwordx2 v[198:199], v[98:99], off offset:16
	global_load_dwordx2 v[200:201], v[98:99], off offset:32
	global_load_dwordx2 v[202:203], v[98:99], off offset:48
	global_load_dwordx2 v[230:231], v[98:99], off offset:64
	global_load_dwordx2 v[232:233], v[98:99], off offset:80
	global_load_dwordx2 v[234:235], v[98:99], off offset:96
	global_load_dwordx2 v[240:241], v[98:99], off offset:112
	s_waitcnt lgkmcnt(0)
	v_mfma_f32_32x32x16_bf16 v[0:15], v[20:23], v[16:19], v[0:15]
	ds_read_b128 v[16:19], v107 offset:4672
	ds_read_b128 v[20:23], v107 offset:64
	s_waitcnt lgkmcnt(0)
	v_mfma_f32_32x32x16_bf16 v[0:15], v[16:19], v[20:23], v[0:15]
	ds_read_b128 v[16:19], v107 offset:4704
	ds_read_b128 v[20:23], v107 offset:96
	s_waitcnt lgkmcnt(0)
	v_mfma_f32_32x32x16_bf16 v[0:15], v[16:19], v[20:23], v[0:15]
	v_or_b32_e32 v16, 1, v100
	s_nop 10
	v_cndmask_b32_e32 v0, 0, v0, vcc
	v_cmp_ge_i32_e32 vcc, v16, v118
	v_or_b32_e32 v16, 2, v100
	s_nop 0
	v_cndmask_b32_e32 v1, 0, v1, vcc
	v_cmp_ge_i32_e32 vcc, v16, v118
	v_or_b32_e32 v16, 3, v100
	s_nop 0
	v_cndmask_b32_e32 v2, 0, v2, vcc
	v_cmp_ge_i32_e32 vcc, v16, v118
	v_add_u32_e32 v16, 8, v100
	s_nop 0
	v_cndmask_b32_e32 v3, 0, v3, vcc
	v_cmp_ge_i32_e32 vcc, v16, v118
	v_add_u32_e32 v16, 9, v100
	v_cvt_pk_bf16_f32 v17, v2, v3
	v_cndmask_b32_e32 v4, 0, v4, vcc
	v_cmp_ge_i32_e32 vcc, v16, v118
	v_add_u32_e32 v16, 10, v100
	s_nop 0
	v_cndmask_b32_e32 v5, 0, v5, vcc
	v_cmp_ge_i32_e32 vcc, v16, v118
	v_add_u32_e32 v16, 11, v100
	v_cvt_pk_bf16_f32 v18, v4, v5
	v_cndmask_b32_e32 v6, 0, v6, vcc
	v_cmp_ge_i32_e32 vcc, v16, v118
	v_add_u32_e32 v16, 16, v100
	s_nop 0
	v_cndmask_b32_e32 v7, 0, v7, vcc
	v_cmp_ge_i32_e32 vcc, v16, v118
	v_add_u32_e32 v16, 17, v100
	v_cvt_pk_bf16_f32 v19, v6, v7
	v_cndmask_b32_e32 v8, 0, v8, vcc
	v_cmp_ge_i32_e32 vcc, v16, v118
	v_add_u32_e32 v16, 18, v100
	s_nop 0
	v_cndmask_b32_e32 v9, 0, v9, vcc
	v_cmp_ge_i32_e32 vcc, v16, v118
	v_add_u32_e32 v16, 19, v100
	v_cvt_pk_bf16_f32 v20, v8, v9
	v_cndmask_b32_e32 v10, 0, v10, vcc
	v_cmp_ge_i32_e32 vcc, v16, v118
	v_add_u32_e32 v16, 24, v100
	s_nop 0
	v_cndmask_b32_e32 v11, 0, v11, vcc
	v_cmp_ge_i32_e32 vcc, v16, v118
	v_add_u32_e32 v16, 25, v100
	v_cvt_pk_bf16_f32 v21, v10, v11
	v_cndmask_b32_e32 v12, 0, v12, vcc
	v_cmp_ge_i32_e32 vcc, v16, v118
	v_add_u32_e32 v16, 26, v100
	s_nop 0
	v_cndmask_b32_e32 v13, 0, v13, vcc
	v_cmp_ge_i32_e32 vcc, v16, v118
	v_add_u32_e32 v16, 27, v100
	v_cvt_pk_bf16_f32 v22, v12, v13
	v_cndmask_b32_e32 v14, 0, v14, vcc
	v_cmp_ge_i32_e32 vcc, v16, v118
	v_cvt_pk_bf16_f32 v16, v0, v1
	v_lshlrev_b32_e32 v0, 3, v119
	v_mul_u32_u24_e32 v1, 0x50, v118
	v_add3_u32 v107, v92, v0, v1
	v_add_u32_e32 v4, 0x3800, v107
	v_add_u32_e32 v106, v106, v0
	ds_read2_b64 v[0:3], v4 offset1:2
	ds_read2_b64 v[108:111], v4 offset0:4 offset1:6
	v_cndmask_b32_e32 v15, 0, v15, vcc
	v_cvt_pk_bf16_f32 v23, v14, v15
	s_waitcnt lgkmcnt(1)
	v_mfma_f32_32x32x16_bf16 v[0:15], v[0:3], v[16:19], 0
	v_add_co_u32_e32 v104, vcc, s6, v104
	s_nop 1
	v_addc_co_u32_e32 v105, vcc, 0, v105, vcc
	s_waitcnt lgkmcnt(0)
	v_mfma_f32_32x32x16_bf16 v[0:15], v[108:111], v[20:23], v[0:15]
	ds_read2_b64 v[108:111], v106 offset1:2
	ds_read2_b64 v[112:115], v106 offset0:4 offset1:6
	s_waitcnt lgkmcnt(1)
	v_mfma_f32_32x32x16_bf16 v[0:15], v[120:123], v[108:111], v[0:15]
	v_cvt_pk_bf16_f32 v108, v40, v41
	v_cvt_pk_bf16_f32 v109, v42, v43
	v_cvt_pk_bf16_f32 v110, v44, v45
	v_cvt_pk_bf16_f32 v111, v46, v47
	s_waitcnt lgkmcnt(0)
	s_nop 0
	v_mfma_f32_32x32x16_bf16 v[0:15], v[108:111], v[112:115], v[0:15]
	ds_read2_b64 v[108:111], v106 offset0:8 offset1:10
	v_cvt_pk_bf16_f32 v112, v54, v55
	v_cvt_pk_bf16_f32 v113, v50, v51
	v_cvt_pk_bf16_f32 v114, v52, v53
	v_cvt_pk_bf16_f32 v115, v82, v83
	s_waitcnt lgkmcnt(0)
	s_nop 0
	v_mfma_f32_32x32x16_bf16 v[0:15], v[112:115], v[108:111], v[0:15]
	ds_read2_b64 v[108:111], v106 offset0:12 offset1:14
	v_cvt_pk_bf16_f32 v112, v56, v57
	v_cvt_pk_bf16_f32 v113, v58, v59
	v_cvt_pk_bf16_f32 v114, v60, v61
	v_cvt_pk_bf16_f32 v115, v62, v63
	s_waitcnt lgkmcnt(0)
	s_nop 0
	v_mfma_f32_32x32x16_bf16 v[0:15], v[112:115], v[108:111], v[0:15]
	s_waitcnt vmcnt(7)
	v_lshlrev_b32_e32 v110, 16, v196
	v_and_b32_e32 v111, 0xffff0000, v196
	s_nop 7
	v_pk_add_f32 v[0:1], v[0:1], v[110:111]
	v_lshlrev_b32_e32 v108, 16, v197
	v_and_b32_e32 v109, 0xffff0000, v197
	v_pk_add_f32 v[2:3], v[2:3], v[108:109]
	v_mul_f32_e32 v108, v1, v1
	v_pk_fma_f32 v[108:109], v[0:1], v[0:1], v[108:109] op_sel_hi:[1,1,0]
	v_cvt_pk_bf16_f32 v0, v0, v1
	v_cvt_pk_bf16_f32 v1, v2, v3
	global_store_dwordx2 v[104:105], v[0:1], off offset:1536
	v_mul_f32_e32 v110, v3, v3
	v_pk_fma_f32 v[110:111], v[2:3], v[2:3], v[110:111] op_sel_hi:[1,1,0]
	s_waitcnt vmcnt(7)
	v_lshlrev_b32_e32 v2, 16, v198
	v_and_b32_e32 v3, 0xffff0000, v198
	v_lshlrev_b32_e32 v0, 16, v199
	v_and_b32_e32 v1, 0xffff0000, v199
	v_pk_add_f32 v[2:3], v[4:5], v[2:3]
	v_pk_add_f32 v[0:1], v[6:7], v[0:1]
	v_mul_f32_e32 v4, v3, v3
	v_mul_f32_e32 v6, v1, v1
	v_pk_fma_f32 v[4:5], v[2:3], v[2:3], v[4:5] op_sel_hi:[1,1,0]
	v_pk_fma_f32 v[6:7], v[0:1], v[0:1], v[6:7] op_sel_hi:[1,1,0]
	v_cvt_pk_bf16_f32 v2, v2, v3
	v_cvt_pk_bf16_f32 v3, v0, v1
	v_pk_add_f32 v[4:5], v[4:5], v[6:7]
	global_store_dwordx2 v[98:99], v[2:3], off offset:16
	v_pk_add_f32 v[108:109], v[108:109], v[110:111]
	s_waitcnt vmcnt(7)
	v_lshlrev_b32_e32 v2, 16, v200
	v_and_b32_e32 v3, 0xffff0000, v200
	v_pk_add_f32 v[2:3], v[8:9], v[2:3]
	v_lshlrev_b32_e32 v0, 16, v201
	v_and_b32_e32 v1, 0xffff0000, v201
	v_pk_add_f32 v[6:7], v[10:11], v[0:1]
	v_mul_f32_e32 v0, v3, v3
	v_pk_fma_f32 v[0:1], v[2:3], v[2:3], v[0:1] op_sel_hi:[1,1,0]
	v_cvt_pk_bf16_f32 v2, v2, v3
	v_cvt_pk_bf16_f32 v3, v6, v7
	global_store_dwordx2 v[98:99], v[2:3], off offset:32
	v_mul_f32_e32 v8, v7, v7
	v_pk_fma_f32 v[8:9], v[6:7], v[6:7], v[8:9] op_sel_hi:[1,1,0]
	v_pk_add_f32 v[4:5], v[108:109], v[4:5]
	v_pk_add_f32 v[0:1], v[0:1], v[8:9]
	s_nop 0
	v_pk_add_f32 v[0:1], v[4:5], v[0:1]
	s_waitcnt vmcnt(7)
	v_lshlrev_b32_e32 v4, 16, v202
	v_and_b32_e32 v5, 0xffff0000, v202
	v_lshlrev_b32_e32 v2, 16, v203
	v_and_b32_e32 v3, 0xffff0000, v203
	v_pk_add_f32 v[4:5], v[12:13], v[4:5]
	v_pk_add_f32 v[2:3], v[14:15], v[2:3]
	v_mul_f32_e32 v6, v5, v5
	v_mul_f32_e32 v8, v3, v3
	v_pk_fma_f32 v[6:7], v[4:5], v[4:5], v[6:7] op_sel_hi:[1,1,0]
	v_pk_fma_f32 v[8:9], v[2:3], v[2:3], v[8:9] op_sel_hi:[1,1,0]
	s_nop 0
	v_pk_add_f32 v[6:7], v[6:7], v[8:9]
	s_nop 0
	v_pk_add_f32 v[112:113], v[0:1], v[6:7]
	v_cvt_pk_bf16_f32 v0, v4, v5
	v_cvt_pk_bf16_f32 v1, v2, v3
	global_store_dwordx2 v[98:99], v[0:1], off offset:48
	v_add_u32_e32 v4, 0x4000, v107
	ds_read2_b64 v[0:3], v4 offset0:64 offset1:66
	ds_read2_b64 v[108:111], v4 offset0:68 offset1:70
	s_waitcnt lgkmcnt(1)
	v_mfma_f32_32x32x16_bf16 v[0:15], v[0:3], v[16:19], 0
	s_waitcnt lgkmcnt(0)
	v_mfma_f32_32x32x16_bf16 v[0:15], v[108:111], v[20:23], v[0:15]
	v_cvt_pk_bf16_f32 v108, v26, v27
	v_cvt_pk_bf16_f32 v109, v28, v29
	v_cvt_pk_bf16_f32 v110, v30, v31
	v_cvt_pk_bf16_f32 v111, v48, v49
	ds_read2_b64 v[16:19], v106 offset1:2
	ds_read2_b64 v[20:23], v106 offset0:4 offset1:6
	s_waitcnt lgkmcnt(1)
	v_mfma_f32_32x32x16_bf16 v[0:15], v[108:111], v[16:19], v[0:15]
	v_cvt_pk_bf16_f32 v16, v24, v25
	v_cvt_pk_bf16_f32 v17, v84, v85
	v_cvt_pk_bf16_f32 v18, v86, v87
	v_cvt_pk_bf16_f32 v19, v96, v97
	s_waitcnt lgkmcnt(0)
	s_nop 0
	v_mfma_f32_32x32x16_bf16 v[0:15], v[16:19], v[20:23], v[0:15]
	ds_read2_b64 v[16:19], v106 offset0:8 offset1:10
	v_cvt_pk_bf16_f32 v20, v66, v67
	v_cvt_pk_bf16_f32 v21, v68, v69
	v_cvt_pk_bf16_f32 v22, v70, v71
	v_cvt_pk_bf16_f32 v23, v72, v73
	s_waitcnt lgkmcnt(0)
	s_nop 0
	v_mfma_f32_32x32x16_bf16 v[0:15], v[20:23], v[16:19], v[0:15]
	ds_read2_b64 v[16:19], v106 offset0:12 offset1:14
	v_cvt_pk_bf16_f32 v20, v74, v75
	v_cvt_pk_bf16_f32 v21, v76, v77
	v_cvt_pk_bf16_f32 v22, v78, v79
	v_cvt_pk_bf16_f32 v23, v80, v81
	s_waitcnt lgkmcnt(0)
	s_nop 0
	v_mfma_f32_32x32x16_bf16 v[0:15], v[20:23], v[16:19], v[0:15]
	s_waitcnt vmcnt(7)
	v_lshlrev_b32_e32 v18, 16, v230
	v_and_b32_e32 v19, 0xffff0000, v230
	s_nop 7
	v_pk_add_f32 v[0:1], v[0:1], v[18:19]
	v_lshlrev_b32_e32 v16, 16, v231
	v_and_b32_e32 v17, 0xffff0000, v231
	v_pk_add_f32 v[2:3], v[2:3], v[16:17]
	v_mul_f32_e32 v16, v1, v1
	v_pk_fma_f32 v[16:17], v[0:1], v[0:1], v[16:17] op_sel_hi:[1,1,0]
	v_cvt_pk_bf16_f32 v0, v0, v1
	v_cvt_pk_bf16_f32 v1, v2, v3
	global_store_dwordx2 v[98:99], v[0:1], off offset:64
	v_mul_f32_e32 v18, v3, v3
	v_pk_fma_f32 v[18:19], v[2:3], v[2:3], v[18:19] op_sel_hi:[1,1,0]
	s_waitcnt vmcnt(7)
	v_lshlrev_b32_e32 v2, 16, v232
	v_and_b32_e32 v3, 0xffff0000, v232
	v_lshlrev_b32_e32 v0, 16, v233
	v_and_b32_e32 v1, 0xffff0000, v233
	v_pk_add_f32 v[2:3], v[4:5], v[2:3]
	v_pk_add_f32 v[0:1], v[6:7], v[0:1]
	v_mul_f32_e32 v4, v3, v3
	v_mul_f32_e32 v6, v1, v1
	v_pk_fma_f32 v[4:5], v[2:3], v[2:3], v[4:5] op_sel_hi:[1,1,0]
	v_pk_fma_f32 v[6:7], v[0:1], v[0:1], v[6:7] op_sel_hi:[1,1,0]
	v_cvt_pk_bf16_f32 v2, v2, v3
	v_cvt_pk_bf16_f32 v3, v0, v1
	v_pk_add_f32 v[4:5], v[4:5], v[6:7]
	global_store_dwordx2 v[98:99], v[2:3], off offset:80
	v_pk_add_f32 v[16:17], v[16:17], v[18:19]
	s_waitcnt vmcnt(7)
	v_lshlrev_b32_e32 v2, 16, v234
	v_and_b32_e32 v3, 0xffff0000, v234
	v_lshlrev_b32_e32 v0, 16, v235
	v_and_b32_e32 v1, 0xffff0000, v235
	v_pk_add_f32 v[2:3], v[8:9], v[2:3]
	v_pk_add_f32 v[6:7], v[10:11], v[0:1]
	v_mov_b32_e32 v0, v2
	v_mov_b32_e32 v8, v3
	v_cvt_pk_bf16_f32 v2, v2, v3
	v_cvt_pk_bf16_f32 v3, v6, v7
	global_store_dwordx2 v[98:99], v[2:3], off offset:96
	v_mov_b32_e32 v9, v7
	v_mov_b32_e32 v1, v6
	v_pk_mul_f32 v[8:9], v[8:9], v[8:9]
	v_pk_add_f32 v[16:17], v[112:113], v[16:17]
	v_pk_fma_f32 v[0:1], v[0:1], v[0:1], v[8:9]
	v_pk_add_f32 v[4:5], v[16:17], v[4:5]
	v_pk_add_f32 v[0:1], v[0:1], v[0:1] op_sel:[0,1] op_sel_hi:[1,0]
	s_nop 0
	v_pk_add_f32 v[0:1], v[4:5], v[0:1]
	s_waitcnt vmcnt(7)
	v_lshlrev_b32_e32 v4, 16, v240
	v_and_b32_e32 v5, 0xffff0000, v240
	v_lshlrev_b32_e32 v2, 16, v241
	v_and_b32_e32 v3, 0xffff0000, v241
	v_pk_add_f32 v[4:5], v[12:13], v[4:5]
	v_pk_add_f32 v[2:3], v[14:15], v[2:3]
	v_mov_b32_e32 v8, v5
	v_mov_b32_e32 v9, v3
	v_mov_b32_e32 v6, v4
	v_mov_b32_e32 v7, v2
	v_pk_mul_f32 v[8:9], v[8:9], v[8:9]
	s_nop 0
	v_pk_fma_f32 v[6:7], v[6:7], v[6:7], v[8:9]
	s_nop 0
	v_pk_add_f32 v[6:7], v[6:7], v[6:7] op_sel:[0,1] op_sel_hi:[1,0]
	s_nop 0
	v_pk_add_f32 v[114:115], v[0:1], v[6:7]
	v_cvt_pk_bf16_f32 v0, v4, v5
	v_cvt_pk_bf16_f32 v1, v2, v3
	global_store_dwordx2 v[98:99], v[0:1], off offset:112
	v_add_u32_e32 v95, v92, v95
	v_mad_u32_u24 v115, v118, s0, v95
	ds_read_b128 v[0:3], v95 offset:19456
	ds_read_b128 v[4:7], v95 offset:19488
	ds_read_b128 v[8:11], v95 offset:19520
	ds_read_b128 v[12:15], v95 offset:19552
	ds_read_b128 v[16:19], v115 offset:9216
	ds_read_b128 v[20:23], v115 offset:14336
	ds_read_b128 v[106:109], v115 offset:9248
	ds_read_b128 v[110:113], v115 offset:14368
	ds_read_b128 v[118:121], v115 offset:16896
	s_waitcnt lgkmcnt(8)
	v_pk_mul_f32 v[34:35], v[2:3], v[34:35]
	v_pk_mul_f32 v[32:33], v[0:1], v[32:33]
	s_waitcnt lgkmcnt(7)
	v_pk_mul_f32 v[38:39], v[6:7], v[38:39]
	v_pk_mul_f32 v[36:37], v[4:5], v[36:37]
	s_waitcnt lgkmcnt(6)
	v_pk_mul_f32 v[42:43], v[10:11], v[42:43]
	v_pk_mul_f32 v[40:41], v[8:9], v[40:41]
	s_waitcnt lgkmcnt(5)
	v_pk_mul_f32 v[46:47], v[14:15], v[46:47]
	v_pk_mul_f32 v[44:45], v[12:13], v[44:45]
	v_pk_mul_f32 v[0:1], v[0:1], v[26:27]
	v_pk_mul_f32 v[2:3], v[2:3], v[28:29]
	v_pk_mul_f32 v[4:5], v[4:5], v[30:31]
	v_pk_mul_f32 v[6:7], v[6:7], v[48:49]
	v_pk_mul_f32 v[8:9], v[8:9], v[24:25]
	v_pk_mul_f32 v[10:11], v[10:11], v[84:85]
	v_pk_mul_f32 v[12:13], v[12:13], v[86:87]
	v_pk_mul_f32 v[14:15], v[14:15], v[96:97]
	s_waitcnt lgkmcnt(3)
	v_mfma_f32_32x32x16_bf16 v[32:47], v[16:19], v[20:23], v[32:47]
	ds_read_b128 v[84:87], v115 offset:16928
	s_movk_i32 s4, 0x50
	s_waitcnt lgkmcnt(1)
	v_mfma_f32_32x32x16_bf16 v[0:15], v[16:19], v[118:121], v[0:15]
	v_mfma_f32_32x32x16_bf16 v[32:47], v[106:109], v[110:113], v[32:47]
	s_waitcnt lgkmcnt(0)
	v_mfma_f32_32x32x16_bf16 v[0:15], v[106:109], v[84:87], v[0:15]
	ds_read_b128 v[16:19], v95 offset:19584
	ds_read_b128 v[24:27], v95 offset:19616
	ds_read_b128 v[28:31], v95 offset:19648
	ds_read_b128 v[106:109], v95 offset:19680
	ds_read_b128 v[122:125], v115 offset:11776
	s_waitcnt lgkmcnt(4)
	v_pk_mul_f32 v[50:51], v[18:19], v[50:51]
	v_pk_mul_f32 v[48:49], v[16:17], v[54:55]
	s_waitcnt lgkmcnt(3)
	v_pk_mul_f32 v[54:55], v[26:27], v[82:83]
	v_pk_mul_f32 v[52:53], v[24:25], v[52:53]
	s_waitcnt lgkmcnt(2)
	v_pk_mul_f32 v[58:59], v[30:31], v[58:59]
	v_pk_mul_f32 v[56:57], v[28:29], v[56:57]
	s_waitcnt lgkmcnt(1)
	v_pk_mul_f32 v[62:63], v[108:109], v[62:63]
	v_pk_mul_f32 v[60:61], v[106:107], v[60:61]
	ds_read_b128 v[126:129], v115 offset:11808
	v_pk_mul_f32 v[16:17], v[16:17], v[66:67]
	s_waitcnt lgkmcnt(1)
	v_mfma_f32_32x32x16_bf16 v[48:63], v[122:125], v[20:23], v[48:63]
	v_mul_f32_e64 v18, v18, v68
	v_mul_f32_e64 v19, v19, v69
	v_mul_f32_e64 v20, v24, v70
	v_mul_f32_e64 v21, v25, v71
	v_mul_f32_e64 v22, v26, v72
	v_mul_f32_e64 v23, v27, v73
	v_pk_mul_f32 v[24:25], v[28:29], v[74:75]
	v_pk_mul_f32 v[26:27], v[30:31], v[76:77]
	v_pk_mul_f32 v[28:29], v[106:107], v[78:79]
	v_pk_mul_f32 v[30:31], v[108:109], v[80:81]
	s_waitcnt lgkmcnt(0)
	s_waitcnt lgkmcnt(0)
	v_mfma_f32_32x32x16_bf16 v[48:63], v[126:129], v[110:113], v[48:63]
	v_mfma_f32_32x32x16_bf16 v[16:31], v[122:125], v[118:121], v[16:31]
	v_mfma_f32_32x32x16_bf16 v[16:31], v[126:129], v[84:87], v[16:31]
	v_mad_i64_i32 v[64:65], s[2:3], v88, s1, v[64:65]
	v_lshl_add_u64 v[64:65], v[64:65], 0, v[90:91]
	v_lshl_add_u64 v[64:65], v[64:65], 0, v[102:103]
	s_mov_b64 s[48:49], 0x1000
	s_movk_i32 s5, 0x1000
	v_lshl_add_u64 v[72:73], v[64:65], 0, s[48:49]
	v_add_co_u32_e32 v64, vcc, s5, v64
	global_load_dwordx2 v[74:75], v[104:105], off offset:1536
	s_nop 0
	v_addc_co_u32_e32 v65, vcc, 0, v65, vcc
	global_load_dwordx2 v[76:77], v[64:65], off
	v_readlane_b32 s0, v255, 18
	v_readlane_b32 s1, v255, 19
	s_add_u32 s2, s40, s0
	v_mov_b32_e32 v66, v114
	s_addc_u32 s3, s41, s1
	s_nop 0
	v_permlane32_swap_b32_e32 v114, v66
	v_lshl_add_u64 v[64:65], v[100:101], 2, s[2:3]
	s_mov_b64 s[2:3], 0x4800
	v_add_f32_e32 v66, v114, v66
	v_lshl_add_u64 v[70:71], v[64:65], 0, s[2:3]
	v_add_co_u32_e32 v64, vcc, s7, v64
	v_fmamk_f32 v66, v66, 0x3c800000, v237
	s_nop 0
	v_addc_co_u32_e32 v65, vcc, 0, v65, vcc
	v_rsq_f32_e32 v68, v66
	global_load_dwordx4 v[64:67], v[64:65], off offset:2048
	global_load_dwordx4 v[206:209], v[70:71], off offset:32
	global_load_dwordx2 v[210:211], v[72:73], off offset:16
	global_load_dwordx2 v[212:213], v[98:99], off offset:16
	global_load_dwordx4 v[214:217], v[70:71], off offset:64
	global_load_dwordx2 v[218:219], v[72:73], off offset:32
	global_load_dwordx2 v[220:221], v[98:99], off offset:32
	global_load_dwordx4 v[222:225], v[70:71], off offset:96
	global_load_dwordx2 v[226:227], v[72:73], off offset:48
	global_load_dwordx2 v[228:229], v[98:99], off offset:48
	s_movk_i32 s6, 0x1200
	s_waitcnt vmcnt(11)
	v_lshlrev_b32_e32 v82, 16, v74
	v_and_b32_e32 v83, 0xffff0000, v74
	v_lshlrev_b32_e32 v74, 16, v75
	s_waitcnt vmcnt(10)
	v_lshlrev_b32_e32 v78, 16, v76
	v_mul_f32_e32 v69, 0xbfb8aa3b, v78
	v_exp_f32_e32 v69, v69
	v_and_b32_e32 v79, 0xffff0000, v76
	v_lshlrev_b32_e32 v76, 16, v77
	v_and_b32_e32 v77, 0xffff0000, v77
	v_add_f32_e32 v69, 1.0, v69
	v_rcp_f32_e32 v80, v69
	v_mul_f32_e32 v69, 0xbfb8aa3b, v79
	v_exp_f32_e32 v69, v69
	v_and_b32_e32 v75, 0xffff0000, v75
	v_add_f32_e32 v69, 1.0, v69
	v_rcp_f32_e32 v81, v69
	v_pk_mul_f32 v[82:83], v[68:69], v[82:83] op_sel_hi:[0,1]
	v_pk_mul_f32 v[74:75], v[68:69], v[74:75] op_sel_hi:[0,1]
	s_waitcnt vmcnt(9)
	v_pk_mul_f32 v[64:65], v[64:65], v[82:83]
	v_pk_mul_f32 v[78:79], v[80:81], v[78:79]
	v_pk_mul_f32 v[66:67], v[66:67], v[74:75]
	v_pk_mul_f32 v[64:65], v[64:65], v[78:79]
	s_nop 0
	v_cvt_pk_bf16_f32 v64, v64, v65
	v_mul_f32_e32 v65, 0xbfb8aa3b, v76
	v_exp_f32_e32 v65, v65
	s_nop 0
	v_add_f32_e32 v65, 1.0, v65
	v_rcp_f32_e32 v78, v65
	v_mul_f32_e32 v65, 0xbfb8aa3b, v77
	v_exp_f32_e32 v65, v65
	s_nop 0
	v_add_f32_e32 v65, 1.0, v65
	v_rcp_f32_e32 v79, v65
	s_nop 0
	v_pk_mul_f32 v[74:75], v[78:79], v[76:77]
	s_nop 0
	v_pk_mul_f32 v[66:67], v[66:67], v[74:75]
	s_nop 0
	v_cvt_pk_bf16_f32 v65, v66, v67
	global_store_dwordx2 v[104:105], v[64:65], off offset:1536
	s_nop 0
	s_waitcnt vmcnt(8)
	v_lshlrev_b32_e32 v78, 16, v210
	v_mul_f32_e32 v69, 0xbfb8aa3b, v78
	v_exp_f32_e32 v69, v69
	v_and_b32_e32 v79, 0xffff0000, v210
	s_waitcnt vmcnt(7)
	v_lshlrev_b32_e32 v82, 16, v212
	v_and_b32_e32 v83, 0xffff0000, v212
	v_add_f32_e32 v69, 1.0, v69
	v_rcp_f32_e32 v80, v69
	v_mul_f32_e32 v69, 0xbfb8aa3b, v79
	v_exp_f32_e32 v69, v69
	v_lshlrev_b32_e32 v74, 16, v211
	v_and_b32_e32 v75, 0xffff0000, v211
	v_lshlrev_b32_e32 v76, 16, v213
	v_add_f32_e32 v69, 1.0, v69
	v_rcp_f32_e32 v81, v69
	v_pk_mul_f32 v[82:83], v[68:69], v[82:83] op_sel_hi:[0,1]
	v_pk_mul_f32 v[64:65], v[206:207], v[82:83]
	v_and_b32_e32 v77, 0xffff0000, v213
	v_pk_mul_f32 v[78:79], v[80:81], v[78:79]
	v_pk_mul_f32 v[76:77], v[68:69], v[76:77] op_sel_hi:[0,1]
	v_pk_mul_f32 v[64:65], v[64:65], v[78:79]
	v_pk_mul_f32 v[66:67], v[208:209], v[76:77]
	v_cvt_pk_bf16_f32 v64, v64, v65
	v_mul_f32_e32 v65, 0xbfb8aa3b, v74
	v_exp_f32_e32 v65, v65
	s_nop 0
	v_add_f32_e32 v65, 1.0, v65
	v_rcp_f32_e32 v78, v65
	v_mul_f32_e32 v65, 0xbfb8aa3b, v75
	v_exp_f32_e32 v65, v65
	s_nop 0
	v_add_f32_e32 v65, 1.0, v65
	v_rcp_f32_e32 v79, v65
	s_nop 0
	v_pk_mul_f32 v[74:75], v[78:79], v[74:75]
	s_nop 0
	v_pk_mul_f32 v[66:67], v[66:67], v[74:75]
	s_nop 0
	v_cvt_pk_bf16_f32 v65, v66, v67
	global_store_dwordx2 v[98:99], v[64:65], off offset:16
	s_nop 0
	s_waitcnt vmcnt(6)
	v_lshlrev_b32_e32 v78, 16, v218
	v_mul_f32_e32 v69, 0xbfb8aa3b, v78
	v_exp_f32_e32 v69, v69
	v_and_b32_e32 v79, 0xffff0000, v218
	s_waitcnt vmcnt(5)
	v_lshlrev_b32_e32 v82, 16, v220
	v_and_b32_e32 v83, 0xffff0000, v220
	v_add_f32_e32 v69, 1.0, v69
	v_rcp_f32_e32 v80, v69
	v_mul_f32_e32 v69, 0xbfb8aa3b, v79
	v_exp_f32_e32 v69, v69
	v_lshlrev_b32_e32 v74, 16, v219
	v_and_b32_e32 v75, 0xffff0000, v219
	v_lshlrev_b32_e32 v76, 16, v221
	v_add_f32_e32 v69, 1.0, v69
	v_rcp_f32_e32 v81, v69
	v_pk_mul_f32 v[82:83], v[68:69], v[82:83] op_sel_hi:[0,1]
	v_pk_mul_f32 v[64:65], v[214:215], v[82:83]
	v_and_b32_e32 v77, 0xffff0000, v221
	v_pk_mul_f32 v[78:79], v[80:81], v[78:79]
	v_pk_mul_f32 v[76:77], v[68:69], v[76:77] op_sel_hi:[0,1]
	v_pk_mul_f32 v[64:65], v[64:65], v[78:79]
	v_pk_mul_f32 v[66:67], v[216:217], v[76:77]
	v_cvt_pk_bf16_f32 v64, v64, v65
	v_mul_f32_e32 v65, 0xbfb8aa3b, v74
	v_exp_f32_e32 v65, v65
	s_nop 0
	v_add_f32_e32 v65, 1.0, v65
	v_rcp_f32_e32 v78, v65
	v_mul_f32_e32 v65, 0xbfb8aa3b, v75
	v_exp_f32_e32 v65, v65
	s_nop 0
	v_add_f32_e32 v65, 1.0, v65
	v_rcp_f32_e32 v79, v65
	s_nop 0
	v_pk_mul_f32 v[74:75], v[78:79], v[74:75]
	s_nop 0
	v_pk_mul_f32 v[66:67], v[66:67], v[74:75]
	s_nop 0
	v_cvt_pk_bf16_f32 v65, v66, v67
	global_store_dwordx2 v[98:99], v[64:65], off offset:32
	s_nop 0
	s_waitcnt vmcnt(4)
	v_lshlrev_b32_e32 v78, 16, v226
	v_mul_f32_e32 v69, 0xbfb8aa3b, v78
	v_exp_f32_e32 v69, v69
	v_and_b32_e32 v79, 0xffff0000, v226
	s_waitcnt vmcnt(3)
	v_lshlrev_b32_e32 v82, 16, v228
	v_and_b32_e32 v83, 0xffff0000, v228
	v_add_f32_e32 v69, 1.0, v69
	v_rcp_f32_e32 v80, v69
	v_mul_f32_e32 v69, 0xbfb8aa3b, v79
	v_exp_f32_e32 v69, v69
	v_lshlrev_b32_e32 v74, 16, v227
	v_and_b32_e32 v75, 0xffff0000, v227
	v_lshlrev_b32_e32 v76, 16, v229
	v_add_f32_e32 v69, 1.0, v69
	v_rcp_f32_e32 v81, v69
	v_pk_mul_f32 v[82:83], v[68:69], v[82:83] op_sel_hi:[0,1]
	v_pk_mul_f32 v[64:65], v[222:223], v[82:83]
	v_and_b32_e32 v77, 0xffff0000, v229
	v_pk_mul_f32 v[78:79], v[80:81], v[78:79]
	v_pk_mul_f32 v[76:77], v[68:69], v[76:77] op_sel_hi:[0,1]
	v_pk_mul_f32 v[64:65], v[64:65], v[78:79]
	v_pk_mul_f32 v[66:67], v[224:225], v[76:77]
	v_cvt_pk_bf16_f32 v64, v64, v65
	v_mul_f32_e32 v65, 0xbfb8aa3b, v74
	v_exp_f32_e32 v65, v65
	s_nop 0
	v_add_f32_e32 v65, 1.0, v65
	v_rcp_f32_e32 v78, v65
	v_mul_f32_e32 v65, 0xbfb8aa3b, v75
	v_exp_f32_e32 v65, v65
	s_nop 0
	v_add_f32_e32 v65, 1.0, v65
	v_rcp_f32_e32 v79, v65
	s_nop 0
	v_pk_mul_f32 v[74:75], v[78:79], v[74:75]
	s_nop 0
	v_pk_mul_f32 v[66:67], v[66:67], v[74:75]
	s_nop 0
	v_cvt_pk_bf16_f32 v65, v66, v67
	global_store_dwordx2 v[98:99], v[64:65], off offset:48
	global_load_dwordx2 v[74:75], v[98:99], off offset:64
	global_load_dwordx2 v[76:77], v[72:73], off offset:64
	global_load_dwordx4 v[64:67], v[70:71], off offset:128
	global_load_dwordx2 v[212:213], v[98:99], off offset:80
	global_load_dwordx2 v[210:211], v[72:73], off offset:80
	global_load_dwordx4 v[206:209], v[70:71], off offset:160
	global_load_dwordx2 v[220:221], v[98:99], off offset:96
	global_load_dwordx2 v[218:219], v[72:73], off offset:96
	global_load_dwordx4 v[214:217], v[70:71], off offset:192
	global_load_dwordx2 v[228:229], v[98:99], off offset:112
	global_load_dwordx2 v[226:227], v[72:73], off offset:112
	global_load_dwordx4 v[222:225], v[70:71], off offset:224
	s_waitcnt vmcnt(11)
	v_lshlrev_b32_e32 v82, 16, v74
	s_waitcnt vmcnt(10)
	v_lshlrev_b32_e32 v78, 16, v76
	v_mul_f32_e32 v69, 0xbfb8aa3b, v78
	v_exp_f32_e32 v69, v69
	v_and_b32_e32 v79, 0xffff0000, v76
	v_and_b32_e32 v83, 0xffff0000, v74
	v_lshlrev_b32_e32 v76, 16, v77
	v_add_f32_e32 v69, 1.0, v69
	v_rcp_f32_e32 v80, v69
	v_mul_f32_e32 v69, 0xbfb8aa3b, v79
	v_exp_f32_e32 v69, v69
	v_and_b32_e32 v77, 0xffff0000, v77
	v_lshlrev_b32_e32 v74, 16, v75
	v_and_b32_e32 v75, 0xffff0000, v75
	v_add_f32_e32 v69, 1.0, v69
	v_rcp_f32_e32 v81, v69
	v_pk_mul_f32 v[82:83], v[68:69], v[82:83] op_sel_hi:[0,1]
	s_waitcnt vmcnt(9)
	v_pk_mul_f32 v[64:65], v[64:65], v[82:83]
	v_pk_mul_f32 v[74:75], v[68:69], v[74:75] op_sel_hi:[0,1]
	v_pk_mul_f32 v[78:79], v[80:81], v[78:79]
	v_pk_mul_f32 v[66:67], v[66:67], v[74:75]
	v_pk_mul_f32 v[64:65], v[64:65], v[78:79]
	s_nop 0
	v_cvt_pk_bf16_f32 v64, v64, v65
	v_mul_f32_e32 v65, 0xbfb8aa3b, v76
	v_exp_f32_e32 v65, v65
	s_nop 0
	v_add_f32_e32 v65, 1.0, v65
	v_rcp_f32_e32 v78, v65
	v_mul_f32_e32 v65, 0xbfb8aa3b, v77
	v_exp_f32_e32 v65, v65
	s_nop 0
	v_add_f32_e32 v65, 1.0, v65
	v_rcp_f32_e32 v79, v65
	s_nop 0
	v_pk_mul_f32 v[74:75], v[78:79], v[76:77]
	s_nop 0
	v_pk_mul_f32 v[66:67], v[66:67], v[74:75]
	s_nop 0
	v_cvt_pk_bf16_f32 v65, v66, v67
	global_store_dwordx2 v[98:99], v[64:65], off offset:64
	s_nop 0
	s_waitcnt vmcnt(9)
	v_lshlrev_b32_e32 v82, 16, v212
	s_waitcnt vmcnt(8)
	v_lshlrev_b32_e32 v78, 16, v210
	v_mul_f32_e32 v69, 0xbfb8aa3b, v78
	v_exp_f32_e32 v69, v69
	v_and_b32_e32 v79, 0xffff0000, v210
	v_and_b32_e32 v83, 0xffff0000, v212
	v_lshlrev_b32_e32 v76, 16, v211
	v_add_f32_e32 v69, 1.0, v69
	v_rcp_f32_e32 v80, v69
	v_mul_f32_e32 v69, 0xbfb8aa3b, v79
	v_exp_f32_e32 v69, v69
	v_and_b32_e32 v77, 0xffff0000, v211
	v_lshlrev_b32_e32 v74, 16, v213
	v_and_b32_e32 v75, 0xffff0000, v213
	v_add_f32_e32 v69, 1.0, v69
	v_rcp_f32_e32 v81, v69
	v_pk_mul_f32 v[82:83], v[68:69], v[82:83] op_sel_hi:[0,1]
	s_waitcnt vmcnt(7)
	v_pk_mul_f32 v[64:65], v[206:207], v[82:83]
	v_pk_mul_f32 v[74:75], v[68:69], v[74:75] op_sel_hi:[0,1]
	v_pk_mul_f32 v[78:79], v[80:81], v[78:79]
	v_pk_mul_f32 v[66:67], v[208:209], v[74:75]
	v_pk_mul_f32 v[64:65], v[64:65], v[78:79]
	s_nop 0
	v_cvt_pk_bf16_f32 v64, v64, v65
	v_mul_f32_e32 v65, 0xbfb8aa3b, v76
	v_exp_f32_e32 v65, v65
	s_nop 0
	v_add_f32_e32 v65, 1.0, v65
	v_rcp_f32_e32 v78, v65
	v_mul_f32_e32 v65, 0xbfb8aa3b, v77
	v_exp_f32_e32 v65, v65
	s_nop 0
	v_add_f32_e32 v65, 1.0, v65
	v_rcp_f32_e32 v79, v65
	s_nop 0
	v_pk_mul_f32 v[74:75], v[78:79], v[76:77]
	s_nop 0
	v_pk_mul_f32 v[66:67], v[66:67], v[74:75]
	s_nop 0
	v_cvt_pk_bf16_f32 v65, v66, v67
	global_store_dwordx2 v[98:99], v[64:65], off offset:80
	s_nop 0
	s_waitcnt vmcnt(7)
	v_lshlrev_b32_e32 v82, 16, v220
	s_waitcnt vmcnt(6)
	v_lshlrev_b32_e32 v78, 16, v218
	v_mul_f32_e32 v69, 0xbfb8aa3b, v78
	v_exp_f32_e32 v69, v69
	v_and_b32_e32 v79, 0xffff0000, v218
	v_and_b32_e32 v83, 0xffff0000, v220
	v_lshlrev_b32_e32 v76, 16, v219
	v_add_f32_e32 v69, 1.0, v69
	v_rcp_f32_e32 v80, v69
	v_mul_f32_e32 v69, 0xbfb8aa3b, v79
	v_exp_f32_e32 v69, v69
	v_and_b32_e32 v77, 0xffff0000, v219
	v_lshlrev_b32_e32 v74, 16, v221
	v_and_b32_e32 v75, 0xffff0000, v221
	v_add_f32_e32 v69, 1.0, v69
	v_rcp_f32_e32 v81, v69
	v_pk_mul_f32 v[82:83], v[68:69], v[82:83] op_sel_hi:[0,1]
	s_waitcnt vmcnt(5)
	v_pk_mul_f32 v[64:65], v[214:215], v[82:83]
	v_pk_mul_f32 v[74:75], v[68:69], v[74:75] op_sel_hi:[0,1]
	v_pk_mul_f32 v[78:79], v[80:81], v[78:79]
	v_pk_mul_f32 v[66:67], v[216:217], v[74:75]
	v_pk_mul_f32 v[64:65], v[64:65], v[78:79]
	s_nop 0
	v_cvt_pk_bf16_f32 v64, v64, v65
	v_mul_f32_e32 v65, 0xbfb8aa3b, v76
	v_exp_f32_e32 v65, v65
	s_nop 0
	v_add_f32_e32 v65, 1.0, v65
	v_rcp_f32_e32 v78, v65
	v_mul_f32_e32 v65, 0xbfb8aa3b, v77
	v_exp_f32_e32 v65, v65
	s_nop 0
	v_add_f32_e32 v65, 1.0, v65
	v_rcp_f32_e32 v79, v65
	s_nop 0
	v_pk_mul_f32 v[74:75], v[78:79], v[76:77]
	s_nop 0
	v_pk_mul_f32 v[66:67], v[66:67], v[74:75]
	s_nop 0
	v_cvt_pk_bf16_f32 v65, v66, v67
	global_store_dwordx2 v[98:99], v[64:65], off offset:96
	s_nop 0
	s_nop 0
	s_waitcnt vmcnt(5)
	v_lshlrev_b32_e32 v78, 16, v228
	s_waitcnt vmcnt(4)
	v_lshlrev_b32_e32 v74, 16, v226
	v_mul_f32_e32 v69, 0xbfb8aa3b, v74
	v_exp_f32_e32 v69, v69
	v_and_b32_e32 v75, 0xffff0000, v226
	v_lshlrev_b32_e32 v66, 16, v227
	v_and_b32_e32 v79, 0xffff0000, v228
	v_add_f32_e32 v69, 1.0, v69
	v_rcp_f32_e32 v76, v69
	v_mul_f32_e32 v69, 0xbfb8aa3b, v75
	v_exp_f32_e32 v69, v69
	v_and_b32_e32 v67, 0xffff0000, v227
	v_add_f32_e32 v69, 1.0, v69
	v_rcp_f32_e32 v77, v69
	v_pk_mul_f32 v[78:79], v[68:69], v[78:79] op_sel_hi:[0,1]
	v_mul_f32_e32 v69, 0xbfb8aa3b, v66
	v_exp_f32_e32 v69, v69
	s_waitcnt vmcnt(3)
	v_pk_mul_f32 v[70:71], v[222:223], v[78:79]
	v_pk_mul_f32 v[74:75], v[76:77], v[74:75]
	v_add_f32_e32 v69, 1.0, v69
	v_pk_mul_f32 v[70:71], v[70:71], v[74:75]
	v_lshlrev_b32_e32 v74, 16, v229
	v_cvt_pk_bf16_f32 v64, v70, v71
	v_rcp_f32_e32 v70, v69
	v_mul_f32_e32 v69, 0xbfb8aa3b, v67
	v_exp_f32_e32 v69, v69
	v_and_b32_e32 v75, 0xffff0000, v229
	v_add_f32_e32 v69, 1.0, v69
	v_rcp_f32_e32 v71, v69
	v_pk_mul_f32 v[68:69], v[68:69], v[74:75] op_sel_hi:[0,1]
	v_pk_mul_f32 v[68:69], v[224:225], v[68:69]
	v_pk_mul_f32 v[66:67], v[70:71], v[66:67]
	s_nop 0
	v_pk_mul_f32 v[66:67], v[68:69], v[66:67]
	s_nop 0
	v_cvt_pk_bf16_f32 v65, v66, v67
	global_store_dwordx2 v[98:99], v[64:65], off offset:112
	s_add_u32 s2, s12, 0xb200000
	v_and_b32_e32 v114, 31, v94
	v_ashrrev_i32_e32 v115, 5, v94
	s_addc_u32 s3, s13, 0
	v_mov_b64_e32 v[96:97], s[2:3]
	v_mad_i64_i32 v[64:65], s[2:3], v93, s6, v[96:97]
	v_ashrrev_i32_e32 v95, 31, v94
	v_lshl_add_u64 v[64:65], v[64:65], 0, v[90:91]
	v_lshl_add_u64 v[64:65], v[94:95], 1, v[64:65]
	v_add_co_u32_e32 v76, vcc, s37, v64
	s_movk_i32 s2, 0x5000
	s_nop 0
	v_addc_co_u32_e32 v77, vcc, 0, v65, vcc
	global_load_ushort v95, v[76:77], off offset:3072
	global_load_ushort v107, v[76:77], off offset:1536
	v_add_co_u32_e32 v66, vcc, s20, v64
	v_lshl_add_u32 v88, v94, 1, v92
	s_nop 0
	v_addc_co_u32_e32 v67, vcc, 0, v65, vcc
	v_add_co_u32_e32 v68, vcc, s2, v64
	s_movk_i32 s2, 0x7000
	s_nop 0
	v_addc_co_u32_e32 v69, vcc, 0, v65, vcc
	v_add_co_u32_e32 v70, vcc, s2, v64
	s_mov_b32 s2, 0x10000
	s_nop 0
	v_addc_co_u32_e32 v71, vcc, 0, v65, vcc
	v_add_co_u32_e32 v80, vcc, s28, v64
	s_waitcnt vmcnt(0)
	v_lshlrev_b32_e32 v107, 16, v107
	v_addc_co_u32_e32 v81, vcc, 0, v65, vcc
	v_add_co_u32_e32 v82, vcc, s29, v64
	v_readlane_b32 s28, v255, 28
	s_nop 0
	v_addc_co_u32_e32 v83, vcc, 0, v65, vcc
	v_add_co_u32_e32 v84, vcc, s18, v64
	v_readlane_b32 s29, v255, 29
	s_nop 0
	v_addc_co_u32_e32 v85, vcc, 0, v65, vcc
	v_add_co_u32_e32 v86, vcc, s2, v64
	s_mov_b32 s2, 0x14000
	s_nop 0
	v_addc_co_u32_e32 v87, vcc, 0, v65, vcc
	v_add_co_u32_e32 v72, vcc, s51, v64
	s_nop 1
	v_addc_co_u32_e32 v73, vcc, 0, v65, vcc
	v_add_co_u32_e32 v74, vcc, s2, v64
	s_mov_b32 s2, 0x1a000
	s_nop 0
	v_addc_co_u32_e32 v75, vcc, 0, v65, vcc
	v_add_co_u32_e32 v78, vcc, s30, v64
	s_nop 1
	v_addc_co_u32_e32 v79, vcc, 0, v65, vcc
	v_add_co_u32_e32 v98, vcc, s31, v64
	s_mov_b64 s[30:31], 0x4800
	s_nop 0
	v_addc_co_u32_e32 v99, vcc, 0, v65, vcc
	v_add_co_u32_e32 v100, vcc, s34, v64
	s_nop 1
	v_addc_co_u32_e32 v101, vcc, 0, v65, vcc
	v_add_co_u32_e32 v102, vcc, s35, v64
	s_mov_b64 s[34:35], 0x1200
	s_nop 0
	v_addc_co_u32_e32 v103, vcc, 0, v65, vcc
	v_add_co_u32_e32 v104, vcc, s19, v64
	v_readlane_b32 s18, v255, 26
	s_nop 0
	v_addc_co_u32_e32 v105, vcc, 0, v65, vcc
	v_add_co_u32_e32 v118, vcc, s36, v64
	v_readlane_b32 s36, v255, 30
	s_nop 0
	v_addc_co_u32_e32 v119, vcc, 0, v65, vcc
	v_add_co_u32_e32 v108, vcc, s21, v64
	v_readlane_b32 s19, v255, 27
	s_nop 0
	v_addc_co_u32_e32 v109, vcc, 0, v65, vcc
	global_load_ushort v111, v[108:109], off offset:512
	global_load_ushort v106, v[108:109], off offset:1024
	global_load_ushort v113, v[108:109], off offset:2048
	s_nop 0
	global_load_ushort v108, v[76:77], off offset:2048
	global_load_ushort v110, v[118:119], off offset:1536
	global_load_ushort v120, v[118:119], off offset:2560
	global_load_ushort v121, v[102:103], off offset:3584
	global_load_ushort v122, v[104:105], off offset:512
	global_load_ushort v152, v[118:119], off offset:1024
	global_load_ushort v153, v[104:105], off offset:1536
	global_load_ushort v154, v[104:105], off
	global_load_ushort v158, v[102:103], off offset:3072
	global_load_ushort v160, v[102:103], off
	global_load_ushort v165, v[100:101], off offset:3584
	v_lshlrev_b32_e32 v76, 16, v95
	v_max_f32_e32 v76, v76, v76
	v_med3_f32 v76, v76, s9, v244
	v_mul_f32_e32 v76, 0xbfb8aa3b, v76
	v_exp_f32_e32 v95, v76
	v_add_co_u32_e32 v76, vcc, s42, v64
	global_load_ushort v123, v[78:79], off offset:512
	global_load_ushort v124, v[98:99], off offset:1536
	global_load_ushort v126, v[100:101], off offset:2560
	global_load_ushort v166, v[100:101], off offset:2048
	global_load_ushort v168, v[98:99], off offset:2560
	global_load_ushort v171, v[98:99], off offset:1024
	global_load_ushort v167, v[78:79], off offset:1536
	global_load_ushort v163, v[78:79], off
	v_add_f32_e32 v109, 1.0, v95
	v_addc_co_u32_e32 v77, vcc, 0, v65, vcc
	v_rcp_f32_e32 v109, v109
	v_add_co_u32_e32 v134, vcc, s17, v64
	v_readlane_b32 s37, v255, 31
	s_nop 0
	v_addc_co_u32_e32 v135, vcc, 0, v65, vcc
	v_add_co_u32_e32 v132, vcc, s16, v64
	v_fma_f32 v112, v117, v109, v116
	s_nop 0
	v_addc_co_u32_e32 v133, vcc, 0, v65, vcc
	v_max_f32_e32 v150, 0xda24260, v112
	v_add_co_u32_e32 v118, vcc, s2, v64
	v_mul_f32_e32 v95, v95, v109
	v_rcp_f32_e32 v109, v150
	v_addc_co_u32_e32 v119, vcc, 0, v65, vcc
	s_mov_b32 s2, 0x18000
	v_add_co_u32_e32 v136, vcc, s2, v64
	s_mov_b32 s2, 0x16000
	s_nop 0
	v_addc_co_u32_e32 v137, vcc, 0, v65, vcc
	v_mul_f32_e32 v95, v117, v95
	v_mul_f32_e32 v107, v150, v107
	v_add_co_u32_e32 v78, vcc, s2, v64
	v_bfe_u32 v112, v107, 16, 1
	v_mul_f32_e32 v95, v95, v109
	v_addc_co_u32_e32 v79, vcc, 0, v65, vcc
	v_add3_u32 v151, v107, v112, s10
	v_bfe_u32 v107, v95, 16, 1
	v_add_co_u32_e32 v138, vcc, s43, v64
	v_add3_u32 v112, v95, v107, s10
	s_nop 0
	v_addc_co_u32_e32 v139, vcc, 0, v65, vcc
	global_load_ushort v125, v[84:85], off offset:512
	global_load_ushort v127, v[86:87], off offset:1536
	global_load_ushort v128, v[72:73], off offset:2560
	global_load_ushort v129, v[74:75], off offset:3584
	global_load_ushort v157, v[74:75], off offset:3072
	global_load_ushort v155, v[74:75], off
	global_load_ushort v109, v[72:73], off offset:3584
	global_load_ushort v107, v[72:73], off offset:2048
	global_load_ushort v172, v[76:77], off offset:1024
	global_load_ushort v173, v[134:135], off offset:3584
	global_load_ushort v174, v[132:133], off offset:2560
	global_load_ushort v175, v[118:119], off offset:1536
	global_load_ushort v131, v[118:119], off offset:2048
	s_nop 0
	global_load_ushort v132, v[132:133], off offset:3072
	s_nop 0
	global_load_ushort v176, v[134:135], off offset:512
	global_load_ushort v133, v[76:77], off
	global_load_ushort v177, v[118:119], off offset:3072
	global_load_ushort v170, v[136:137], off offset:2048
	global_load_ushort v169, v[136:137], off offset:512
	global_load_ushort v164, v[78:79], off offset:1024
	global_load_ushort v162, v[138:139], off offset:3584
	global_load_ushort v159, v[138:139], off offset:512
	global_load_ushort v135, v[78:79], off
	s_nop 0
	global_load_ushort v137, v[136:137], off offset:1024
	v_add_co_u32_e32 v144, vcc, s44, v64
	global_load_ushort v130, v[64:65], off offset:2560
	global_load_ushort v134, v[66:67], off offset:3584
	global_load_ushort v136, v[68:69], off offset:512
	global_load_ushort v138, v[70:71], off offset:1536
	global_load_ushort v139, v[80:81], off offset:2560
	global_load_ushort v141, v[82:83], off offset:3584
	global_load_ushort v142, v[84:85], off offset:-4096
	global_load_ushort v140, v[68:69], off offset:-4096
	v_addc_co_u32_e32 v145, vcc, 0, v65, vcc
	v_add_co_u32_e32 v100, vcc, s45, v64
	v_readlane_b32 s42, v255, 32
	s_nop 0
	v_addc_co_u32_e32 v101, vcc, 0, v65, vcc
	v_add_co_u32_e32 v102, vcc, s46, v64
	v_readlane_b32 s43, v255, 33
	s_nop 0
	v_addc_co_u32_e32 v103, vcc, 0, v65, vcc
	v_add_co_u32_e32 v104, vcc, s47, v64
	v_readlane_b32 s46, v255, 38
	s_nop 0
	v_addc_co_u32_e32 v105, vcc, 0, v65, vcc
	v_add_co_u32_e32 v98, vcc, s15, v64
	s_waitcnt vmcnt(53)
	v_lshlrev_b32_e32 v111, 16, v111
	v_addc_co_u32_e32 v99, vcc, 0, v65, vcc
	s_waitcnt vmcnt(51)
	v_lshlrev_b32_e32 v113, 16, v113
	s_waitcnt vmcnt(48)
	v_lshlrev_b32_e32 v72, 16, v120
	v_max_f32_e32 v72, v72, v72
	v_med3_f32 v72, v72, s9, v244
	v_mul_f32_e32 v72, 0xbfb8aa3b, v72
	v_exp_f32_e32 v95, v72
	v_add_co_u32_e32 v74, vcc, s14, v64
	v_max_f32_e32 v113, v113, v113
	v_add_f32_e32 v118, 1.0, v95
	v_rcp_f32_e32 v118, v118
	v_addc_co_u32_e32 v75, vcc, 0, v65, vcc
	v_med3_f32 v113, v113, s9, v244
	v_fma_f32 v119, v117, v118, v116
	v_mul_f32_e32 v119, v150, v119
	v_max_f32_e32 v119, 0xda24260, v119
	v_add_co_u32_e32 v76, vcc, s27, v64
	v_rcp_f32_e32 v120, v119
	v_mul_f32_e32 v113, 0xbfb8aa3b, v113
	v_addc_co_u32_e32 v77, vcc, 0, v65, vcc
	v_exp_f32_e32 v113, v113
	v_add_co_u32_e32 v78, vcc, s7, v64
	v_mul_f32_e32 v95, v95, v118
	s_nop 0
	v_addc_co_u32_e32 v79, vcc, 0, v65, vcc
	v_mul_f32_e32 v95, v117, v95
	v_add_co_u32_e32 v72, vcc, s5, v64
	v_mul_f32_e32 v95, v95, v120
	s_nop 0
	v_addc_co_u32_e32 v73, vcc, 0, v65, vcc
	global_load_ushort v156, v[144:145], off offset:2560
	global_load_ushort v148, v[144:145], off offset:3072
	global_load_ushort v149, v[100:101], off offset:2048
	global_load_ushort v147, v[102:103], off offset:1024
	global_load_ushort v146, v[98:99], off offset:3072
	s_nop 0
	global_load_ushort v144, v[74:75], off offset:2048
	global_load_ushort v145, v[76:77], off offset:1024
	global_load_ushort v143, v[72:73], off offset:3072
	v_bfe_u32 v118, v95, 16, 1
	v_add_f32_e32 v120, 1.0, v113
	v_add3_u32 v95, v95, v118, s10
	s_waitcnt vmcnt(53)
	v_lshlrev_b32_e32 v118, 16, v152
	v_rcp_f32_e32 v120, v120
	v_mul_f32_e32 v118, v119, v118
	v_bfe_u32 v150, v118, 16, 1
	v_add3_u32 v118, v118, v150, s10
	ds_write_b16_d16_hi v88, v118 offset:4320
	v_fma_f32 v118, v117, v120, v116
	v_mul_f32_e32 v118, v119, v118
	v_mul_f32_e32 v113, v113, v120
	s_waitcnt vmcnt(52)
	v_lshlrev_b32_e32 v120, 16, v153
	v_max_f32_e32 v118, 0xda24260, v118
	v_max_f32_e32 v120, v120, v120
	v_rcp_f32_e32 v119, v118
	v_med3_f32 v120, v120, s9, v244
	v_mul_f32_e32 v120, 0xbfb8aa3b, v120
	v_exp_f32_e32 v120, v120
	v_mul_f32_e32 v113, v117, v113
	v_mul_f32_e32 v113, v113, v119
	v_bfe_u32 v119, v113, 16, 1
	ds_write_b16_d16_hi v88, v151 offset:4464
	v_add3_u32 v151, v113, v119, s10
	v_add_f32_e32 v113, 1.0, v120
	v_rcp_f32_e32 v113, v113
	v_mul_f32_e32 v111, v118, v111
	v_bfe_u32 v119, v111, 16, 1
	v_add3_u32 v111, v111, v119, s10
	ds_write_b16_d16_hi v88, v111 offset:4176
	v_fma_f32 v111, v117, v113, v116
	s_waitcnt vmcnt(31)
	v_lshlrev_b32_e32 v119, 16, v172
	v_mul_f32_e32 v111, v118, v111
	v_max_f32_e32 v119, v119, v119
	v_max_f32_e32 v111, 0xda24260, v111
	v_med3_f32 v119, v119, s9, v244
	v_rcp_f32_e32 v118, v111
	v_mul_f32_e32 v119, 0xbfb8aa3b, v119
	v_exp_f32_e32 v119, v119
	v_mul_f32_e32 v113, v120, v113
	v_mul_f32_e32 v113, v117, v113
	v_mul_f32_e32 v113, v113, v118
	v_bfe_u32 v118, v113, 16, 1
	v_add_f32_e32 v120, 1.0, v119
	v_add3_u32 v118, v113, v118, s10
	v_lshlrev_b32_e32 v113, 16, v154
	v_rcp_f32_e32 v120, v120
	v_mul_f32_e32 v113, v111, v113
	v_bfe_u32 v150, v113, 16, 1
	v_add3_u32 v113, v113, v150, s10
	ds_write_b16_d16_hi v88, v113 offset:4032
	v_fma_f32 v113, v117, v120, v116
	v_mul_f32_e32 v111, v111, v113
	v_mul_f32_e32 v119, v119, v120
	s_waitcnt vmcnt(25)
	v_lshlrev_b32_e32 v120, 16, v176
	v_max_f32_e32 v111, 0xda24260, v111
	v_max_f32_e32 v120, v120, v120
	v_rcp_f32_e32 v113, v111
	v_med3_f32 v120, v120, s9, v244
	v_mul_f32_e32 v120, 0xbfb8aa3b, v120
	v_exp_f32_e32 v120, v120
	v_mul_f32_e32 v119, v117, v119
	v_mul_f32_e32 v113, v119, v113
	v_bfe_u32 v119, v113, 16, 1
	v_add3_u32 v152, v113, v119, s10
	v_add_f32_e32 v119, 1.0, v120
	v_lshlrev_b32_e32 v113, 16, v173
	v_rcp_f32_e32 v119, v119
	v_mul_f32_e32 v113, v111, v113
	v_bfe_u32 v150, v113, 16, 1
	v_add3_u32 v113, v113, v150, s10
	ds_write_b16_d16_hi v88, v113 offset:3888
	v_fma_f32 v113, v117, v119, v116
	v_mul_f32_e32 v119, v120, v119
	v_lshlrev_b32_e32 v120, 16, v160
	v_mul_f32_e32 v111, v111, v113
	v_max_f32_e32 v120, v120, v120
	v_max_f32_e32 v111, 0xda24260, v111
	v_med3_f32 v120, v120, s9, v244
	v_rcp_f32_e32 v113, v111
	v_mul_f32_e32 v120, 0xbfb8aa3b, v120
	v_exp_f32_e32 v120, v120
	v_mul_f32_e32 v119, v117, v119
	v_mul_f32_e32 v113, v119, v113
	v_bfe_u32 v119, v113, 16, 1
	v_add_f32_e32 v150, 1.0, v120
	v_add3_u32 v119, v113, v119, s10
	v_lshlrev_b32_e32 v113, 16, v158
	v_rcp_f32_e32 v150, v150
	v_mul_f32_e32 v113, v111, v113
	v_bfe_u32 v153, v113, 16, 1
	v_add3_u32 v113, v113, v153, s10
	ds_write_b16_d16_hi v88, v113 offset:3744
	v_fma_f32 v113, v117, v150, v116
	v_mul_f32_e32 v111, v111, v113
	v_mul_f32_e32 v120, v120, v150
	v_lshlrev_b32_e32 v150, 16, v165
	v_max_f32_e32 v111, 0xda24260, v111
	v_max_f32_e32 v150, v150, v150
	v_rcp_f32_e32 v113, v111
	v_med3_f32 v150, v150, s9, v244
	v_mul_f32_e32 v150, 0xbfb8aa3b, v150
	v_exp_f32_e32 v150, v150
	v_mul_f32_e32 v120, v117, v120
	v_mul_f32_e32 v113, v120, v113
	v_bfe_u32 v120, v113, 16, 1
	v_add3_u32 v153, v113, v120, s10
	v_add_f32_e32 v120, 1.0, v150
	v_lshlrev_b32_e32 v113, 16, v174
	v_rcp_f32_e32 v120, v120
	v_mul_f32_e32 v113, v111, v113
	v_bfe_u32 v154, v113, 16, 1
	v_add3_u32 v113, v113, v154, s10
	ds_write_b16_d16_hi v88, v113 offset:3600
	v_fma_f32 v113, v117, v120, v116
	v_mul_f32_e32 v111, v111, v113
	v_max_f32_e32 v111, 0xda24260, v111
	v_rcp_f32_e32 v113, v111
	v_mul_f32_e32 v120, v150, v120
	v_mul_f32_e32 v120, v117, v120
	v_readlane_b32 s47, v255, 39
	v_mul_f32_e32 v113, v120, v113
	v_bfe_u32 v120, v113, 16, 1
	v_add3_u32 v120, v113, v120, s10
	v_lshlrev_b32_e32 v113, 16, v166
	v_mul_f32_e32 v113, v111, v113
	v_bfe_u32 v150, v113, 16, 1
	v_add3_u32 v113, v113, v150, s10
	ds_write_b16_d16_hi v88, v112 offset:9072
	ds_write_b16_d16_hi v88, v95 offset:8928
	ds_write_b16_d16_hi v88, v151 offset:8784
	ds_write_b16_d16_hi v88, v118 offset:8640
	ds_write_b16_d16_hi v88, v152 offset:8496
	ds_write_b16_d16_hi v88, v119 offset:8352
	ds_write_b16_d16_hi v88, v153 offset:8208
	ds_write_b16_d16_hi v88, v113 offset:3456
	ds_write_b16_d16_hi v88, v120 offset:8064
	s_waitcnt vmcnt(23)
	v_lshlrev_b32_e32 v113, 16, v177
	v_max_f32_e32 v113, v113, v113
	v_med3_f32 v113, v113, s9, v244
	v_mul_f32_e32 v113, 0xbfb8aa3b, v113
	v_exp_f32_e32 v113, v113
	v_lshlrev_b32_e32 v107, 16, v107
	v_add_f32_e32 v150, 1.0, v113
	v_rcp_f32_e32 v150, v150
	s_nop 0
	v_fma_f32 v154, v117, v150, v116
	v_mul_f32_e32 v111, v111, v154
	v_max_f32_e32 v111, 0xda24260, v111
	v_mul_f32_e32 v113, v113, v150
	v_rcp_f32_e32 v150, v111
	v_mul_f32_e32 v113, v117, v113
	v_mul_f32_e32 v113, v113, v150
	v_bfe_u32 v150, v113, 16, 1
	v_add3_u32 v154, v113, v150, s10
	v_lshlrev_b32_e32 v113, 16, v175
	v_mul_f32_e32 v113, v111, v113
	v_bfe_u32 v150, v113, 16, 1
	v_add3_u32 v113, v113, v150, s10
	ds_write_b16_d16_hi v88, v113 offset:3312
	ds_write_b16_d16_hi v88, v154 offset:7920
	v_lshlrev_b32_e32 v113, 16, v168
	v_max_f32_e32 v113, v113, v113
	v_med3_f32 v113, v113, s9, v244
	v_mul_f32_e32 v113, 0xbfb8aa3b, v113
	v_exp_f32_e32 v113, v113
	s_nop 0
	v_add_f32_e32 v150, 1.0, v113
	v_rcp_f32_e32 v150, v150
	s_nop 0
	v_fma_f32 v158, v117, v150, v116
	v_mul_f32_e32 v111, v111, v158
	v_max_f32_e32 v172, 0xda24260, v111
	v_rcp_f32_e32 v111, v172
	v_mul_f32_e32 v113, v113, v150
	v_mul_f32_e32 v113, v117, v113
	v_mul_f32_e32 v111, v113, v111
	v_bfe_u32 v113, v111, 16, 1
	v_add3_u32 v150, v111, v113, s10
	v_lshlrev_b32_e32 v111, 16, v171
	v_mul_f32_e32 v111, v172, v111
	v_bfe_u32 v113, v111, 16, 1
	v_add3_u32 v171, v111, v113, s10
	global_load_ushort v168, v[100:101], off offset:3072
	global_load_ushort v166, v[100:101], off offset:1536
	global_load_ushort v165, v[86:87], off offset:2560
	global_load_ushort v160, v[86:87], off offset:1024
	global_load_ushort v158, v[102:103], off offset:2048
	global_load_ushort v113, v[102:103], off offset:512
	global_load_ushort v111, v[84:85], off offset:1536
	s_nop 0
	global_load_ushort v103, v[84:85], off
	global_load_ushort v102, v[104:105], off offset:1024
	v_add_co_u32_e32 v84, vcc, s50, v64
	s_nop 1
	v_addc_co_u32_e32 v85, vcc, 0, v65, vcc
	global_load_ushort v101, v[84:85], off offset:3584
	global_load_ushort v100, v[84:85], off offset:512
	global_load_ushort v87, v[82:83], off offset:3072
	global_load_ushort v86, v[82:83], off
	s_nop 0
	global_load_ushort v83, v[98:99], off offset:2560
	global_load_ushort v82, v[80:81], off offset:3584
	s_nop 0
	global_load_ushort v81, v[80:81], off offset:2048
	s_waitcnt vmcnt(38)
	v_lshlrev_b32_e32 v80, 16, v170
	v_max_f32_e32 v80, v80, v80
	v_med3_f32 v80, v80, s9, v244
	v_mul_f32_e32 v80, 0xbfb8aa3b, v80
	v_exp_f32_e32 v80, v80
	ds_write_b16_d16_hi v88, v171 offset:3168
	ds_write_b16_d16_hi v88, v150 offset:7776
	v_add_f32_e32 v84, 1.0, v80
	v_rcp_f32_e32 v84, v84
	s_nop 0
	v_fma_f32 v85, v117, v84, v116
	v_mul_f32_e32 v80, v80, v84
	v_mul_f32_e32 v84, v172, v85
	v_max_f32_e32 v84, 0xda24260, v84
	v_rcp_f32_e32 v85, v84
	v_mul_f32_e32 v80, v117, v80
	v_mul_f32_e32 v80, v80, v85
	v_bfe_u32 v85, v80, 16, 1
	v_add3_u32 v85, v80, v85, s10
	s_waitcnt vmcnt(37)
	v_lshlrev_b32_e32 v80, 16, v169
	v_mul_f32_e32 v80, v84, v80
	v_bfe_u32 v98, v80, 16, 1
	v_add3_u32 v80, v80, v98, s10
	ds_write_b16_d16_hi v88, v80 offset:3024
	ds_write_b16_d16_hi v88, v85 offset:7632
	v_lshlrev_b32_e32 v80, 16, v167
	v_max_f32_e32 v80, v80, v80
	v_med3_f32 v80, v80, s9, v244
	v_mul_f32_e32 v80, 0xbfb8aa3b, v80
	v_exp_f32_e32 v80, v80
	s_nop 0
	v_add_f32_e32 v98, 1.0, v80
	v_rcp_f32_e32 v98, v98
	s_nop 0
	v_fma_f32 v99, v117, v98, v116
	v_mul_f32_e32 v84, v84, v99
	v_max_f32_e32 v84, 0xda24260, v84
	v_mul_f32_e32 v80, v80, v98
	v_rcp_f32_e32 v98, v84
	v_mul_f32_e32 v80, v117, v80
	v_mul_f32_e32 v80, v80, v98
	v_bfe_u32 v98, v80, 16, 1
	v_add3_u32 v80, v80, v98, s10
	v_lshlrev_b32_e32 v98, 16, v163
	v_mul_f32_e32 v98, v84, v98
	v_bfe_u32 v99, v98, 16, 1
	v_add3_u32 v98, v98, v99, s10
	ds_write_b16_d16_hi v88, v98 offset:2880
	ds_write_b16_d16_hi v88, v80 offset:7488
	s_waitcnt vmcnt(36)
	v_lshlrev_b32_e32 v98, 16, v164
	v_max_f32_e32 v98, v98, v98
	v_med3_f32 v98, v98, s9, v244
	v_mul_f32_e32 v98, 0xbfb8aa3b, v98
	v_exp_f32_e32 v98, v98
	s_nop 0
	v_add_f32_e32 v99, 1.0, v98
	v_rcp_f32_e32 v99, v99
	s_nop 0
	v_fma_f32 v104, v117, v99, v116
	v_mul_f32_e32 v84, v84, v104
	v_max_f32_e32 v84, 0xda24260, v84
	v_mul_f32_e32 v98, v98, v99
	v_rcp_f32_e32 v99, v84
	v_mul_f32_e32 v98, v117, v98
	v_mul_f32_e32 v98, v98, v99
	v_bfe_u32 v99, v98, 16, 1
	v_add3_u32 v99, v98, v99, s10
	s_waitcnt vmcnt(35)
	v_lshlrev_b32_e32 v98, 16, v162
	v_mul_f32_e32 v98, v84, v98
	v_bfe_u32 v104, v98, 16, 1
	v_add3_u32 v98, v98, v104, s10
	ds_write_b16_d16_hi v88, v98 offset:2736
	ds_write_b16_d16_hi v88, v99 offset:7344
	s_waitcnt vmcnt(34)
	v_lshlrev_b32_e32 v98, 16, v159
	v_max_f32_e32 v98, v98, v98
	v_med3_f32 v98, v98, s9, v244
	v_mul_f32_e32 v98, 0xbfb8aa3b, v98
	v_exp_f32_e32 v98, v98
	s_nop 0
	v_add_f32_e32 v104, 1.0, v98
	v_rcp_f32_e32 v104, v104
	s_nop 0
	v_fma_f32 v105, v117, v104, v116
	v_mul_f32_e32 v84, v84, v105
	v_mul_f32_e32 v98, v98, v104
	v_max_f32_e32 v104, 0xda24260, v84
	v_rcp_f32_e32 v84, v104
	v_mul_f32_e32 v98, v117, v98
	v_mul_f32_e32 v84, v98, v84
	v_bfe_u32 v98, v84, 16, 1
	v_add3_u32 v84, v84, v98, s10
	v_lshlrev_b32_e32 v98, 16, v157
	v_mul_f32_e32 v98, v104, v98
	v_bfe_u32 v105, v98, 16, 1
	v_add3_u32 v98, v98, v105, s10
	ds_write_b16_d16_hi v88, v98 offset:2592
	ds_write_b16_d16_hi v88, v84 offset:7200
	v_lshlrev_b32_e32 v98, 16, v155
	v_max_f32_e32 v98, v98, v98
	v_med3_f32 v98, v98, s9, v244
	v_mul_f32_e32 v98, 0xbfb8aa3b, v98
	v_exp_f32_e32 v98, v98
	s_nop 0
	v_add_f32_e32 v105, 1.0, v98
	v_rcp_f32_e32 v105, v105
	s_nop 0
	v_fma_f32 v155, v117, v105, v116
	v_mul_f32_e32 v104, v104, v155
	v_max_f32_e32 v104, 0xda24260, v104
	v_mul_f32_e32 v98, v98, v105
	v_rcp_f32_e32 v105, v104
	v_mul_f32_e32 v98, v117, v98
	v_mul_f32_e32 v98, v98, v105
	v_bfe_u32 v105, v98, 16, 1
	v_add3_u32 v105, v98, v105, s10
	s_waitcnt vmcnt(23)
	v_lshlrev_b32_e32 v98, 16, v156
	v_mul_f32_e32 v98, v104, v98
	v_bfe_u32 v155, v98, 16, 1
	v_add3_u32 v98, v98, v155, s10
	ds_write_b16_d16_hi v88, v98 offset:2448
	ds_write_b16_d16_hi v88, v105 offset:7056
	v_lshlrev_b32_e32 v98, 16, v109
	v_max_f32_e32 v98, v98, v98
	v_med3_f32 v98, v98, s9, v244
	v_mul_f32_e32 v98, 0xbfb8aa3b, v98
	v_exp_f32_e32 v98, v98
	s_nop 0
	v_add_f32_e32 v109, 1.0, v98
	v_rcp_f32_e32 v109, v109
	s_nop 0
	v_fma_f32 v155, v117, v109, v116
	v_mul_f32_e32 v104, v104, v155
	v_max_f32_e32 v104, 0xda24260, v104
	v_mul_f32_e32 v98, v98, v109
	v_rcp_f32_e32 v109, v104
	v_mul_f32_e32 v98, v117, v98
	v_mul_f32_e32 v107, v104, v107
	v_mul_f32_e32 v98, v98, v109
	v_bfe_u32 v109, v98, 16, 1
	v_add3_u32 v98, v98, v109, s10
	v_bfe_u32 v109, v107, 16, 1
	v_add3_u32 v107, v107, v109, s10
	ds_write_b16_d16_hi v88, v107 offset:2304
	ds_write_b16_d16_hi v88, v98 offset:6912
	s_waitcnt vmcnt(15)
	v_lshlrev_b32_e32 v107, 16, v168
	v_max_f32_e32 v107, v107, v107
	v_med3_f32 v107, v107, s9, v244
	v_mul_f32_e32 v107, 0xbfb8aa3b, v107
	v_exp_f32_e32 v107, v107
	s_nop 0
	v_add_f32_e32 v109, 1.0, v107
	v_rcp_f32_e32 v109, v109
	s_nop 0
	v_fma_f32 v155, v117, v109, v116
	v_mul_f32_e32 v104, v104, v155
	v_max_f32_e32 v104, 0xda24260, v104
	v_mul_f32_e32 v107, v107, v109
	v_rcp_f32_e32 v109, v104
	v_mul_f32_e32 v107, v117, v107
	v_mul_f32_e32 v107, v107, v109
	v_bfe_u32 v109, v107, 16, 1
	v_add3_u32 v107, v107, v109, s10
	s_waitcnt vmcnt(14)
	v_lshlrev_b32_e32 v109, 16, v166
	v_mul_f32_e32 v109, v104, v109
	v_bfe_u32 v155, v109, 16, 1
	v_add3_u32 v109, v109, v155, s10
	ds_write_b16_d16_hi v88, v109 offset:2160
	ds_write_b16_d16_hi v88, v107 offset:6768
	s_waitcnt vmcnt(13)
	v_lshlrev_b32_e32 v109, 16, v165
	v_max_f32_e32 v109, v109, v109
	v_med3_f32 v109, v109, s9, v244
	v_mul_f32_e32 v109, 0xbfb8aa3b, v109
	v_exp_f32_e32 v109, v109
	global_load_ushort v172, v[74:75], off offset:3072
	global_load_ushort v170, v[74:75], off offset:1536
	global_load_ushort v171, v[70:71], off offset:2560
	global_load_ushort v168, v[70:71], off offset:1024
	global_load_ushort v169, v[76:77], off offset:2048
	global_load_ushort v166, v[76:77], off offset:512
	global_load_ushort v167, v[68:69], off offset:1536
	global_load_ushort v162, v[68:69], off
	global_load_ushort v164, v[78:79], off offset:1024
	v_add_co_u32_e32 v68, vcc, s11, v64
	v_add_f32_e32 v155, 1.0, v109
	v_rcp_f32_e32 v155, v155
	v_addc_co_u32_e32 v69, vcc, 0, v65, vcc
	v_fma_f32 v156, v117, v155, v116
	v_mul_f32_e32 v104, v104, v156
	v_max_f32_e32 v173, 0xda24260, v104
	v_rcp_f32_e32 v104, v173
	v_mul_f32_e32 v109, v109, v155
	v_mul_f32_e32 v109, v117, v109
	v_mul_f32_e32 v104, v109, v104
	v_bfe_u32 v109, v104, 16, 1
	v_add3_u32 v104, v104, v109, s10
	s_waitcnt vmcnt(21)
	v_lshlrev_b32_e32 v109, 16, v160
	v_mul_f32_e32 v109, v173, v109
	v_bfe_u32 v155, v109, 16, 1
	v_add3_u32 v109, v109, v155, s10
	global_load_ushort v163, v[68:69], off offset:3584
	global_load_ushort v165, v[68:69], off offset:512
	global_load_ushort v159, v[66:67], off offset:3072
	global_load_ushort v160, v[66:67], off
	global_load_ushort v156, v[72:73], off offset:2560
	global_load_ushort v157, v[64:65], off offset:3584
	global_load_ushort v155, v[64:65], off offset:2048
	s_waitcnt vmcnt(27)
	v_lshlrev_b32_e32 v64, 16, v158
	v_max_f32_e32 v64, v64, v64
	v_med3_f32 v64, v64, s9, v244
	v_mul_f32_e32 v64, 0xbfb8aa3b, v64
	v_exp_f32_e32 v64, v64
	ds_write_b16_d16_hi v88, v109 offset:2016
	ds_write_b16_d16_hi v88, v104 offset:6624
	v_add_f32_e32 v65, 1.0, v64
	v_rcp_f32_e32 v65, v65
	s_nop 0
	v_fma_f32 v66, v117, v65, v116
	v_mul_f32_e32 v64, v64, v65
	v_mul_f32_e32 v65, v173, v66
	v_max_f32_e32 v65, 0xda24260, v65
	v_rcp_f32_e32 v66, v65
	v_mul_f32_e32 v64, v117, v64
	v_mul_f32_e32 v64, v64, v66
	v_bfe_u32 v66, v64, 16, 1
	v_add3_u32 v64, v64, v66, s10
	s_waitcnt vmcnt(26)
	v_lshlrev_b32_e32 v66, 16, v113
	v_mul_f32_e32 v66, v65, v66
	v_bfe_u32 v67, v66, 16, 1
	v_add3_u32 v66, v66, v67, s10
	ds_write_b16_d16_hi v88, v66 offset:1872
	ds_write_b16_d16_hi v88, v64 offset:6480
	s_waitcnt vmcnt(25)
	v_lshlrev_b32_e32 v66, 16, v111
	v_max_f32_e32 v66, v66, v66
	v_med3_f32 v66, v66, s9, v244
	v_mul_f32_e32 v66, 0xbfb8aa3b, v66
	v_exp_f32_e32 v66, v66
	s_nop 0
	v_add_f32_e32 v67, 1.0, v66
	v_rcp_f32_e32 v67, v67
	s_nop 0
	v_fma_f32 v68, v117, v67, v116
	v_mul_f32_e32 v65, v65, v68
	v_max_f32_e32 v65, 0xda24260, v65
	v_mul_f32_e32 v66, v66, v67
	v_rcp_f32_e32 v67, v65
	v_mul_f32_e32 v66, v117, v66
	v_mul_f32_e32 v66, v66, v67
	v_bfe_u32 v67, v66, 16, 1
	v_add3_u32 v158, v66, v67, s10
	s_waitcnt vmcnt(24)
	v_lshlrev_b32_e32 v66, 16, v103
	v_mul_f32_e32 v66, v65, v66
	v_bfe_u32 v67, v66, 16, 1
	v_add3_u32 v66, v66, v67, s10
	ds_write_b16_d16_hi v88, v66 offset:1728
	ds_write_b16_d16_hi v88, v158 offset:6336
	s_waitcnt vmcnt(23)
	v_lshlrev_b32_e32 v66, 16, v102
	v_max_f32_e32 v66, v66, v66
	v_med3_f32 v66, v66, s9, v244
	v_mul_f32_e32 v66, 0xbfb8aa3b, v66
	v_exp_f32_e32 v66, v66
	s_nop 0
	v_add_f32_e32 v67, 1.0, v66
	v_rcp_f32_e32 v67, v67
	s_nop 0
	v_fma_f32 v68, v117, v67, v116
	v_mul_f32_e32 v65, v65, v68
	v_max_f32_e32 v65, 0xda24260, v65
	v_mul_f32_e32 v66, v66, v67
	v_rcp_f32_e32 v67, v65
	v_mul_f32_e32 v66, v117, v66
	v_mul_f32_e32 v66, v66, v67
	v_bfe_u32 v67, v66, 16, 1
	v_add3_u32 v66, v66, v67, s10
	s_waitcnt vmcnt(22)
	v_lshlrev_b32_e32 v67, 16, v101
	v_mul_f32_e32 v67, v65, v67
	v_bfe_u32 v68, v67, 16, 1
	v_add3_u32 v67, v67, v68, s10
	ds_write_b16_d16_hi v88, v67 offset:1584
	ds_write_b16_d16_hi v88, v66 offset:6192
	s_waitcnt vmcnt(21)
	v_lshlrev_b32_e32 v67, 16, v100
	v_max_f32_e32 v67, v67, v67
	v_med3_f32 v67, v67, s9, v244
	v_mul_f32_e32 v67, 0xbfb8aa3b, v67
	v_exp_f32_e32 v67, v67
	s_nop 0
	v_add_f32_e32 v68, 1.0, v67
	v_rcp_f32_e32 v68, v68
	s_nop 0
	v_fma_f32 v69, v117, v68, v116
	v_mul_f32_e32 v65, v65, v69
	v_max_f32_e32 v65, 0xda24260, v65
	v_mul_f32_e32 v67, v67, v68
	v_rcp_f32_e32 v68, v65
	v_mul_f32_e32 v67, v117, v67
	v_mul_f32_e32 v67, v67, v68
	v_bfe_u32 v68, v67, 16, 1
	v_add3_u32 v100, v67, v68, s10
	s_waitcnt vmcnt(20)
	v_lshlrev_b32_e32 v67, 16, v87
	v_mul_f32_e32 v67, v65, v67
	v_bfe_u32 v68, v67, 16, 1
	v_add3_u32 v67, v67, v68, s10
	ds_write_b16_d16_hi v88, v67 offset:1440
	ds_write_b16_d16_hi v88, v100 offset:6048
	s_waitcnt vmcnt(19)
	v_lshlrev_b32_e32 v67, 16, v86
	v_max_f32_e32 v67, v67, v67
	v_med3_f32 v67, v67, s9, v244
	v_mul_f32_e32 v67, 0xbfb8aa3b, v67
	v_exp_f32_e32 v67, v67
	s_nop 0
	v_add_f32_e32 v68, 1.0, v67
	v_rcp_f32_e32 v68, v68
	s_nop 0
	v_fma_f32 v69, v117, v68, v116
	v_mul_f32_e32 v65, v65, v69
	v_max_f32_e32 v65, 0xda24260, v65
	v_mul_f32_e32 v67, v67, v68
	v_rcp_f32_e32 v68, v65
	v_mul_f32_e32 v67, v117, v67
	v_mul_f32_e32 v67, v67, v68
	v_bfe_u32 v68, v67, 16, 1
	v_add3_u32 v67, v67, v68, s10
	s_waitcnt vmcnt(18)
	v_lshlrev_b32_e32 v68, 16, v83
	v_mul_f32_e32 v68, v65, v68
	v_bfe_u32 v69, v68, 16, 1
	v_add3_u32 v68, v68, v69, s10
	ds_write_b16_d16_hi v88, v68 offset:1296
	ds_write_b16_d16_hi v88, v67 offset:5904
	s_waitcnt vmcnt(17)
	v_lshlrev_b32_e32 v68, 16, v82
	v_max_f32_e32 v68, v68, v68
	v_med3_f32 v68, v68, s9, v244
	v_mul_f32_e32 v68, 0xbfb8aa3b, v68
	v_exp_f32_e32 v68, v68
	s_nop 0
	v_add_f32_e32 v69, 1.0, v68
	v_rcp_f32_e32 v69, v69
	s_nop 0
	v_fma_f32 v70, v117, v69, v116
	v_mul_f32_e32 v65, v65, v70
	v_max_f32_e32 v76, 0xda24260, v65
	v_rcp_f32_e32 v65, v76
	v_mul_f32_e32 v68, v68, v69
	v_mul_f32_e32 v68, v117, v68
	v_mul_f32_e32 v65, v68, v65
	v_bfe_u32 v68, v65, 16, 1
	v_add3_u32 v82, v65, v68, s10
	s_waitcnt vmcnt(16)
	v_lshlrev_b32_e32 v65, 16, v81
	v_mul_f32_e32 v65, v76, v65
	v_bfe_u32 v68, v65, 16, 1
	v_add3_u32 v65, v65, v68, s10
	ds_write_b16_d16_hi v88, v65 offset:1152
	ds_write_b16_d16_hi v88, v82 offset:5760
	s_waitcnt vmcnt(15)
	v_lshlrev_b32_e32 v72, 16, v172
	v_max_f32_e32 v72, v72, v72
	v_med3_f32 v72, v72, s9, v244
	v_mul_f32_e32 v72, 0xbfb8aa3b, v72
	v_exp_f32_e32 v86, v72
	v_and_b32_e32 v111, 0xffff0000, v66
	v_lshl_or_b32 v66, v106, 16, v122
	v_and_b32_e32 v113, 0xffff0000, v67
	v_add_f32_e32 v77, 1.0, v86
	v_rcp_f32_e32 v102, v77
	v_lshl_or_b32 v67, v108, 16, v110
	v_and_b32_e32 v81, 0xffff0000, v112
	v_lshl_or_b32 v75, v149, 16, v127
	v_fma_f32 v106, v117, v102, v116
	v_mul_f32_e32 v76, v76, v106
	v_max_f32_e32 v106, 0xda24260, v76
	v_rcp_f32_e32 v108, v106
	v_mul_f32_e32 v86, v86, v102
	v_mul_f32_e32 v86, v117, v86
	v_lshl_or_b32 v65, v133, 16, v121
	v_mul_f32_e32 v86, v86, v108
	v_bfe_u32 v102, v86, 16, 1
	v_add3_u32 v86, v86, v102, s10
	s_waitcnt vmcnt(13)
	v_lshlrev_b32_e32 v102, 16, v171
	v_max_f32_e32 v102, v102, v102
	v_med3_f32 v102, v102, s9, v244
	v_mul_f32_e32 v102, 0xbfb8aa3b, v102
	v_exp_f32_e32 v102, v102
	v_lshlrev_b32_e32 v108, 16, v170
	v_mul_f32_e32 v108, v106, v108
	v_bfe_u32 v112, v108, 16, 1
	v_add_f32_e32 v110, 1.0, v102
	v_rcp_f32_e32 v110, v110
	v_add3_u32 v108, v108, v112, s10
	ds_write_b16_d16_hi v88, v108 offset:1008
	v_and_b32_e32 v127, 0xffff0000, v86
	v_fma_f32 v108, v117, v110, v116
	v_mul_f32_e32 v106, v106, v108
	v_max_f32_e32 v106, 0xda24260, v106
	v_rcp_f32_e32 v108, v106
	ds_write_b16_d16_hi v88, v86 offset:5616
	v_mul_f32_e32 v86, v102, v110
	v_mul_f32_e32 v86, v117, v86
	v_mul_f32_e32 v86, v86, v108
	s_waitcnt vmcnt(11)
	v_lshlrev_b32_e32 v108, 16, v169
	v_max_f32_e32 v108, v108, v108
	v_med3_f32 v108, v108, s9, v244
	v_mul_f32_e32 v108, 0xbfb8aa3b, v108
	v_exp_f32_e32 v108, v108
	v_bfe_u32 v102, v86, 16, 1
	v_add3_u32 v86, v86, v102, s10
	v_lshlrev_b32_e32 v102, 16, v168
	v_add_f32_e32 v110, 1.0, v108
	v_rcp_f32_e32 v110, v110
	v_mul_f32_e32 v102, v106, v102
	v_bfe_u32 v112, v102, 16, 1
	v_add3_u32 v102, v102, v112, s10
	ds_write_b16_d16_hi v88, v102 offset:864
	v_fma_f32 v102, v117, v110, v116
	v_mul_f32_e32 v102, v106, v102
	v_max_f32_e32 v102, 0xda24260, v102
	v_rcp_f32_e32 v106, v102
	v_mul_f32_e32 v108, v108, v110
	v_mul_f32_e32 v108, v117, v108
	s_waitcnt vmcnt(10)
	v_lshlrev_b32_e32 v110, 16, v166
	v_mul_f32_e32 v106, v108, v106
	v_bfe_u32 v108, v106, 16, 1
	v_add3_u32 v106, v106, v108, s10
	s_waitcnt vmcnt(9)
	v_lshlrev_b32_e32 v108, 16, v167
	v_max_f32_e32 v108, v108, v108
	v_med3_f32 v108, v108, s9, v244
	v_mul_f32_e32 v108, 0xbfb8aa3b, v108
	v_exp_f32_e32 v108, v108
	v_mul_f32_e32 v110, v102, v110
	v_bfe_u32 v121, v110, 16, 1
	v_add3_u32 v110, v110, v121, s10
	v_add_f32_e32 v112, 1.0, v108
	v_rcp_f32_e32 v112, v112
	ds_write_b16_d16_hi v88, v110 offset:720
	v_lshl_or_b32 v74, v147, 16, v125
	v_and_b32_e32 v125, 0xffff0000, v106
	v_fma_f32 v110, v117, v112, v116
	v_mul_f32_e32 v102, v102, v110
	v_max_f32_e32 v102, 0xda24260, v102
	v_rcp_f32_e32 v110, v102
	ds_write_b16_d16_hi v88, v106 offset:5328
	v_mul_f32_e32 v106, v108, v112
	v_mul_f32_e32 v106, v117, v106
	v_mul_f32_e32 v106, v106, v110
	s_waitcnt vmcnt(7)
	v_lshlrev_b32_e32 v110, 16, v164
	v_max_f32_e32 v110, v110, v110
	v_med3_f32 v110, v110, s9, v244
	v_mul_f32_e32 v110, 0xbfb8aa3b, v110
	v_exp_f32_e32 v110, v110
	v_bfe_u32 v108, v106, 16, 1
	v_add3_u32 v106, v106, v108, s10
	v_lshlrev_b32_e32 v108, 16, v162
	v_add_f32_e32 v112, 1.0, v110
	v_rcp_f32_e32 v112, v112
	v_mul_f32_e32 v108, v102, v108
	v_bfe_u32 v121, v108, 16, 1
	v_add3_u32 v108, v108, v121, s10
	ds_write_b16_d16_hi v88, v108 offset:576
	v_fma_f32 v108, v117, v112, v116
	v_mul_f32_e32 v102, v102, v108
	v_max_f32_e32 v102, 0xda24260, v102
	v_rcp_f32_e32 v108, v102
	v_mul_f32_e32 v110, v110, v112
	v_mul_f32_e32 v110, v117, v110
	s_waitcnt vmcnt(6)
	v_lshlrev_b32_e32 v112, 16, v163
	v_mul_f32_e32 v108, v110, v108
	v_bfe_u32 v110, v108, 16, 1
	v_add3_u32 v108, v108, v110, s10
	s_waitcnt vmcnt(5)
	v_lshlrev_b32_e32 v110, 16, v165
	v_max_f32_e32 v110, v110, v110
	v_med3_f32 v110, v110, s9, v244
	v_mul_f32_e32 v110, 0xbfb8aa3b, v110
	v_exp_f32_e32 v110, v110
	v_mul_f32_e32 v112, v102, v112
	v_bfe_u32 v122, v112, 16, 1
	v_add3_u32 v112, v112, v122, s10
	v_add_f32_e32 v121, 1.0, v110
	v_rcp_f32_e32 v121, v121
	ds_write_b16_d16_hi v88, v112 offset:432
	v_lshl_or_b32 v69, v135, 16, v129
	v_and_b32_e32 v129, 0xffff0000, v108
	v_fma_f32 v112, v117, v121, v116
	v_mul_f32_e32 v102, v102, v112
	v_max_f32_e32 v102, 0xda24260, v102
	v_rcp_f32_e32 v112, v102
	ds_write_b16_d16_hi v88, v108 offset:5040
	v_mul_f32_e32 v108, v110, v121
	v_mul_f32_e32 v108, v117, v108
	v_mul_f32_e32 v108, v108, v112
	s_waitcnt vmcnt(3)
	v_lshlrev_b32_e32 v112, 16, v160
	v_max_f32_e32 v112, v112, v112
	v_med3_f32 v112, v112, s9, v244
	v_mul_f32_e32 v112, 0xbfb8aa3b, v112
	v_exp_f32_e32 v112, v112
	v_bfe_u32 v110, v108, 16, 1
	v_add3_u32 v108, v108, v110, s10
	v_lshlrev_b32_e32 v110, 16, v159
	v_add_f32_e32 v121, 1.0, v112
	v_rcp_f32_e32 v121, v121
	v_mul_f32_e32 v110, v102, v110
	v_bfe_u32 v122, v110, 16, 1
	v_add3_u32 v110, v110, v122, s10
	ds_write_b16_d16_hi v88, v110 offset:288
	v_fma_f32 v110, v117, v121, v116
	v_mul_f32_e32 v102, v102, v110
	v_max_f32_e32 v102, 0xda24260, v102
	v_rcp_f32_e32 v110, v102
	v_mul_f32_e32 v112, v112, v121
	v_mul_f32_e32 v112, v117, v112
	s_waitcnt vmcnt(2)
	v_lshlrev_b32_e32 v121, 16, v156
	v_mul_f32_e32 v110, v112, v110
	v_bfe_u32 v112, v110, 16, 1
	v_add3_u32 v110, v110, v112, s10
	s_waitcnt vmcnt(1)
	v_lshlrev_b32_e32 v112, 16, v157
	v_max_f32_e32 v112, v112, v112
	v_med3_f32 v112, v112, s9, v244
	v_mul_f32_e32 v112, 0xbfb8aa3b, v112
	v_exp_f32_e32 v112, v112
	v_mul_f32_e32 v121, v102, v121
	v_lshl_or_b32 v70, v137, 16, v123
	v_and_b32_e32 v123, 0xffff0000, v110
	v_add_f32_e32 v122, 1.0, v112
	v_rcp_f32_e32 v122, v122
	ds_write_b16_d16_hi v88, v110 offset:4752
	v_lshl_or_b32 v71, v131, 16, v124
	v_bfe_u32 v124, v121, 16, 1
	v_fmac_f32_e32 v116, v117, v122
	v_mul_f32_e32 v102, v102, v116
	v_max_f32_e32 v116, 0xda24260, v102
	v_rcp_f32_e32 v102, v116
	v_mul_f32_e32 v110, v112, v122
	v_mul_f32_e32 v110, v117, v110
	v_readlane_b32 s9, v255, 34
	v_mul_f32_e32 v102, v110, v102
	v_bfe_u32 v110, v102, 16, 1
	v_add3_u32 v102, v102, v110, s10
	s_waitcnt vmcnt(0)
	v_lshlrev_b32_e32 v110, 16, v155
	v_mul_f32_e32 v110, v116, v110
	v_bfe_u32 v112, v110, 16, 1
	v_add3_u32 v121, v121, v124, s10
	v_add3_u32 v110, v110, v112, s10
	v_readlane_b32 s10, v255, 36
	v_and_b32_e32 v109, 0xffff0000, v64
	v_and_b32_e32 v107, 0xffff0000, v107
	v_and_b32_e32 v105, 0xffff0000, v105
	v_and_b32_e32 v103, 0xffff0000, v99
	v_and_b32_e32 v101, 0xffff0000, v85
	v_and_b32_e32 v99, 0xffff0000, v154
	v_and_b32_e32 v87, 0xffff0000, v153
	v_and_b32_e32 v85, 0xffff0000, v152
	v_and_b32_e32 v83, 0xffff0000, v151
	v_lshl_or_b32 v64, v132, 16, v126
	v_lshl_or_b32 v68, v148, 16, v128
	v_lshl_or_b32 v73, v142, 16, v141
	v_lshl_or_b32 v72, v146, 16, v139
	v_lshl_or_b32 v79, v144, 16, v138
	v_lshl_or_b32 v78, v145, 16, v136
	v_lshl_or_b32 v77, v140, 16, v134
	v_lshl_or_b32 v76, v143, 16, v130
	ds_write_b16_d16_hi v88, v86 offset:5472
	ds_write_b16_d16_hi v88, v106 offset:5184
	ds_write_b16_d16_hi v88, v108 offset:4896
	ds_write_b16_d16_hi v88, v121 offset:144
	ds_write_b16_d16_hi v88, v110
	ds_write_b16_d16_hi v88, v102 offset:4608
	v_and_b32_e32 v122, 0xffff0000, v102
	v_and_b32_e32 v128, 0xffff0000, v108
	v_and_b32_e32 v124, 0xffff0000, v106
	v_and_b32_e32 v126, 0xffff0000, v86
	v_pk_mul_f32 v[122:123], v[116:117], v[122:123] op_sel_hi:[0,1]
	v_pk_mul_f32 v[128:129], v[116:117], v[128:129] op_sel_hi:[0,1]
	v_pk_mul_f32 v[124:125], v[116:117], v[124:125] op_sel_hi:[0,1]
	v_pk_mul_f32 v[126:127], v[116:117], v[126:127] op_sel_hi:[0,1]
	v_and_b32_e32 v112, 0xffff0000, v82
	v_and_b32_e32 v110, 0xffff0000, v100
	v_and_b32_e32 v108, 0xffff0000, v158
	v_and_b32_e32 v106, 0xffff0000, v104
	v_and_b32_e32 v104, 0xffff0000, v98
	v_and_b32_e32 v102, 0xffff0000, v84
	v_and_b32_e32 v100, 0xffff0000, v80
	v_and_b32_e32 v98, 0xffff0000, v150
	v_and_b32_e32 v86, 0xffff0000, v120
	v_and_b32_e32 v84, 0xffff0000, v119
	v_and_b32_e32 v82, 0xffff0000, v118
	v_and_b32_e32 v80, 0xffff0000, v95
	v_mad_u64_u32 v[130:131], s[2:3], v94, s4, v[92:93]
	v_cvt_pk_bf16_f32 v122, v122, v123
	v_cvt_pk_bf16_f32 v123, v128, v129
	v_cvt_pk_bf16_f32 v124, v124, v125
	v_cvt_pk_bf16_f32 v125, v126, v127
	v_pk_mul_f32 v[112:113], v[116:117], v[112:113] op_sel_hi:[0,1]
	v_pk_mul_f32 v[110:111], v[116:117], v[110:111] op_sel_hi:[0,1]
	v_pk_mul_f32 v[108:109], v[116:117], v[108:109] op_sel_hi:[0,1]
	v_pk_mul_f32 v[106:107], v[116:117], v[106:107] op_sel_hi:[0,1]
	v_pk_mul_f32 v[104:105], v[116:117], v[104:105] op_sel_hi:[0,1]
	v_pk_mul_f32 v[102:103], v[116:117], v[102:103] op_sel_hi:[0,1]
	v_pk_mul_f32 v[100:101], v[116:117], v[100:101] op_sel_hi:[0,1]
	v_pk_mul_f32 v[98:99], v[116:117], v[98:99] op_sel_hi:[0,1]
	v_pk_mul_f32 v[86:87], v[116:117], v[86:87] op_sel_hi:[0,1]
	v_pk_mul_f32 v[84:85], v[116:117], v[84:85] op_sel_hi:[0,1]
	v_pk_mul_f32 v[82:83], v[116:117], v[82:83] op_sel_hi:[0,1]
	v_pk_mul_f32 v[80:81], v[116:117], v[80:81] op_sel_hi:[0,1]
	ds_write_b128 v130, v[122:125] offset:9216
	v_cvt_pk_bf16_f32 v122, v112, v113
	v_cvt_pk_bf16_f32 v123, v110, v111
	v_cvt_pk_bf16_f32 v124, v108, v109
	v_cvt_pk_bf16_f32 v125, v106, v107
	v_cvt_pk_bf16_f32 v104, v104, v105
	v_cvt_pk_bf16_f32 v105, v102, v103
	v_cvt_pk_bf16_f32 v106, v100, v101
	v_cvt_pk_bf16_f32 v107, v98, v99
	v_cvt_pk_bf16_f32 v98, v86, v87
	v_cvt_pk_bf16_f32 v99, v84, v85
	v_cvt_pk_bf16_f32 v100, v82, v83
	v_cvt_pk_bf16_f32 v101, v80, v81
	v_lshl_add_u32 v80, v94, 2, v92
	ds_write_b128 v130, v[122:125] offset:9232
	ds_write_b128 v130, v[104:107] offset:9248
	ds_write_b128 v130, v[98:101] offset:9264
	ds_write_b32 v80, v116 offset:19456
	ds_write_b128 v130, v[76:79] offset:14336
	ds_write_b128 v130, v[72:75] offset:14352
	ds_write_b128 v130, v[68:71] offset:14368
	ds_write_b128 v130, v[64:67] offset:14384
	s_waitcnt lgkmcnt(0)
	v_or_b32_e32 v88, v93, v114
	v_lshlrev_b64 v[64:65], 11, v[88:89]
	v_lshlrev_b32_e32 v98, 2, v115
	v_lshl_add_u64 v[64:65], s[12:13], 0, v[64:65]
	v_ashrrev_i32_e32 v99, 31, v98
	v_lshl_add_u64 v[64:65], v[64:65], 0, v[90:91]
	v_lshlrev_b64 v[100:101], 1, v[98:99]
	v_lshl_add_u64 v[102:103], v[64:65], 0, v[100:101]
	s_mov_b64 s[2:3], 0x16f00600
	v_lshl_add_u64 v[94:95], v[102:103], 0, s[2:3]
	global_load_dwordx2 v[196:197], v[94:95], off
	global_load_dwordx2 v[198:199], v[94:95], off offset:16
	global_load_dwordx2 v[200:201], v[94:95], off offset:32
	global_load_dwordx2 v[202:203], v[94:95], off offset:48
	global_load_dwordx2 v[230:231], v[94:95], off offset:64
	global_load_dwordx2 v[232:233], v[94:95], off offset:80
	global_load_dwordx2 v[234:235], v[94:95], off offset:96
	global_load_dwordx2 v[240:241], v[94:95], off offset:112
	s_movk_i32 s2, 0x90
	v_mad_u32_u24 v89, v114, s2, v92
	v_lshl_add_u32 v93, v115, 4, v89
	ds_read_b128 v[64:67], v93 offset:4608
	ds_read_b128 v[68:71], v93
	ds_read_b128 v[80:83], v93 offset:32
	ds_read_b128 v[84:87], v93 offset:4640
	s_waitcnt lgkmcnt(2)
	v_mfma_f32_32x32x16_bf16 v[64:79], v[64:67], v[68:71], 0
	v_cmp_ge_i32_e32 vcc, v98, v114
	v_cvt_pk_bf16_f32 v32, v32, v33
	v_cvt_pk_bf16_f32 v33, v34, v35
	v_cvt_pk_bf16_f32 v34, v36, v37
	v_cvt_pk_bf16_f32 v35, v38, v39
	v_cvt_pk_bf16_f32 v36, v48, v49
	v_cvt_pk_bf16_f32 v37, v50, v51
	s_waitcnt lgkmcnt(0)
	v_mfma_f32_32x32x16_bf16 v[64:79], v[84:87], v[80:83], v[64:79]
	ds_read_b128 v[80:83], v93 offset:4672
	ds_read_b128 v[84:87], v93 offset:64
	v_cvt_pk_bf16_f32 v38, v52, v53
	v_cvt_pk_bf16_f32 v39, v54, v55
	s_mov_b32 s2, 0x16f00000
	s_waitcnt lgkmcnt(0)
	v_mfma_f32_32x32x16_bf16 v[64:79], v[80:83], v[84:87], v[64:79]
	ds_read_b128 v[80:83], v93 offset:4704
	ds_read_b128 v[84:87], v93 offset:96
	s_waitcnt lgkmcnt(0)
	v_mfma_f32_32x32x16_bf16 v[64:79], v[80:83], v[84:87], v[64:79]
	v_or_b32_e32 v80, 1, v98
	s_nop 10
	v_cndmask_b32_e32 v64, 0, v64, vcc
	v_cmp_ge_i32_e32 vcc, v80, v114
	v_or_b32_e32 v80, 2, v98
	s_nop 0
	v_cndmask_b32_e32 v65, 0, v65, vcc
	v_cmp_ge_i32_e32 vcc, v80, v114
	v_or_b32_e32 v80, 3, v98
	s_nop 0
	v_cndmask_b32_e32 v66, 0, v66, vcc
	v_cmp_ge_i32_e32 vcc, v80, v114
	v_add_u32_e32 v80, 8, v98
	s_nop 0
	v_cndmask_b32_e32 v67, 0, v67, vcc
	v_cmp_ge_i32_e32 vcc, v80, v114
	v_add_u32_e32 v80, 9, v98
	v_cvt_pk_bf16_f32 v81, v66, v67
	v_cndmask_b32_e32 v68, 0, v68, vcc
	v_cmp_ge_i32_e32 vcc, v80, v114
	v_add_u32_e32 v80, 10, v98
	s_nop 0
	v_cndmask_b32_e32 v69, 0, v69, vcc
	v_cmp_ge_i32_e32 vcc, v80, v114
	v_add_u32_e32 v80, 11, v98
	v_cvt_pk_bf16_f32 v82, v68, v69
	v_cndmask_b32_e32 v70, 0, v70, vcc
	v_cmp_ge_i32_e32 vcc, v80, v114
	v_add_u32_e32 v80, 16, v98
	s_nop 0
	v_cndmask_b32_e32 v71, 0, v71, vcc
	v_cmp_ge_i32_e32 vcc, v80, v114
	v_add_u32_e32 v80, 17, v98
	v_cvt_pk_bf16_f32 v83, v70, v71
	v_cndmask_b32_e32 v72, 0, v72, vcc
	v_cmp_ge_i32_e32 vcc, v80, v114
	v_add_u32_e32 v80, 18, v98
	s_nop 0
	v_cndmask_b32_e32 v73, 0, v73, vcc
	v_cmp_ge_i32_e32 vcc, v80, v114
	v_add_u32_e32 v80, 19, v98
	v_cvt_pk_bf16_f32 v84, v72, v73
	v_cndmask_b32_e32 v74, 0, v74, vcc
	v_cmp_ge_i32_e32 vcc, v80, v114
	v_add_u32_e32 v80, 24, v98
	s_nop 0
	v_cndmask_b32_e32 v75, 0, v75, vcc
	v_cmp_ge_i32_e32 vcc, v80, v114
	v_add_u32_e32 v80, 25, v98
	v_cvt_pk_bf16_f32 v85, v74, v75
	v_cndmask_b32_e32 v76, 0, v76, vcc
	v_cmp_ge_i32_e32 vcc, v80, v114
	v_add_u32_e32 v80, 26, v98
	s_nop 0
	v_cndmask_b32_e32 v77, 0, v77, vcc
	v_cmp_ge_i32_e32 vcc, v80, v114
	v_add_u32_e32 v80, 27, v98
	v_cvt_pk_bf16_f32 v86, v76, v77
	v_cndmask_b32_e32 v78, 0, v78, vcc
	v_cmp_ge_i32_e32 vcc, v80, v114
	v_cvt_pk_bf16_f32 v80, v64, v65
	v_lshlrev_b32_e32 v64, 3, v115
	v_mul_u32_u24_e32 v65, 0x50, v114
	v_add3_u32 v92, v92, v64, v65
	v_add_u32_e32 v68, 0x3800, v92
	v_add_u32_e32 v89, v89, v64
	ds_read2_b64 v[64:67], v68 offset1:2
	ds_read2_b64 v[104:107], v68 offset0:4 offset1:6
	v_cndmask_b32_e32 v79, 0, v79, vcc
	v_cvt_pk_bf16_f32 v87, v78, v79
	s_waitcnt lgkmcnt(1)
	v_mfma_f32_32x32x16_bf16 v[64:79], v[64:67], v[80:83], 0
	v_add_co_u32_e32 v48, vcc, s2, v102
	s_nop 1
	v_addc_co_u32_e32 v49, vcc, 0, v103, vcc
	s_waitcnt lgkmcnt(0)
	v_mfma_f32_32x32x16_bf16 v[64:79], v[104:107], v[84:87], v[64:79]
	ds_read2_b64 v[104:107], v89 offset1:2
	ds_read2_b64 v[108:111], v89 offset0:4 offset1:6
	s_waitcnt lgkmcnt(1)
	v_mfma_f32_32x32x16_bf16 v[64:79], v[32:35], v[104:107], v[64:79]
	v_cvt_pk_bf16_f32 v32, v40, v41
	v_cvt_pk_bf16_f32 v33, v42, v43
	v_cvt_pk_bf16_f32 v34, v44, v45
	v_cvt_pk_bf16_f32 v35, v46, v47
	s_waitcnt lgkmcnt(0)
	s_nop 0
	v_mfma_f32_32x32x16_bf16 v[64:79], v[32:35], v[108:111], v[64:79]
	ds_read2_b64 v[32:35], v89 offset0:8 offset1:10
	s_waitcnt lgkmcnt(0)
	v_mfma_f32_32x32x16_bf16 v[64:79], v[36:39], v[32:35], v[64:79]
	ds_read2_b64 v[32:35], v89 offset0:12 offset1:14
	v_cvt_pk_bf16_f32 v36, v56, v57
	v_cvt_pk_bf16_f32 v37, v58, v59
	v_cvt_pk_bf16_f32 v38, v60, v61
	v_cvt_pk_bf16_f32 v39, v62, v63
	s_waitcnt lgkmcnt(0)
	s_nop 0
	v_mfma_f32_32x32x16_bf16 v[64:79], v[36:39], v[32:35], v[64:79]
	s_waitcnt vmcnt(7)
	v_lshlrev_b32_e32 v34, 16, v196
	v_and_b32_e32 v35, 0xffff0000, v196
	v_lshlrev_b32_e32 v32, 16, v197
	v_and_b32_e32 v33, 0xffff0000, v197
	s_nop 5
	v_pk_add_f32 v[34:35], v[64:65], v[34:35]
	v_pk_add_f32 v[32:33], v[66:67], v[32:33]
	v_mul_f32_e32 v36, v35, v35
	v_mul_f32_e32 v38, v33, v33
	v_pk_fma_f32 v[36:37], v[34:35], v[34:35], v[36:37] op_sel_hi:[1,1,0]
	v_pk_fma_f32 v[38:39], v[32:33], v[32:33], v[38:39] op_sel_hi:[1,1,0]
	v_cvt_pk_bf16_f32 v34, v34, v35
	v_cvt_pk_bf16_f32 v35, v32, v33
	v_pk_add_f32 v[36:37], v[36:37], v[38:39]
	global_store_dwordx2 v[48:49], v[34:35], off offset:1536
	s_waitcnt vmcnt(7)
	v_lshlrev_b32_e32 v34, 16, v198
	v_and_b32_e32 v35, 0xffff0000, v198
	v_lshlrev_b32_e32 v32, 16, v199
	v_and_b32_e32 v33, 0xffff0000, v199
	v_pk_add_f32 v[34:35], v[68:69], v[34:35]
	v_pk_add_f32 v[32:33], v[70:71], v[32:33]
	v_mul_f32_e32 v38, v35, v35
	v_mul_f32_e32 v40, v33, v33
	v_pk_fma_f32 v[38:39], v[34:35], v[34:35], v[38:39] op_sel_hi:[1,1,0]
	v_pk_fma_f32 v[40:41], v[32:33], v[32:33], v[40:41] op_sel_hi:[1,1,0]
	v_cvt_pk_bf16_f32 v34, v34, v35
	v_cvt_pk_bf16_f32 v35, v32, v33
	v_pk_add_f32 v[38:39], v[38:39], v[40:41]
	global_store_dwordx2 v[94:95], v[34:35], off offset:16
	v_pk_add_f32 v[36:37], v[36:37], v[38:39]
	s_waitcnt vmcnt(7)
	v_lshlrev_b32_e32 v34, 16, v200
	v_and_b32_e32 v35, 0xffff0000, v200
	v_pk_add_f32 v[34:35], v[72:73], v[34:35]
	v_lshlrev_b32_e32 v32, 16, v201
	v_and_b32_e32 v33, 0xffff0000, v201
	v_pk_add_f32 v[38:39], v[74:75], v[32:33]
	v_mul_f32_e32 v32, v35, v35
	v_pk_fma_f32 v[32:33], v[34:35], v[34:35], v[32:33] op_sel_hi:[1,1,0]
	v_cvt_pk_bf16_f32 v34, v34, v35
	v_cvt_pk_bf16_f32 v35, v38, v39
	global_store_dwordx2 v[94:95], v[34:35], off offset:32
	v_mul_f32_e32 v40, v39, v39
	v_pk_fma_f32 v[40:41], v[38:39], v[38:39], v[40:41] op_sel_hi:[1,1,0]
	s_nop 0
	v_pk_add_f32 v[32:33], v[32:33], v[40:41]
	s_nop 0
	v_pk_add_f32 v[32:33], v[36:37], v[32:33]
	s_waitcnt vmcnt(7)
	v_lshlrev_b32_e32 v36, 16, v202
	v_and_b32_e32 v37, 0xffff0000, v202
	v_lshlrev_b32_e32 v34, 16, v203
	v_and_b32_e32 v35, 0xffff0000, v203
	v_pk_add_f32 v[36:37], v[76:77], v[36:37]
	v_pk_add_f32 v[34:35], v[78:79], v[34:35]
	v_mul_f32_e32 v38, v37, v37
	v_mul_f32_e32 v40, v35, v35
	v_pk_fma_f32 v[38:39], v[36:37], v[36:37], v[38:39] op_sel_hi:[1,1,0]
	v_pk_fma_f32 v[40:41], v[34:35], v[34:35], v[40:41] op_sel_hi:[1,1,0]
	s_nop 0
	v_pk_add_f32 v[38:39], v[38:39], v[40:41]
	s_nop 0
	v_pk_add_f32 v[58:59], v[32:33], v[38:39]
	v_cvt_pk_bf16_f32 v32, v36, v37
	v_cvt_pk_bf16_f32 v33, v34, v35
	global_store_dwordx2 v[94:95], v[32:33], off offset:48
	v_add_u32_e32 v36, 0x4000, v92
	ds_read2_b64 v[32:35], v36 offset0:64 offset1:66
	ds_read2_b64 v[50:53], v36 offset0:68 offset1:70
	v_cvt_pk_bf16_f32 v0, v0, v1
	v_cvt_pk_bf16_f32 v1, v2, v3
	v_cvt_pk_bf16_f32 v2, v4, v5
	s_waitcnt lgkmcnt(1)
	v_mfma_f32_32x32x16_bf16 v[32:47], v[32:35], v[80:83], 0
	v_cvt_pk_bf16_f32 v3, v6, v7
	v_cvt_pk_bf16_f32 v4, v16, v17
	v_cvt_pk_bf16_f32 v5, v18, v19
	v_cvt_pk_bf16_f32 v6, v20, v21
	v_cvt_pk_bf16_f32 v7, v22, v23
	s_waitcnt lgkmcnt(0)
	v_mfma_f32_32x32x16_bf16 v[32:47], v[50:53], v[84:87], v[32:47]
	ds_read2_b64 v[50:53], v89 offset1:2
	ds_read2_b64 v[54:57], v89 offset0:4 offset1:6
	s_waitcnt lgkmcnt(1)
	v_mfma_f32_32x32x16_bf16 v[32:47], v[0:3], v[50:53], v[32:47]
	v_cvt_pk_bf16_f32 v0, v8, v9
	v_cvt_pk_bf16_f32 v1, v10, v11
	v_cvt_pk_bf16_f32 v2, v12, v13
	v_cvt_pk_bf16_f32 v3, v14, v15
	s_waitcnt lgkmcnt(0)
	s_nop 0
	v_mfma_f32_32x32x16_bf16 v[32:47], v[0:3], v[54:57], v[32:47]
	ds_read2_b64 v[0:3], v89 offset0:8 offset1:10
	s_waitcnt lgkmcnt(0)
	v_mfma_f32_32x32x16_bf16 v[32:47], v[4:7], v[0:3], v[32:47]
	ds_read2_b64 v[0:3], v89 offset0:12 offset1:14
	v_cvt_pk_bf16_f32 v4, v24, v25
	v_cvt_pk_bf16_f32 v5, v26, v27
	v_cvt_pk_bf16_f32 v6, v28, v29
	v_cvt_pk_bf16_f32 v7, v30, v31
	s_waitcnt lgkmcnt(0)
	s_nop 0
	v_mfma_f32_32x32x16_bf16 v[32:47], v[4:7], v[0:3], v[32:47]
	s_waitcnt vmcnt(7)
	v_lshlrev_b32_e32 v2, 16, v230
	v_and_b32_e32 v3, 0xffff0000, v230
	v_lshlrev_b32_e32 v0, 16, v231
	v_and_b32_e32 v1, 0xffff0000, v231
	s_nop 5
	v_pk_add_f32 v[2:3], v[32:33], v[2:3]
	v_pk_add_f32 v[0:1], v[34:35], v[0:1]
	v_mul_f32_e32 v4, v3, v3
	v_mul_f32_e32 v6, v1, v1
	v_pk_fma_f32 v[4:5], v[2:3], v[2:3], v[4:5] op_sel_hi:[1,1,0]
	v_pk_fma_f32 v[6:7], v[0:1], v[0:1], v[6:7] op_sel_hi:[1,1,0]
	v_cvt_pk_bf16_f32 v2, v2, v3
	v_cvt_pk_bf16_f32 v3, v0, v1
	v_pk_add_f32 v[4:5], v[4:5], v[6:7]
	global_store_dwordx2 v[94:95], v[2:3], off offset:64
	v_pk_add_f32 v[4:5], v[58:59], v[4:5]
	s_waitcnt vmcnt(7)
	v_lshlrev_b32_e32 v2, 16, v232
	v_and_b32_e32 v3, 0xffff0000, v232
	v_lshlrev_b32_e32 v0, 16, v233
	v_and_b32_e32 v1, 0xffff0000, v233
	v_pk_add_f32 v[2:3], v[36:37], v[2:3]
	v_pk_add_f32 v[0:1], v[38:39], v[0:1]
	v_mul_f32_e32 v6, v3, v3
	v_mul_f32_e32 v8, v1, v1
	v_pk_fma_f32 v[6:7], v[2:3], v[2:3], v[6:7] op_sel_hi:[1,1,0]
	v_pk_fma_f32 v[8:9], v[0:1], v[0:1], v[8:9] op_sel_hi:[1,1,0]
	v_cvt_pk_bf16_f32 v2, v2, v3
	v_cvt_pk_bf16_f32 v3, v0, v1
	v_pk_add_f32 v[6:7], v[6:7], v[8:9]
	global_store_dwordx2 v[94:95], v[2:3], off offset:80
	v_pk_add_f32 v[4:5], v[4:5], v[6:7]
	s_waitcnt vmcnt(7)
	v_lshlrev_b32_e32 v2, 16, v234
	v_and_b32_e32 v3, 0xffff0000, v234
	v_lshlrev_b32_e32 v0, 16, v235
	v_and_b32_e32 v1, 0xffff0000, v235
	v_pk_add_f32 v[2:3], v[40:41], v[2:3]
	v_pk_add_f32 v[6:7], v[42:43], v[0:1]
	v_mov_b32_e32 v0, v2
	v_mov_b32_e32 v8, v3
	v_cvt_pk_bf16_f32 v2, v2, v3
	v_cvt_pk_bf16_f32 v3, v6, v7
	global_store_dwordx2 v[94:95], v[2:3], off offset:96
	v_mov_b32_e32 v9, v7
	v_mov_b32_e32 v1, v6
	v_pk_mul_f32 v[8:9], v[8:9], v[8:9]
	s_nop 0
	v_pk_fma_f32 v[0:1], v[0:1], v[0:1], v[8:9]
	s_nop 0
	v_pk_add_f32 v[0:1], v[0:1], v[0:1] op_sel:[0,1] op_sel_hi:[1,0]
	s_nop 0
	v_pk_add_f32 v[0:1], v[4:5], v[0:1]
	s_waitcnt vmcnt(7)
	v_lshlrev_b32_e32 v4, 16, v240
	v_and_b32_e32 v5, 0xffff0000, v240
	v_lshlrev_b32_e32 v2, 16, v241
	v_and_b32_e32 v3, 0xffff0000, v241
	v_pk_add_f32 v[4:5], v[44:45], v[4:5]
	v_pk_add_f32 v[2:3], v[46:47], v[2:3]
	v_mov_b32_e32 v8, v5
	v_mov_b32_e32 v9, v3
	v_mov_b32_e32 v6, v4
	v_mov_b32_e32 v7, v2
	v_pk_mul_f32 v[8:9], v[8:9], v[8:9]
	v_cvt_pk_bf16_f32 v4, v4, v5
	v_pk_fma_f32 v[6:7], v[6:7], v[6:7], v[8:9]
	v_cvt_pk_bf16_f32 v5, v2, v3
	v_pk_add_f32 v[6:7], v[6:7], v[6:7] op_sel:[0,1] op_sel_hi:[1,0]
	global_store_dwordx2 v[94:95], v[4:5], off offset:112
	v_pk_add_f32 v[0:1], v[0:1], v[6:7]
	s_waitcnt lgkmcnt(0)
	s_nop 0
	v_mov_b32_e32 v1, v0
	s_nop 1
	v_permlane32_swap_b32_e32 v0, v1
	v_add_f32_e32 v0, v0, v1
	v_fmamk_f32 v0, v0, 0x3c800000, v237
	v_rsq_f32_e32 v4, v0
	v_mad_i64_i32 v[0:1], s[2:3], v88, s6, v[96:97]
	v_lshl_add_u64 v[0:1], v[0:1], 0, v[90:91]
	v_lshl_add_u64 v[0:1], v[0:1], 0, v[100:101]
	v_lshl_add_u64 v[8:9], v[0:1], 0, s[48:49]
	v_add_co_u32_e32 v0, vcc, s5, v0
	global_load_dwordx2 v[10:11], v[48:49], off offset:1536
	s_nop 0
	v_addc_co_u32_e32 v1, vcc, 0, v1, vcc
	global_load_dwordx2 v[12:13], v[0:1], off
	s_add_u32 s2, s12, s0
	s_addc_u32 s3, s13, s1
	v_lshl_add_u64 v[0:1], v[98:99], 2, s[2:3]
	v_lshl_add_u64 v[6:7], v[0:1], 0, s[30:31]
	v_add_co_u32_e32 v0, vcc, s7, v0
	v_readlane_b32 s48, v254, 11
	s_nop 0
	v_addc_co_u32_e32 v1, vcc, 0, v1, vcc
	global_load_dwordx4 v[0:3], v[0:1], off offset:2048
	global_load_dwordx4 v[206:209], v[6:7], off offset:32
	global_load_dwordx2 v[210:211], v[8:9], off offset:16
	global_load_dwordx2 v[212:213], v[94:95], off offset:16
	global_load_dwordx4 v[214:217], v[6:7], off offset:64
	global_load_dwordx2 v[218:219], v[8:9], off offset:32
	global_load_dwordx2 v[220:221], v[94:95], off offset:32
	global_load_dwordx4 v[222:225], v[6:7], off offset:96
	global_load_dwordx2 v[226:227], v[8:9], off offset:48
	global_load_dwordx2 v[228:229], v[94:95], off offset:48
	v_readlane_b32 s49, v254, 12
	s_waitcnt vmcnt(11)
	v_lshlrev_b32_e32 v18, 16, v10
	v_and_b32_e32 v19, 0xffff0000, v10
	v_lshlrev_b32_e32 v10, 16, v11
	s_waitcnt vmcnt(10)
	v_lshlrev_b32_e32 v14, 16, v12
	v_mul_f32_e32 v5, 0xbfb8aa3b, v14
	v_exp_f32_e32 v5, v5
	v_and_b32_e32 v15, 0xffff0000, v12
	v_lshlrev_b32_e32 v12, 16, v13
	v_and_b32_e32 v13, 0xffff0000, v13
	v_add_f32_e32 v5, 1.0, v5
	v_rcp_f32_e32 v16, v5
	v_mul_f32_e32 v5, 0xbfb8aa3b, v15
	v_exp_f32_e32 v5, v5
	v_and_b32_e32 v11, 0xffff0000, v11
	v_add_f32_e32 v5, 1.0, v5
	v_rcp_f32_e32 v17, v5
	v_pk_mul_f32 v[18:19], v[4:5], v[18:19] op_sel_hi:[0,1]
	s_waitcnt vmcnt(9)
	v_pk_mul_f32 v[0:1], v[0:1], v[18:19]
	v_pk_mul_f32 v[10:11], v[4:5], v[10:11] op_sel_hi:[0,1]
	v_pk_mul_f32 v[14:15], v[16:17], v[14:15]
	v_pk_mul_f32 v[2:3], v[2:3], v[10:11]
	v_pk_mul_f32 v[0:1], v[0:1], v[14:15]
	s_nop 0
	v_cvt_pk_bf16_f32 v0, v0, v1
	v_mul_f32_e32 v1, 0xbfb8aa3b, v12
	v_exp_f32_e32 v1, v1
	s_nop 0
	v_add_f32_e32 v1, 1.0, v1
	v_rcp_f32_e32 v14, v1
	v_mul_f32_e32 v1, 0xbfb8aa3b, v13
	v_exp_f32_e32 v1, v1
	s_nop 0
	v_add_f32_e32 v1, 1.0, v1
	v_rcp_f32_e32 v15, v1
	s_nop 0
	v_pk_mul_f32 v[10:11], v[14:15], v[12:13]
	s_nop 0
	v_pk_mul_f32 v[2:3], v[2:3], v[10:11]
	s_nop 0
	v_cvt_pk_bf16_f32 v1, v2, v3
	global_store_dwordx2 v[48:49], v[0:1], off offset:1536
	s_nop 0
	s_waitcnt vmcnt(8)
	v_lshlrev_b32_e32 v14, 16, v210
	v_mul_f32_e32 v5, 0xbfb8aa3b, v14
	v_exp_f32_e32 v5, v5
	v_and_b32_e32 v15, 0xffff0000, v210
	s_waitcnt vmcnt(7)
	v_lshlrev_b32_e32 v18, 16, v212
	v_and_b32_e32 v19, 0xffff0000, v212
	v_add_f32_e32 v5, 1.0, v5
	v_rcp_f32_e32 v16, v5
	v_mul_f32_e32 v5, 0xbfb8aa3b, v15
	v_exp_f32_e32 v5, v5
	v_lshlrev_b32_e32 v10, 16, v211
	v_and_b32_e32 v11, 0xffff0000, v211
	v_lshlrev_b32_e32 v12, 16, v213
	v_add_f32_e32 v5, 1.0, v5
	v_rcp_f32_e32 v17, v5
	v_pk_mul_f32 v[18:19], v[4:5], v[18:19] op_sel_hi:[0,1]
	v_pk_mul_f32 v[0:1], v[206:207], v[18:19]
	v_and_b32_e32 v13, 0xffff0000, v213
	v_pk_mul_f32 v[14:15], v[16:17], v[14:15]
	v_pk_mul_f32 v[12:13], v[4:5], v[12:13] op_sel_hi:[0,1]
	v_pk_mul_f32 v[0:1], v[0:1], v[14:15]
	v_pk_mul_f32 v[2:3], v[208:209], v[12:13]
	v_cvt_pk_bf16_f32 v0, v0, v1
	v_mul_f32_e32 v1, 0xbfb8aa3b, v10
	v_exp_f32_e32 v1, v1
	s_nop 0
	v_add_f32_e32 v1, 1.0, v1
	v_rcp_f32_e32 v14, v1
	v_mul_f32_e32 v1, 0xbfb8aa3b, v11
	v_exp_f32_e32 v1, v1
	s_nop 0
	v_add_f32_e32 v1, 1.0, v1
	v_rcp_f32_e32 v15, v1
	s_nop 0
	v_pk_mul_f32 v[10:11], v[14:15], v[10:11]
	s_nop 0
	v_pk_mul_f32 v[2:3], v[2:3], v[10:11]
	s_nop 0
	v_cvt_pk_bf16_f32 v1, v2, v3
	global_store_dwordx2 v[94:95], v[0:1], off offset:16
	s_nop 0
	s_waitcnt vmcnt(6)
	v_lshlrev_b32_e32 v14, 16, v218
	v_mul_f32_e32 v5, 0xbfb8aa3b, v14
	v_exp_f32_e32 v5, v5
	v_and_b32_e32 v15, 0xffff0000, v218
	s_waitcnt vmcnt(5)
	v_lshlrev_b32_e32 v18, 16, v220
	v_and_b32_e32 v19, 0xffff0000, v220
	v_add_f32_e32 v5, 1.0, v5
	v_rcp_f32_e32 v16, v5
	v_mul_f32_e32 v5, 0xbfb8aa3b, v15
	v_exp_f32_e32 v5, v5
	v_lshlrev_b32_e32 v10, 16, v219
	v_and_b32_e32 v11, 0xffff0000, v219
	v_lshlrev_b32_e32 v12, 16, v221
	v_add_f32_e32 v5, 1.0, v5
	v_rcp_f32_e32 v17, v5
	v_pk_mul_f32 v[18:19], v[4:5], v[18:19] op_sel_hi:[0,1]
	v_pk_mul_f32 v[0:1], v[214:215], v[18:19]
	v_and_b32_e32 v13, 0xffff0000, v221
	v_pk_mul_f32 v[14:15], v[16:17], v[14:15]
	v_pk_mul_f32 v[12:13], v[4:5], v[12:13] op_sel_hi:[0,1]
	v_pk_mul_f32 v[0:1], v[0:1], v[14:15]
	v_pk_mul_f32 v[2:3], v[216:217], v[12:13]
	v_cvt_pk_bf16_f32 v0, v0, v1
	v_mul_f32_e32 v1, 0xbfb8aa3b, v10
	v_exp_f32_e32 v1, v1
	s_nop 0
	v_add_f32_e32 v1, 1.0, v1
	v_rcp_f32_e32 v14, v1
	v_mul_f32_e32 v1, 0xbfb8aa3b, v11
	v_exp_f32_e32 v1, v1
	s_nop 0
	v_add_f32_e32 v1, 1.0, v1
	v_rcp_f32_e32 v15, v1
	s_nop 0
	v_pk_mul_f32 v[10:11], v[14:15], v[10:11]
	s_nop 0
	v_pk_mul_f32 v[2:3], v[2:3], v[10:11]
	s_nop 0
	v_cvt_pk_bf16_f32 v1, v2, v3
	global_store_dwordx2 v[94:95], v[0:1], off offset:32
	s_nop 0
	s_waitcnt vmcnt(4)
	v_lshlrev_b32_e32 v14, 16, v226
	v_mul_f32_e32 v5, 0xbfb8aa3b, v14
	v_exp_f32_e32 v5, v5
	v_and_b32_e32 v15, 0xffff0000, v226
	s_waitcnt vmcnt(3)
	v_lshlrev_b32_e32 v18, 16, v228
	v_and_b32_e32 v19, 0xffff0000, v228
	v_add_f32_e32 v5, 1.0, v5
	v_rcp_f32_e32 v16, v5
	v_mul_f32_e32 v5, 0xbfb8aa3b, v15
	v_exp_f32_e32 v5, v5
	v_lshlrev_b32_e32 v10, 16, v227
	v_and_b32_e32 v11, 0xffff0000, v227
	v_lshlrev_b32_e32 v12, 16, v229
	v_add_f32_e32 v5, 1.0, v5
	v_rcp_f32_e32 v17, v5
	v_pk_mul_f32 v[18:19], v[4:5], v[18:19] op_sel_hi:[0,1]
	v_pk_mul_f32 v[0:1], v[222:223], v[18:19]
	v_and_b32_e32 v13, 0xffff0000, v229
	v_pk_mul_f32 v[14:15], v[16:17], v[14:15]
	v_pk_mul_f32 v[12:13], v[4:5], v[12:13] op_sel_hi:[0,1]
	v_pk_mul_f32 v[0:1], v[0:1], v[14:15]
	v_pk_mul_f32 v[2:3], v[224:225], v[12:13]
	v_cvt_pk_bf16_f32 v0, v0, v1
	v_mul_f32_e32 v1, 0xbfb8aa3b, v10
	v_exp_f32_e32 v1, v1
	s_nop 0
	v_add_f32_e32 v1, 1.0, v1
	v_rcp_f32_e32 v14, v1
	v_mul_f32_e32 v1, 0xbfb8aa3b, v11
	v_exp_f32_e32 v1, v1
	s_nop 0
	v_add_f32_e32 v1, 1.0, v1
	v_rcp_f32_e32 v15, v1
	s_nop 0
	v_pk_mul_f32 v[10:11], v[14:15], v[10:11]
	s_nop 0
	v_pk_mul_f32 v[2:3], v[2:3], v[10:11]
	s_nop 0
	v_cvt_pk_bf16_f32 v1, v2, v3
	global_store_dwordx2 v[94:95], v[0:1], off offset:48
	global_load_dwordx2 v[10:11], v[94:95], off offset:64
	global_load_dwordx2 v[12:13], v[8:9], off offset:64
	global_load_dwordx4 v[0:3], v[6:7], off offset:128
	global_load_dwordx2 v[212:213], v[94:95], off offset:80
	global_load_dwordx2 v[210:211], v[8:9], off offset:80
	global_load_dwordx4 v[206:209], v[6:7], off offset:160
	global_load_dwordx2 v[220:221], v[94:95], off offset:96
	global_load_dwordx2 v[218:219], v[8:9], off offset:96
	global_load_dwordx4 v[214:217], v[6:7], off offset:192
	global_load_dwordx2 v[228:229], v[94:95], off offset:112
	global_load_dwordx2 v[226:227], v[8:9], off offset:112
	global_load_dwordx4 v[222:225], v[6:7], off offset:224
	s_waitcnt vmcnt(11)
	v_lshlrev_b32_e32 v18, 16, v10
	s_waitcnt vmcnt(10)
	v_lshlrev_b32_e32 v14, 16, v12
	v_mul_f32_e32 v5, 0xbfb8aa3b, v14
	v_exp_f32_e32 v5, v5
	v_and_b32_e32 v15, 0xffff0000, v12
	v_and_b32_e32 v19, 0xffff0000, v10
	v_lshlrev_b32_e32 v12, 16, v13
	v_add_f32_e32 v5, 1.0, v5
	v_rcp_f32_e32 v16, v5
	v_mul_f32_e32 v5, 0xbfb8aa3b, v15
	v_exp_f32_e32 v5, v5
	v_and_b32_e32 v13, 0xffff0000, v13
	v_lshlrev_b32_e32 v10, 16, v11
	v_and_b32_e32 v11, 0xffff0000, v11
	v_add_f32_e32 v5, 1.0, v5
	v_rcp_f32_e32 v17, v5
	v_pk_mul_f32 v[18:19], v[4:5], v[18:19] op_sel_hi:[0,1]
	s_waitcnt vmcnt(9)
	v_pk_mul_f32 v[0:1], v[0:1], v[18:19]
	v_pk_mul_f32 v[10:11], v[4:5], v[10:11] op_sel_hi:[0,1]
	v_pk_mul_f32 v[14:15], v[16:17], v[14:15]
	v_pk_mul_f32 v[2:3], v[2:3], v[10:11]
	v_pk_mul_f32 v[0:1], v[0:1], v[14:15]
	s_nop 0
	v_cvt_pk_bf16_f32 v0, v0, v1
	v_mul_f32_e32 v1, 0xbfb8aa3b, v12
	v_exp_f32_e32 v1, v1
	s_nop 0
	v_add_f32_e32 v1, 1.0, v1
	v_rcp_f32_e32 v14, v1
	v_mul_f32_e32 v1, 0xbfb8aa3b, v13
	v_exp_f32_e32 v1, v1
	s_nop 0
	v_add_f32_e32 v1, 1.0, v1
	v_rcp_f32_e32 v15, v1
	s_nop 0
	v_pk_mul_f32 v[10:11], v[14:15], v[12:13]
	s_nop 0
	v_pk_mul_f32 v[2:3], v[2:3], v[10:11]
	s_nop 0
	v_cvt_pk_bf16_f32 v1, v2, v3
	global_store_dwordx2 v[94:95], v[0:1], off offset:64
	s_nop 0
	s_waitcnt vmcnt(9)
	v_lshlrev_b32_e32 v18, 16, v212
	s_waitcnt vmcnt(8)
	v_lshlrev_b32_e32 v14, 16, v210
	v_mul_f32_e32 v5, 0xbfb8aa3b, v14
	v_exp_f32_e32 v5, v5
	v_and_b32_e32 v15, 0xffff0000, v210
	v_and_b32_e32 v19, 0xffff0000, v212
	v_lshlrev_b32_e32 v12, 16, v211
	v_add_f32_e32 v5, 1.0, v5
	v_rcp_f32_e32 v16, v5
	v_mul_f32_e32 v5, 0xbfb8aa3b, v15
	v_exp_f32_e32 v5, v5
	v_and_b32_e32 v13, 0xffff0000, v211
	v_lshlrev_b32_e32 v10, 16, v213
	v_and_b32_e32 v11, 0xffff0000, v213
	v_add_f32_e32 v5, 1.0, v5
	v_rcp_f32_e32 v17, v5
	v_pk_mul_f32 v[18:19], v[4:5], v[18:19] op_sel_hi:[0,1]
	s_waitcnt vmcnt(7)
	v_pk_mul_f32 v[0:1], v[206:207], v[18:19]
	v_pk_mul_f32 v[10:11], v[4:5], v[10:11] op_sel_hi:[0,1]
	v_pk_mul_f32 v[14:15], v[16:17], v[14:15]
	v_pk_mul_f32 v[2:3], v[208:209], v[10:11]
	v_pk_mul_f32 v[0:1], v[0:1], v[14:15]
	s_nop 0
	v_cvt_pk_bf16_f32 v0, v0, v1
	v_mul_f32_e32 v1, 0xbfb8aa3b, v12
	v_exp_f32_e32 v1, v1
	s_nop 0
	v_add_f32_e32 v1, 1.0, v1
	v_rcp_f32_e32 v14, v1
	v_mul_f32_e32 v1, 0xbfb8aa3b, v13
	v_exp_f32_e32 v1, v1
	s_nop 0
	v_add_f32_e32 v1, 1.0, v1
	v_rcp_f32_e32 v15, v1
	s_nop 0
	v_pk_mul_f32 v[10:11], v[14:15], v[12:13]
	s_nop 0
	v_pk_mul_f32 v[2:3], v[2:3], v[10:11]
	s_nop 0
	v_cvt_pk_bf16_f32 v1, v2, v3
	global_store_dwordx2 v[94:95], v[0:1], off offset:80
	s_nop 0
	s_waitcnt vmcnt(7)
	v_lshlrev_b32_e32 v18, 16, v220
	s_waitcnt vmcnt(6)
	v_lshlrev_b32_e32 v14, 16, v218
	v_mul_f32_e32 v5, 0xbfb8aa3b, v14
	v_exp_f32_e32 v5, v5
	v_and_b32_e32 v15, 0xffff0000, v218
	v_and_b32_e32 v19, 0xffff0000, v220
	v_lshlrev_b32_e32 v12, 16, v219
	v_add_f32_e32 v5, 1.0, v5
	v_rcp_f32_e32 v16, v5
	v_mul_f32_e32 v5, 0xbfb8aa3b, v15
	v_exp_f32_e32 v5, v5
	v_and_b32_e32 v13, 0xffff0000, v219
	v_lshlrev_b32_e32 v10, 16, v221
	v_and_b32_e32 v11, 0xffff0000, v221
	v_add_f32_e32 v5, 1.0, v5
	v_rcp_f32_e32 v17, v5
	v_pk_mul_f32 v[18:19], v[4:5], v[18:19] op_sel_hi:[0,1]
	s_waitcnt vmcnt(5)
	v_pk_mul_f32 v[0:1], v[214:215], v[18:19]
	v_pk_mul_f32 v[10:11], v[4:5], v[10:11] op_sel_hi:[0,1]
	v_pk_mul_f32 v[14:15], v[16:17], v[14:15]
	v_pk_mul_f32 v[2:3], v[216:217], v[10:11]
	v_pk_mul_f32 v[0:1], v[0:1], v[14:15]
	s_nop 0
	v_cvt_pk_bf16_f32 v0, v0, v1
	v_mul_f32_e32 v1, 0xbfb8aa3b, v12
	v_exp_f32_e32 v1, v1
	s_nop 0
	v_add_f32_e32 v1, 1.0, v1
	v_rcp_f32_e32 v14, v1
	v_mul_f32_e32 v1, 0xbfb8aa3b, v13
	v_exp_f32_e32 v1, v1
	s_nop 0
	v_add_f32_e32 v1, 1.0, v1
	v_rcp_f32_e32 v15, v1
	s_nop 0
	v_pk_mul_f32 v[10:11], v[14:15], v[12:13]
	s_nop 0
	v_pk_mul_f32 v[2:3], v[2:3], v[10:11]
	s_nop 0
	v_cvt_pk_bf16_f32 v1, v2, v3
	global_store_dwordx2 v[94:95], v[0:1], off offset:96
	s_nop 0
	s_nop 0
	s_waitcnt vmcnt(5)
	v_lshlrev_b32_e32 v14, 16, v228
	s_waitcnt vmcnt(4)
	v_lshlrev_b32_e32 v10, 16, v226
	v_mul_f32_e32 v5, 0xbfb8aa3b, v10
	v_exp_f32_e32 v5, v5
	v_and_b32_e32 v11, 0xffff0000, v226
	v_lshlrev_b32_e32 v2, 16, v227
	v_and_b32_e32 v15, 0xffff0000, v228
	v_add_f32_e32 v5, 1.0, v5
	v_rcp_f32_e32 v12, v5
	v_mul_f32_e32 v5, 0xbfb8aa3b, v11
	v_exp_f32_e32 v5, v5
	v_and_b32_e32 v3, 0xffff0000, v227
	v_add_f32_e32 v5, 1.0, v5
	v_rcp_f32_e32 v13, v5
	v_pk_mul_f32 v[14:15], v[4:5], v[14:15] op_sel_hi:[0,1]
	v_mul_f32_e32 v5, 0xbfb8aa3b, v2
	v_exp_f32_e32 v5, v5
	s_waitcnt vmcnt(3)
	v_pk_mul_f32 v[6:7], v[222:223], v[14:15]
	v_pk_mul_f32 v[10:11], v[12:13], v[10:11]
	v_add_f32_e32 v5, 1.0, v5
	v_pk_mul_f32 v[6:7], v[6:7], v[10:11]
	v_lshlrev_b32_e32 v10, 16, v229
	v_cvt_pk_bf16_f32 v0, v6, v7
	v_rcp_f32_e32 v6, v5
	v_mul_f32_e32 v5, 0xbfb8aa3b, v3
	v_exp_f32_e32 v5, v5
	v_and_b32_e32 v11, 0xffff0000, v229
	v_add_f32_e32 v5, 1.0, v5
	v_rcp_f32_e32 v7, v5
	v_pk_mul_f32 v[4:5], v[4:5], v[10:11] op_sel_hi:[0,1]
	v_pk_mul_f32 v[4:5], v[224:225], v[4:5]
	v_pk_mul_f32 v[2:3], v[6:7], v[2:3]
	s_nop 0
	v_pk_mul_f32 v[2:3], v[4:5], v[2:3]
	s_nop 0
	v_cvt_pk_bf16_f32 v1, v2, v3
	global_store_dwordx2 v[94:95], v[0:1], off offset:112
	s_branch .LBB0_338
